# s_setprio 2 around the MFMA bursts of all GEMM k-loops (256-tile and 128-tile), priority dropped for staging/barriers
# speedup vs baseline: 1.0395x; 1.0076x over previous
.LBB0_340:
	s_setprio 2
	ds_read_b128 v[142:145], v132
	ds_read_b128 v[146:149], v133 offset:36864
	ds_read_b128 v[150:153], v133 offset:46080
	s_cmp_gt_u32 s3, 12
	s_waitcnt lgkmcnt(1)
	v_mfma_f32_32x32x16_bf16 v[50:65], v[142:145], v[146:149], v[50:65]
	s_waitcnt lgkmcnt(0)
	v_mfma_f32_32x32x16_bf16 v[34:49], v[142:145], v[150:153], v[34:49]
	ds_read_b128 v[142:145], v132 offset:4608
	s_waitcnt lgkmcnt(0)
	v_mfma_f32_32x32x16_bf16 v[16:31], v[142:145], v[146:149], v[16:31]
	v_mfma_f32_32x32x16_bf16 v[0:15], v[142:145], v[150:153], v[0:15]
	ds_read_b128 v[142:145], v132 offset:32
	ds_read_b128 v[146:149], v133 offset:36896
	ds_read_b128 v[150:153], v133 offset:46112
	s_waitcnt lgkmcnt(1)
	v_mfma_f32_32x32x16_bf16 v[50:65], v[142:145], v[146:149], v[50:65]
	s_waitcnt lgkmcnt(0)
	v_mfma_f32_32x32x16_bf16 v[34:49], v[142:145], v[150:153], v[34:49]
	ds_read_b128 v[142:145], v132 offset:4640
	s_waitcnt lgkmcnt(0)
	v_mfma_f32_32x32x16_bf16 v[16:31], v[142:145], v[146:149], v[16:31]
	v_mfma_f32_32x32x16_bf16 v[0:15], v[142:145], v[150:153], v[0:15]
	ds_read_b128 v[142:145], v132 offset:64
	ds_read_b128 v[146:149], v133 offset:36928
	ds_read_b128 v[150:153], v133 offset:46144
	s_waitcnt lgkmcnt(1)
	v_mfma_f32_32x32x16_bf16 v[50:65], v[142:145], v[146:149], v[50:65]
	s_waitcnt lgkmcnt(0)
	v_mfma_f32_32x32x16_bf16 v[34:49], v[142:145], v[150:153], v[34:49]
	ds_read_b128 v[142:145], v132 offset:4672
	s_waitcnt lgkmcnt(0)
	v_mfma_f32_32x32x16_bf16 v[16:31], v[142:145], v[146:149], v[16:31]
	v_mfma_f32_32x32x16_bf16 v[0:15], v[142:145], v[150:153], v[0:15]
	ds_read_b128 v[142:145], v132 offset:96
	ds_read_b128 v[146:149], v133 offset:36960
	ds_read_b128 v[150:153], v133 offset:46176
	s_waitcnt lgkmcnt(1)
	v_mfma_f32_32x32x16_bf16 v[50:65], v[142:145], v[146:149], v[50:65]
	s_waitcnt lgkmcnt(0)
	v_mfma_f32_32x32x16_bf16 v[34:49], v[142:145], v[150:153], v[34:49]
	s_setprio 0
	ds_read_b128 v[142:145], v132 offset:4704
	s_waitcnt vmcnt(7)
	ds_write_b128 v134, v[90:93] offset:18432
	s_waitcnt vmcnt(3)
	ds_write_b128 v134, v[110:113] offset:55296
	ds_write_b128 v134, v[98:101] offset:23040
	s_waitcnt vmcnt(2)
	ds_write_b128 v134, v[118:121] offset:59904
	ds_write_b128 v134, v[106:109] offset:27648
	s_waitcnt vmcnt(1)
	ds_write_b128 v134, v[122:125] offset:64512
	ds_write_b128 v134, v[114:117] offset:32256
	s_waitcnt vmcnt(0)
	ds_write_b128 v135, v[126:129] offset:13824
	s_waitcnt lgkmcnt(0)
	s_barrier
	v_mfma_f32_32x32x16_bf16 v[16:31], v[142:145], v[146:149], v[16:31]
	v_mfma_f32_32x32x16_bf16 v[0:15], v[142:145], v[150:153], v[0:15]
	s_cbranch_scc1 .LBB0_342
	v_add_co_u32_e32 v98, vcc, 0x240000, v138
	global_load_dwordx4 v[90:93], v[140:141], off offset:384
	s_nop 0
	v_addc_co_u32_e32 v99, vcc, 0, v139, vcc
	global_load_dwordx4 v[110:113], v[98:99], off offset:384
	v_add_co_u32_e32 v98, vcc, 0x10000, v140
	s_nop 1
	v_addc_co_u32_e32 v99, vcc, 0, v141, vcc
	v_add_co_u32_e32 v106, vcc, 0x250000, v138
	global_load_dwordx4 v[98:101], v[98:99], off offset:384
	s_nop 0
	v_addc_co_u32_e32 v107, vcc, 0, v139, vcc
	global_load_dwordx4 v[118:121], v[106:107], off offset:384
	v_add_co_u32_e32 v106, vcc, 0x20000, v140
	s_nop 1
	v_addc_co_u32_e32 v107, vcc, 0, v141, vcc
	v_add_co_u32_e32 v114, vcc, 0x260000, v138
	global_load_dwordx4 v[106:109], v[106:107], off offset:384
	s_nop 0
	v_addc_co_u32_e32 v115, vcc, 0, v139, vcc
	global_load_dwordx4 v[122:125], v[114:115], off offset:384
	v_add_co_u32_e32 v114, vcc, 0x30000, v140
	s_nop 1
	v_addc_co_u32_e32 v115, vcc, 0, v141, vcc
	v_add_co_u32_e32 v126, vcc, 0x270000, v138
	global_load_dwordx4 v[114:117], v[114:115], off offset:384
	s_nop 0
	v_addc_co_u32_e32 v127, vcc, 0, v139, vcc
	global_load_dwordx4 v[126:129], v[126:127], off offset:384
.LBB0_342:
	s_setprio 2
	ds_read_b128 v[138:141], v132 offset:18432
	ds_read_b128 v[142:145], v133 offset:55296
	ds_read_b128 v[146:149], v133 offset:64512
	s_andn2_b64 vcc, exec, s[8:9]
	s_waitcnt lgkmcnt(1)
	v_mfma_f32_32x32x16_bf16 v[50:65], v[138:141], v[142:145], v[50:65]
	s_waitcnt lgkmcnt(0)
	v_mfma_f32_32x32x16_bf16 v[34:49], v[138:141], v[146:149], v[34:49]
	ds_read_b128 v[138:141], v132 offset:23040
	s_waitcnt lgkmcnt(0)
	v_mfma_f32_32x32x16_bf16 v[16:31], v[138:141], v[142:145], v[16:31]
	v_mfma_f32_32x32x16_bf16 v[0:15], v[138:141], v[146:149], v[0:15]
	ds_read_b128 v[138:141], v132 offset:18464
	ds_read_b128 v[142:145], v133 offset:55328
	ds_read_b128 v[146:149], v133 offset:64544
	s_waitcnt lgkmcnt(1)
	v_mfma_f32_32x32x16_bf16 v[50:65], v[138:141], v[142:145], v[50:65]
	s_waitcnt lgkmcnt(0)
	v_mfma_f32_32x32x16_bf16 v[34:49], v[138:141], v[146:149], v[34:49]
	ds_read_b128 v[138:141], v132 offset:23072
	s_waitcnt lgkmcnt(0)
	v_mfma_f32_32x32x16_bf16 v[16:31], v[138:141], v[142:145], v[16:31]
	v_mfma_f32_32x32x16_bf16 v[0:15], v[138:141], v[146:149], v[0:15]
	ds_read_b128 v[138:141], v132 offset:18496
	ds_read_b128 v[142:145], v133 offset:55360
	ds_read_b128 v[146:149], v133 offset:64576
	s_waitcnt lgkmcnt(1)
	v_mfma_f32_32x32x16_bf16 v[50:65], v[138:141], v[142:145], v[50:65]
	s_waitcnt lgkmcnt(0)
	v_mfma_f32_32x32x16_bf16 v[34:49], v[138:141], v[146:149], v[34:49]
	ds_read_b128 v[138:141], v132 offset:23104
	s_waitcnt lgkmcnt(0)
	v_mfma_f32_32x32x16_bf16 v[16:31], v[138:141], v[142:145], v[16:31]
	v_mfma_f32_32x32x16_bf16 v[0:15], v[138:141], v[146:149], v[0:15]
	ds_read_b128 v[138:141], v132 offset:18528
	ds_read_b128 v[142:145], v133 offset:55392
	ds_read_b128 v[146:149], v133 offset:64608
	s_waitcnt lgkmcnt(1)
	v_mfma_f32_32x32x16_bf16 v[50:65], v[138:141], v[142:145], v[50:65]
	s_waitcnt lgkmcnt(0)
	v_mfma_f32_32x32x16_bf16 v[34:49], v[138:141], v[146:149], v[34:49]
	ds_read_b128 v[138:141], v132 offset:23136
	s_waitcnt lgkmcnt(0)
	v_mfma_f32_32x32x16_bf16 v[16:31], v[138:141], v[142:145], v[16:31]
	v_mfma_f32_32x32x16_bf16 v[0:15], v[138:141], v[146:149], v[0:15]
	s_setprio 0
	s_cbranch_vccnz .LBB0_337
	ds_write_b128 v134, v[66:69]
	ds_write_b128 v134, v[70:73] offset:36864
	ds_write_b128 v134, v[74:77] offset:4608
	ds_write_b128 v134, v[78:81] offset:41472
	ds_write_b128 v134, v[82:85] offset:9216
	ds_write_b128 v134, v[86:89] offset:46080
	ds_write_b128 v134, v[94:97] offset:13824
	ds_write_b128 v134, v[102:105] offset:50688
	s_branch .LBB0_337

.LBB0_944:
	s_add_i32 s3, s1, 1
	s_cmp_lt_u32 s1, 15
	s_cselect_b32 s1, s3, s1
	s_lshl_b32 s12, s1, 6
	s_lshl_b64 s[10:11], s[12:13], 1
	s_barrier
	s_waitcnt vmcnt(0)
	ds_write_b128 v204, v[174:177]
	ds_write_b128 v204, v[170:173] offset:4608
	ds_write_b128 v204, v[166:169] offset:9216
	ds_write_b128 v204, v[162:165] offset:13824
	ds_write_b128 v204, v[158:161] offset:18432
	ds_write_b128 v204, v[154:157] offset:23040
	ds_write_b128 v204, v[150:153] offset:27648
	ds_write_b128 v204, v[146:149] offset:32256
	ds_write_b128 v204, v[142:145] offset:36864
	ds_write_b128 v204, v[134:137] offset:41472
	ds_write_b128 v204, v[130:133] offset:46080
	ds_write_b128 v204, v[138:141] offset:50688
	v_lshl_add_u64 v[130:131], v[178:179], 0, s[10:11]
	s_add_u32 s100, s10, 0x10000
	s_addc_u32 s101, s11, 0
	v_lshl_add_u64 v[132:133], v[178:179], 0, s[100:101]
	s_add_u32 s100, s100, 0x10000
	s_addc_u32 s101, s101, 0
	v_lshl_add_u64 v[134:135], v[178:179], 0, s[100:101]
	s_add_u32 s100, s100, 0x10000
	s_addc_u32 s101, s101, 0
	v_lshl_add_u64 v[136:137], v[178:179], 0, s[100:101]
	s_add_u32 s100, s100, 0x10000
	s_addc_u32 s101, s101, 0
	v_lshl_add_u64 v[138:139], v[178:179], 0, s[100:101]
	s_add_u32 s100, s100, 0x10000
	s_addc_u32 s101, s101, 0
	v_lshl_add_u64 v[140:141], v[178:179], 0, s[100:101]
	s_add_u32 s100, s100, 0x10000
	s_addc_u32 s101, s101, 0
	v_lshl_add_u64 v[142:143], v[178:179], 0, s[100:101]
	s_add_u32 s100, s100, 0x10000
	s_addc_u32 s101, s101, 0
	v_lshl_add_u64 v[144:145], v[178:179], 0, s[100:101]
	s_waitcnt lgkmcnt(0)
	s_barrier
	v_lshl_add_u64 v[224:225], v[180:181], 0, s[10:11]
	s_add_u32 s100, s10, 0x10000
	s_addc_u32 s101, s11, 0
	v_lshl_add_u64 v[226:227], v[180:181], 0, s[100:101]
	s_add_u32 s100, s100, 0x10000
	s_addc_u32 s101, s101, 0
	v_lshl_add_u64 v[228:229], v[180:181], 0, s[100:101]
	s_add_u32 s100, s100, 0x10000
	s_addc_u32 s101, s101, 0
	v_lshl_add_u64 v[230:231], v[180:181], 0, s[100:101]
	global_load_dwordx4 v[174:177], v[130:131], off
	global_load_dwordx4 v[170:173], v[132:133], off
	global_load_dwordx4 v[166:169], v[134:135], off
	global_load_dwordx4 v[162:165], v[136:137], off
	global_load_dwordx4 v[158:161], v[138:139], off
	global_load_dwordx4 v[154:157], v[140:141], off
	global_load_dwordx4 v[150:153], v[142:143], off
	global_load_dwordx4 v[146:149], v[144:145], off
	global_load_dwordx4 v[142:145], v[224:225], off
	global_load_dwordx4 v[134:137], v[226:227], off
	global_load_dwordx4 v[130:133], v[228:229], off
	global_load_dwordx4 v[138:141], v[230:231], off
	s_setprio 2
	ds_read_b128 v[224:227], v182
	ds_read_b128 v[228:231], v183 offset:36864
	ds_read_b128 v[232:235], v183 offset:41472
	ds_read_b128 v[184:187], v182 offset:4608
	ds_read_b128 v[236:239], v183 offset:46080
	ds_read_b128 v[240:243], v183 offset:50688
	s_waitcnt lgkmcnt(4)
	v_mfma_f32_32x32x16_bf16 v[114:129], v[224:227], v[228:231], v[114:129]
	ds_read_b128 v[188:191], v183 offset:36896
	ds_read_b128 v[192:195], v183 offset:41504
	s_waitcnt lgkmcnt(5)
	v_mfma_f32_32x32x16_bf16 v[82:97], v[224:227], v[232:235], v[82:97]
	ds_read_b128 v[196:199], v183 offset:46112
	ds_read_b128 v[200:203], v183 offset:50720
	s_waitcnt lgkmcnt(5)
	v_mfma_f32_32x32x16_bf16 v[98:113], v[224:227], v[236:239], v[98:113]
	s_waitcnt lgkmcnt(4)
	v_mfma_f32_32x32x16_bf16 v[66:81], v[224:227], v[240:243], v[66:81]
	ds_read_b128 v[224:227], v182 offset:32
	v_mfma_f32_32x32x16_bf16 v[50:65], v[184:187], v[228:231], v[50:65]
	v_mfma_f32_32x32x16_bf16 v[16:31], v[184:187], v[232:235], v[16:31]
	v_mfma_f32_32x32x16_bf16 v[34:49], v[184:187], v[236:239], v[34:49]
	v_mfma_f32_32x32x16_bf16 v[0:15], v[184:187], v[240:243], v[0:15]
	ds_read_b128 v[184:187], v182 offset:4640
	s_waitcnt lgkmcnt(1)
	v_mfma_f32_32x32x16_bf16 v[114:129], v[224:227], v[188:191], v[114:129]
	ds_read_b128 v[228:231], v183 offset:36928
	ds_read_b128 v[232:235], v183 offset:41536
	v_mfma_f32_32x32x16_bf16 v[82:97], v[224:227], v[192:195], v[82:97]
	ds_read_b128 v[236:239], v183 offset:46144
	ds_read_b128 v[240:243], v183 offset:50752
	v_mfma_f32_32x32x16_bf16 v[98:113], v[224:227], v[196:199], v[98:113]
	v_mfma_f32_32x32x16_bf16 v[66:81], v[224:227], v[200:203], v[66:81]
	ds_read_b128 v[224:227], v182 offset:64
	s_waitcnt lgkmcnt(5)
	v_mfma_f32_32x32x16_bf16 v[50:65], v[184:187], v[188:191], v[50:65]
	v_mfma_f32_32x32x16_bf16 v[16:31], v[184:187], v[192:195], v[16:31]
	v_mfma_f32_32x32x16_bf16 v[34:49], v[184:187], v[196:199], v[34:49]
	v_mfma_f32_32x32x16_bf16 v[0:15], v[184:187], v[200:203], v[0:15]
	ds_read_b128 v[184:187], v182 offset:4672
	s_waitcnt lgkmcnt(1)
	v_mfma_f32_32x32x16_bf16 v[114:129], v[224:227], v[228:231], v[114:129]
	ds_read_b128 v[188:191], v183 offset:36960
	ds_read_b128 v[192:195], v183 offset:41568
	v_mfma_f32_32x32x16_bf16 v[82:97], v[224:227], v[232:235], v[82:97]
	ds_read_b128 v[196:199], v183 offset:46176
	ds_read_b128 v[200:203], v183 offset:50784
	v_mfma_f32_32x32x16_bf16 v[98:113], v[224:227], v[236:239], v[98:113]
	v_mfma_f32_32x32x16_bf16 v[66:81], v[224:227], v[240:243], v[66:81]
	ds_read_b128 v[224:227], v182 offset:96
	s_waitcnt lgkmcnt(5)
	v_mfma_f32_32x32x16_bf16 v[50:65], v[184:187], v[228:231], v[50:65]
	v_mfma_f32_32x32x16_bf16 v[16:31], v[184:187], v[232:235], v[16:31]
	v_mfma_f32_32x32x16_bf16 v[34:49], v[184:187], v[236:239], v[34:49]
	v_mfma_f32_32x32x16_bf16 v[0:15], v[184:187], v[240:243], v[0:15]
	ds_read_b128 v[184:187], v182 offset:4704
	s_waitcnt lgkmcnt(1)
	v_mfma_f32_32x32x16_bf16 v[114:129], v[224:227], v[188:191], v[114:129]
	v_mfma_f32_32x32x16_bf16 v[82:97], v[224:227], v[192:195], v[82:97]
	v_mfma_f32_32x32x16_bf16 v[98:113], v[224:227], v[196:199], v[98:113]
	v_mfma_f32_32x32x16_bf16 v[66:81], v[224:227], v[200:203], v[66:81]
	s_waitcnt lgkmcnt(0)
	v_mfma_f32_32x32x16_bf16 v[50:65], v[184:187], v[188:191], v[50:65]
	v_mfma_f32_32x32x16_bf16 v[16:31], v[184:187], v[192:195], v[16:31]
	v_mfma_f32_32x32x16_bf16 v[34:49], v[184:187], v[196:199], v[34:49]
	v_mfma_f32_32x32x16_bf16 v[0:15], v[184:187], v[200:203], v[0:15]
	s_setprio 0
	s_mov_b32 s1, s3
	s_cmp_lg_u32 s3, 16
	s_cbranch_scc1 .LBB0_944
	s_lshl_b32 s1, s2, 7
	s_lshr_b32 s2, s9, 24
	s_add_i32 s2, s8, s2
	s_lshr_b32 s2, s2, 8
	s_add_i32 s2, s2, s6
	s_mulk_i32 s2, 0x1800
	v_mov_b32_e32 v32, v206
	s_barrier
	s_ashr_i32 s3, s2, 31
	v_readlane_b32 s36, v248, 46
	s_lshl_b64 s[2:3], s[2:3], 2
	s_waitcnt vmcnt(1)
	v_and_b32_e32 v130, 0xffffffc0, v32
	v_lshrrev_b32_e32 v131, 3, v32
	v_readlane_b32 s40, v248, 50
	v_and_or_b32 v148, v32, 31, s1
	v_and_or_b32 v32, v131, 4, v130
	v_readlane_b32 s41, v248, 51
	s_add_u32 s2, s40, s2
	v_lshl_add_u32 v132, s0, 8, v32
	s_addc_u32 s3, s41, s3
	v_ashrrev_i32_e32 v133, 31, v132
	v_readlane_b32 s48, v248, 58
	v_readlane_b32 s49, v248, 59
	s_add_u32 s2, s2, 0x2000
	v_ashrrev_i32_e32 v149, 31, v148
	v_lshlrev_b64 v[136:137], 12, v[132:133]
	s_addc_u32 s3, s3, 0
	v_lshlrev_b64 v[130:131], 2, v[148:149]
	v_lshl_add_u64 v[136:137], s[48:49], 0, v[136:137]
	v_lshl_add_u64 v[134:135], s[2:3], 0, v[130:131]
	v_lshl_add_u64 v[150:151], v[136:137], 0, v[130:131]
	v_writelane_b32 v251, s12, 29
	v_readlane_b32 s37, v248, 47
	v_readlane_b32 s38, v248, 48
	v_writelane_b32 v251, s13, 30
	v_readlane_b32 s39, v248, 49
	v_readlane_b32 s0, v251, 24
	s_add_i32 s7, s7, s0
	s_cmpk_lt_i32 s7, 0x200
	v_readlane_b32 s42, v248, 52
	v_readlane_b32 s43, v248, 53
	v_readlane_b32 s44, v248, 54
	v_readlane_b32 s45, v248, 55
	v_readlane_b32 s46, v248, 56
	v_readlane_b32 s47, v248, 57
	v_readlane_b32 s50, v248, 60
	v_readlane_b32 s51, v248, 61
	v_readlane_b32 s1, v251, 25
	s_waitcnt vmcnt(0)
	v_lshlrev_b32_e32 v240, 2, v148
	v_lshl_add_u32 v240, v132, 12, v240
	s_nop 2
	global_load_dword v241, v[134:135], off
	global_load_dword v242, v[134:135], off offset:128
	global_load_dword v243, v[134:135], off offset:256
	global_load_dword v151, v[134:135], off offset:384
	v_mov_b32_e32 v232, v240
	v_add_u32_e32 v233, 0x1000, v240
	v_add_u32_e32 v234, 0x2000, v240
	v_add_u32_e32 v235, 0x3000, v240
	v_add_u32_e32 v236, 0x8000, v240
	v_add_u32_e32 v237, 0x9000, v240
	v_add_u32_e32 v238, 0xa000, v240
	v_add_u32_e32 v239, 0xb000, v240
	global_load_dword v138, v232, s[48:49]
	global_load_dword v139, v232, s[48:49] offset:128
	global_load_dword v140, v232, s[48:49] offset:256
	global_load_dword v141, v232, s[48:49] offset:384
	global_load_dword v142, v233, s[48:49]
	global_load_dword v143, v233, s[48:49] offset:128
	global_load_dword v144, v233, s[48:49] offset:256
	global_load_dword v145, v233, s[48:49] offset:384
	global_load_dword v146, v234, s[48:49]
	global_load_dword v147, v234, s[48:49] offset:128
	global_load_dword v152, v234, s[48:49] offset:256
	global_load_dword v153, v234, s[48:49] offset:384
	global_load_dword v154, v235, s[48:49]
	global_load_dword v155, v235, s[48:49] offset:128
	global_load_dword v156, v235, s[48:49] offset:256
	global_load_dword v157, v235, s[48:49] offset:384
	global_load_dword v158, v236, s[48:49]
	global_load_dword v159, v236, s[48:49] offset:128
	global_load_dword v160, v236, s[48:49] offset:256
	global_load_dword v161, v236, s[48:49] offset:384
	global_load_dword v162, v237, s[48:49]
	global_load_dword v163, v237, s[48:49] offset:128
	global_load_dword v164, v237, s[48:49] offset:256
	global_load_dword v165, v237, s[48:49] offset:384
	global_load_dword v166, v238, s[48:49]
	global_load_dword v167, v238, s[48:49] offset:128
	global_load_dword v168, v238, s[48:49] offset:256
	global_load_dword v169, v238, s[48:49] offset:384
	global_load_dword v170, v239, s[48:49]
	global_load_dword v171, v239, s[48:49] offset:128
	global_load_dword v172, v239, s[48:49] offset:256
	global_load_dword v173, v239, s[48:49] offset:384
	v_add_u32_e32 v130, 0x10000, v240
	v_add_u32_e32 v131, 0x11000, v240
	v_add_u32_e32 v132, 0x12000, v240
	v_add_u32_e32 v133, 0x13000, v240
	v_add_u32_e32 v134, 0x18000, v240
	v_add_u32_e32 v135, 0x19000, v240
	v_add_u32_e32 v136, 0x1a000, v240
	v_add_u32_e32 v137, 0x1b000, v240
	global_load_dword v174, v130, s[48:49]
	global_load_dword v175, v130, s[48:49] offset:128
	global_load_dword v176, v130, s[48:49] offset:256
	global_load_dword v177, v130, s[48:49] offset:384
	global_load_dword v184, v131, s[48:49]
	global_load_dword v185, v131, s[48:49] offset:128
	global_load_dword v186, v131, s[48:49] offset:256
	global_load_dword v187, v131, s[48:49] offset:384
	global_load_dword v188, v132, s[48:49]
	global_load_dword v189, v132, s[48:49] offset:128
	global_load_dword v190, v132, s[48:49] offset:256
	global_load_dword v191, v132, s[48:49] offset:384
	global_load_dword v192, v133, s[48:49]
	global_load_dword v193, v133, s[48:49] offset:128
	global_load_dword v194, v133, s[48:49] offset:256
	global_load_dword v195, v133, s[48:49] offset:384
	global_load_dword v196, v134, s[48:49]
	global_load_dword v197, v134, s[48:49] offset:128
	global_load_dword v198, v134, s[48:49] offset:256
	global_load_dword v199, v134, s[48:49] offset:384
	global_load_dword v200, v135, s[48:49]
	global_load_dword v201, v135, s[48:49] offset:128
	global_load_dword v202, v135, s[48:49] offset:256
	global_load_dword v203, v135, s[48:49] offset:384
	global_load_dword v224, v136, s[48:49]
	global_load_dword v225, v136, s[48:49] offset:128
	global_load_dword v226, v136, s[48:49] offset:256
	global_load_dword v227, v136, s[48:49] offset:384
	global_load_dword v228, v137, s[48:49]
	global_load_dword v229, v137, s[48:49] offset:128
	global_load_dword v230, v137, s[48:49] offset:256
	global_load_dword v231, v137, s[48:49] offset:384
	s_waitcnt vmcnt(32)
	v_mul_f32_e32 v138, 0x3fd744fd, v138
	v_mul_f32_e32 v139, 0x3fd744fd, v139
	v_mul_f32_e32 v140, 0x3fd744fd, v140
	v_mul_f32_e32 v141, 0x3fd744fd, v141
	v_mul_f32_e32 v142, 0x3fd744fd, v142
	v_mul_f32_e32 v143, 0x3fd744fd, v143
	v_mul_f32_e32 v144, 0x3fd744fd, v144
	v_mul_f32_e32 v145, 0x3fd744fd, v145
	v_mul_f32_e32 v146, 0x3fd744fd, v146
	v_mul_f32_e32 v147, 0x3fd744fd, v147
	v_mul_f32_e32 v152, 0x3fd744fd, v152
	v_mul_f32_e32 v153, 0x3fd744fd, v153
	v_mul_f32_e32 v154, 0x3fd744fd, v154
	v_mul_f32_e32 v155, 0x3fd744fd, v155
	v_mul_f32_e32 v156, 0x3fd744fd, v156
	v_mul_f32_e32 v157, 0x3fd744fd, v157
	v_mul_f32_e32 v158, 0x3fd744fd, v158
	v_mul_f32_e32 v159, 0x3fd744fd, v159
	v_mul_f32_e32 v160, 0x3fd744fd, v160
	v_mul_f32_e32 v161, 0x3fd744fd, v161
	v_mul_f32_e32 v162, 0x3fd744fd, v162
	v_mul_f32_e32 v163, 0x3fd744fd, v163
	v_mul_f32_e32 v164, 0x3fd744fd, v164
	v_mul_f32_e32 v165, 0x3fd744fd, v165
	v_mul_f32_e32 v166, 0x3fd744fd, v166
	v_mul_f32_e32 v167, 0x3fd744fd, v167
	v_mul_f32_e32 v168, 0x3fd744fd, v168
	v_mul_f32_e32 v169, 0x3fd744fd, v169
	v_mul_f32_e32 v170, 0x3fd744fd, v170
	v_mul_f32_e32 v171, 0x3fd744fd, v171
	v_mul_f32_e32 v172, 0x3fd744fd, v172
	v_mul_f32_e32 v173, 0x3fd744fd, v173
	v_fmac_f32_e32 v138, v114, v241
	v_fmac_f32_e32 v139, v82, v242
	v_fmac_f32_e32 v140, v98, v243
	v_fmac_f32_e32 v141, v66, v151
	v_fmac_f32_e32 v142, v115, v241
	v_fmac_f32_e32 v143, v83, v242
	v_fmac_f32_e32 v144, v99, v243
	v_fmac_f32_e32 v145, v67, v151
	v_fmac_f32_e32 v146, v116, v241
	v_fmac_f32_e32 v147, v84, v242
	v_fmac_f32_e32 v152, v100, v243
	v_fmac_f32_e32 v153, v68, v151
	v_fmac_f32_e32 v154, v117, v241
	v_fmac_f32_e32 v155, v85, v242
	v_fmac_f32_e32 v156, v101, v243
	v_fmac_f32_e32 v157, v69, v151
	v_fmac_f32_e32 v158, v118, v241
	v_fmac_f32_e32 v159, v86, v242
	v_fmac_f32_e32 v160, v102, v243
	v_fmac_f32_e32 v161, v70, v151
	v_fmac_f32_e32 v162, v119, v241
	v_fmac_f32_e32 v163, v87, v242
	v_fmac_f32_e32 v164, v103, v243
	v_fmac_f32_e32 v165, v71, v151
	v_fmac_f32_e32 v166, v120, v241
	v_fmac_f32_e32 v167, v88, v242
	v_fmac_f32_e32 v168, v104, v243
	v_fmac_f32_e32 v169, v72, v151
	v_fmac_f32_e32 v170, v121, v241
	v_fmac_f32_e32 v171, v89, v242
	v_fmac_f32_e32 v172, v105, v243
	v_fmac_f32_e32 v173, v73, v151
	global_store_dword v232, v138, s[48:49]
	global_store_dword v232, v139, s[48:49] offset:128
	global_store_dword v232, v140, s[48:49] offset:256
	global_store_dword v232, v141, s[48:49] offset:384
	global_store_dword v233, v142, s[48:49]
	global_store_dword v233, v143, s[48:49] offset:128
	global_store_dword v233, v144, s[48:49] offset:256
	global_store_dword v233, v145, s[48:49] offset:384
	global_store_dword v234, v146, s[48:49]
	global_store_dword v234, v147, s[48:49] offset:128
	global_store_dword v234, v152, s[48:49] offset:256
	global_store_dword v234, v153, s[48:49] offset:384
	global_store_dword v235, v154, s[48:49]
	global_store_dword v235, v155, s[48:49] offset:128
	global_store_dword v235, v156, s[48:49] offset:256
	global_store_dword v235, v157, s[48:49] offset:384
	global_store_dword v236, v158, s[48:49]
	global_store_dword v236, v159, s[48:49] offset:128
	global_store_dword v236, v160, s[48:49] offset:256
	global_store_dword v236, v161, s[48:49] offset:384
	global_store_dword v237, v162, s[48:49]
	global_store_dword v237, v163, s[48:49] offset:128
	global_store_dword v237, v164, s[48:49] offset:256
	global_store_dword v237, v165, s[48:49] offset:384
	global_store_dword v238, v166, s[48:49]
	global_store_dword v238, v167, s[48:49] offset:128
	global_store_dword v238, v168, s[48:49] offset:256
	global_store_dword v238, v169, s[48:49] offset:384
	global_store_dword v239, v170, s[48:49]
	global_store_dword v239, v171, s[48:49] offset:128
	global_store_dword v239, v172, s[48:49] offset:256
	global_store_dword v239, v173, s[48:49] offset:384
	v_add_u32_e32 v232, 0x20000, v240
	v_add_u32_e32 v233, 0x21000, v240
	v_add_u32_e32 v234, 0x22000, v240
	v_add_u32_e32 v235, 0x23000, v240
	v_add_u32_e32 v236, 0x28000, v240
	v_add_u32_e32 v237, 0x29000, v240
	v_add_u32_e32 v238, 0x2a000, v240
	v_add_u32_e32 v239, 0x2b000, v240
	global_load_dword v138, v232, s[48:49]
	global_load_dword v139, v232, s[48:49] offset:128
	global_load_dword v140, v232, s[48:49] offset:256
	global_load_dword v141, v232, s[48:49] offset:384
	global_load_dword v142, v233, s[48:49]
	global_load_dword v143, v233, s[48:49] offset:128
	global_load_dword v144, v233, s[48:49] offset:256
	global_load_dword v145, v233, s[48:49] offset:384
	global_load_dword v146, v234, s[48:49]
	global_load_dword v147, v234, s[48:49] offset:128
	global_load_dword v152, v234, s[48:49] offset:256
	global_load_dword v153, v234, s[48:49] offset:384
	global_load_dword v154, v235, s[48:49]
	global_load_dword v155, v235, s[48:49] offset:128
	global_load_dword v156, v235, s[48:49] offset:256
	global_load_dword v157, v235, s[48:49] offset:384
	global_load_dword v158, v236, s[48:49]
	global_load_dword v159, v236, s[48:49] offset:128
	global_load_dword v160, v236, s[48:49] offset:256
	global_load_dword v161, v236, s[48:49] offset:384
	global_load_dword v162, v237, s[48:49]
	global_load_dword v163, v237, s[48:49] offset:128
	global_load_dword v164, v237, s[48:49] offset:256
	global_load_dword v165, v237, s[48:49] offset:384
	global_load_dword v166, v238, s[48:49]
	global_load_dword v167, v238, s[48:49] offset:128
	global_load_dword v168, v238, s[48:49] offset:256
	global_load_dword v169, v238, s[48:49] offset:384
	global_load_dword v170, v239, s[48:49]
	global_load_dword v171, v239, s[48:49] offset:128
	global_load_dword v172, v239, s[48:49] offset:256
	global_load_dword v173, v239, s[48:49] offset:384
	s_waitcnt vmcnt(63)
	v_mul_f32_e32 v174, 0x3fd744fd, v174
	v_mul_f32_e32 v175, 0x3fd744fd, v175
	v_mul_f32_e32 v176, 0x3fd744fd, v176
	v_mul_f32_e32 v177, 0x3fd744fd, v177
	v_mul_f32_e32 v184, 0x3fd744fd, v184
	v_mul_f32_e32 v185, 0x3fd744fd, v185
	v_mul_f32_e32 v186, 0x3fd744fd, v186
	v_mul_f32_e32 v187, 0x3fd744fd, v187
	v_mul_f32_e32 v188, 0x3fd744fd, v188
	v_mul_f32_e32 v189, 0x3fd744fd, v189
	v_mul_f32_e32 v190, 0x3fd744fd, v190
	v_mul_f32_e32 v191, 0x3fd744fd, v191
	v_mul_f32_e32 v192, 0x3fd744fd, v192
	v_mul_f32_e32 v193, 0x3fd744fd, v193
	v_mul_f32_e32 v194, 0x3fd744fd, v194
	v_mul_f32_e32 v195, 0x3fd744fd, v195
	v_mul_f32_e32 v196, 0x3fd744fd, v196
	v_mul_f32_e32 v197, 0x3fd744fd, v197
	v_mul_f32_e32 v198, 0x3fd744fd, v198
	v_mul_f32_e32 v199, 0x3fd744fd, v199
	v_mul_f32_e32 v200, 0x3fd744fd, v200
	v_mul_f32_e32 v201, 0x3fd744fd, v201
	v_mul_f32_e32 v202, 0x3fd744fd, v202
	v_mul_f32_e32 v203, 0x3fd744fd, v203
	v_mul_f32_e32 v224, 0x3fd744fd, v224
	v_mul_f32_e32 v225, 0x3fd744fd, v225
	v_mul_f32_e32 v226, 0x3fd744fd, v226
	v_mul_f32_e32 v227, 0x3fd744fd, v227
	v_mul_f32_e32 v228, 0x3fd744fd, v228
	v_mul_f32_e32 v229, 0x3fd744fd, v229
	v_mul_f32_e32 v230, 0x3fd744fd, v230
	v_mul_f32_e32 v231, 0x3fd744fd, v231
	v_fmac_f32_e32 v174, v122, v241
	v_fmac_f32_e32 v175, v90, v242
	v_fmac_f32_e32 v176, v106, v243
	v_fmac_f32_e32 v177, v74, v151
	v_fmac_f32_e32 v184, v123, v241
	v_fmac_f32_e32 v185, v91, v242
	v_fmac_f32_e32 v186, v107, v243
	v_fmac_f32_e32 v187, v75, v151
	v_fmac_f32_e32 v188, v124, v241
	v_fmac_f32_e32 v189, v92, v242
	v_fmac_f32_e32 v190, v108, v243
	v_fmac_f32_e32 v191, v76, v151
	v_fmac_f32_e32 v192, v125, v241
	v_fmac_f32_e32 v193, v93, v242
	v_fmac_f32_e32 v194, v109, v243
	v_fmac_f32_e32 v195, v77, v151
	v_fmac_f32_e32 v196, v126, v241
	v_fmac_f32_e32 v197, v94, v242
	v_fmac_f32_e32 v198, v110, v243
	v_fmac_f32_e32 v199, v78, v151
	v_fmac_f32_e32 v200, v127, v241
	v_fmac_f32_e32 v201, v95, v242
	v_fmac_f32_e32 v202, v111, v243
	v_fmac_f32_e32 v203, v79, v151
	v_fmac_f32_e32 v224, v128, v241
	v_fmac_f32_e32 v225, v96, v242
	v_fmac_f32_e32 v226, v112, v243
	v_fmac_f32_e32 v227, v80, v151
	v_fmac_f32_e32 v228, v129, v241
	v_fmac_f32_e32 v229, v97, v242
	v_fmac_f32_e32 v230, v113, v243
	v_fmac_f32_e32 v231, v81, v151
	global_store_dword v130, v174, s[48:49]
	global_store_dword v130, v175, s[48:49] offset:128
	global_store_dword v130, v176, s[48:49] offset:256
	global_store_dword v130, v177, s[48:49] offset:384
	global_store_dword v131, v184, s[48:49]
	global_store_dword v131, v185, s[48:49] offset:128
	global_store_dword v131, v186, s[48:49] offset:256
	global_store_dword v131, v187, s[48:49] offset:384
	global_store_dword v132, v188, s[48:49]
	global_store_dword v132, v189, s[48:49] offset:128
	global_store_dword v132, v190, s[48:49] offset:256
	global_store_dword v132, v191, s[48:49] offset:384
	global_store_dword v133, v192, s[48:49]
	global_store_dword v133, v193, s[48:49] offset:128
	global_store_dword v133, v194, s[48:49] offset:256
	global_store_dword v133, v195, s[48:49] offset:384
	global_store_dword v134, v196, s[48:49]
	global_store_dword v134, v197, s[48:49] offset:128
	global_store_dword v134, v198, s[48:49] offset:256
	global_store_dword v134, v199, s[48:49] offset:384
	global_store_dword v135, v200, s[48:49]
	global_store_dword v135, v201, s[48:49] offset:128
	global_store_dword v135, v202, s[48:49] offset:256
	global_store_dword v135, v203, s[48:49] offset:384
	global_store_dword v136, v224, s[48:49]
	global_store_dword v136, v225, s[48:49] offset:128
	global_store_dword v136, v226, s[48:49] offset:256
	global_store_dword v136, v227, s[48:49] offset:384
	global_store_dword v137, v228, s[48:49]
	global_store_dword v137, v229, s[48:49] offset:128
	global_store_dword v137, v230, s[48:49] offset:256
	global_store_dword v137, v231, s[48:49] offset:384
	v_add_u32_e32 v130, 0x30000, v240
	v_add_u32_e32 v131, 0x31000, v240
	v_add_u32_e32 v132, 0x32000, v240
	v_add_u32_e32 v133, 0x33000, v240
	v_add_u32_e32 v134, 0x38000, v240
	v_add_u32_e32 v135, 0x39000, v240
	v_add_u32_e32 v136, 0x3a000, v240
	v_add_u32_e32 v137, 0x3b000, v240
	global_load_dword v174, v130, s[48:49]
	global_load_dword v175, v130, s[48:49] offset:128
	global_load_dword v176, v130, s[48:49] offset:256
	global_load_dword v177, v130, s[48:49] offset:384
	global_load_dword v184, v131, s[48:49]
	global_load_dword v185, v131, s[48:49] offset:128
	global_load_dword v186, v131, s[48:49] offset:256
	global_load_dword v187, v131, s[48:49] offset:384
	global_load_dword v188, v132, s[48:49]
	global_load_dword v189, v132, s[48:49] offset:128
	global_load_dword v190, v132, s[48:49] offset:256
	global_load_dword v191, v132, s[48:49] offset:384
	global_load_dword v192, v133, s[48:49]
	global_load_dword v193, v133, s[48:49] offset:128
	global_load_dword v194, v133, s[48:49] offset:256
	global_load_dword v195, v133, s[48:49] offset:384
	global_load_dword v196, v134, s[48:49]
	global_load_dword v197, v134, s[48:49] offset:128
	global_load_dword v198, v134, s[48:49] offset:256
	global_load_dword v199, v134, s[48:49] offset:384
	global_load_dword v200, v135, s[48:49]
	global_load_dword v201, v135, s[48:49] offset:128
	global_load_dword v202, v135, s[48:49] offset:256
	global_load_dword v203, v135, s[48:49] offset:384
	global_load_dword v224, v136, s[48:49]
	global_load_dword v225, v136, s[48:49] offset:128
	global_load_dword v226, v136, s[48:49] offset:256
	global_load_dword v227, v136, s[48:49] offset:384
	global_load_dword v228, v137, s[48:49]
	global_load_dword v229, v137, s[48:49] offset:128
	global_load_dword v230, v137, s[48:49] offset:256
	global_load_dword v231, v137, s[48:49] offset:384
	s_waitcnt vmcnt(63)
	v_mul_f32_e32 v138, 0x3fd744fd, v138
	v_mul_f32_e32 v139, 0x3fd744fd, v139
	v_mul_f32_e32 v140, 0x3fd744fd, v140
	v_mul_f32_e32 v141, 0x3fd744fd, v141
	v_mul_f32_e32 v142, 0x3fd744fd, v142
	v_mul_f32_e32 v143, 0x3fd744fd, v143
	v_mul_f32_e32 v144, 0x3fd744fd, v144
	v_mul_f32_e32 v145, 0x3fd744fd, v145
	v_mul_f32_e32 v146, 0x3fd744fd, v146
	v_mul_f32_e32 v147, 0x3fd744fd, v147
	v_mul_f32_e32 v152, 0x3fd744fd, v152
	v_mul_f32_e32 v153, 0x3fd744fd, v153
	v_mul_f32_e32 v154, 0x3fd744fd, v154
	v_mul_f32_e32 v155, 0x3fd744fd, v155
	v_mul_f32_e32 v156, 0x3fd744fd, v156
	v_mul_f32_e32 v157, 0x3fd744fd, v157
	v_mul_f32_e32 v158, 0x3fd744fd, v158
	v_mul_f32_e32 v159, 0x3fd744fd, v159
	v_mul_f32_e32 v160, 0x3fd744fd, v160
	v_mul_f32_e32 v161, 0x3fd744fd, v161
	v_mul_f32_e32 v162, 0x3fd744fd, v162
	v_mul_f32_e32 v163, 0x3fd744fd, v163
	v_mul_f32_e32 v164, 0x3fd744fd, v164
	v_mul_f32_e32 v165, 0x3fd744fd, v165
	v_mul_f32_e32 v166, 0x3fd744fd, v166
	v_mul_f32_e32 v167, 0x3fd744fd, v167
	v_mul_f32_e32 v168, 0x3fd744fd, v168
	v_mul_f32_e32 v169, 0x3fd744fd, v169
	v_mul_f32_e32 v170, 0x3fd744fd, v170
	v_mul_f32_e32 v171, 0x3fd744fd, v171
	v_mul_f32_e32 v172, 0x3fd744fd, v172
	v_mul_f32_e32 v173, 0x3fd744fd, v173
	v_fmac_f32_e32 v138, v50, v241
	v_fmac_f32_e32 v139, v16, v242
	v_fmac_f32_e32 v140, v34, v243
	v_fmac_f32_e32 v141, v0, v151
	v_fmac_f32_e32 v142, v51, v241
	v_fmac_f32_e32 v143, v17, v242
	v_fmac_f32_e32 v144, v35, v243
	v_fmac_f32_e32 v145, v1, v151
	v_fmac_f32_e32 v146, v52, v241
	v_fmac_f32_e32 v147, v18, v242
	v_fmac_f32_e32 v152, v36, v243
	v_fmac_f32_e32 v153, v2, v151
	v_fmac_f32_e32 v154, v53, v241
	v_fmac_f32_e32 v155, v19, v242
	v_fmac_f32_e32 v156, v37, v243
	v_fmac_f32_e32 v157, v3, v151
	v_fmac_f32_e32 v158, v54, v241
	v_fmac_f32_e32 v159, v20, v242
	v_fmac_f32_e32 v160, v38, v243
	v_fmac_f32_e32 v161, v4, v151
	v_fmac_f32_e32 v162, v55, v241
	v_fmac_f32_e32 v163, v21, v242
	v_fmac_f32_e32 v164, v39, v243
	v_fmac_f32_e32 v165, v5, v151
	v_fmac_f32_e32 v166, v56, v241
	v_fmac_f32_e32 v167, v22, v242
	v_fmac_f32_e32 v168, v40, v243
	v_fmac_f32_e32 v169, v6, v151
	v_fmac_f32_e32 v170, v57, v241
	v_fmac_f32_e32 v171, v23, v242
	v_fmac_f32_e32 v172, v41, v243
	v_fmac_f32_e32 v173, v7, v151
	global_store_dword v232, v138, s[48:49]
	global_store_dword v232, v139, s[48:49] offset:128
	global_store_dword v232, v140, s[48:49] offset:256
	global_store_dword v232, v141, s[48:49] offset:384
	global_store_dword v233, v142, s[48:49]
	global_store_dword v233, v143, s[48:49] offset:128
	global_store_dword v233, v144, s[48:49] offset:256
	global_store_dword v233, v145, s[48:49] offset:384
	global_store_dword v234, v146, s[48:49]
	global_store_dword v234, v147, s[48:49] offset:128
	global_store_dword v234, v152, s[48:49] offset:256
	global_store_dword v234, v153, s[48:49] offset:384
	global_store_dword v235, v154, s[48:49]
	global_store_dword v235, v155, s[48:49] offset:128
	global_store_dword v235, v156, s[48:49] offset:256
	global_store_dword v235, v157, s[48:49] offset:384
	global_store_dword v236, v158, s[48:49]
	global_store_dword v236, v159, s[48:49] offset:128
	global_store_dword v236, v160, s[48:49] offset:256
	global_store_dword v236, v161, s[48:49] offset:384
	global_store_dword v237, v162, s[48:49]
	global_store_dword v237, v163, s[48:49] offset:128
	global_store_dword v237, v164, s[48:49] offset:256
	global_store_dword v237, v165, s[48:49] offset:384
	global_store_dword v238, v166, s[48:49]
	global_store_dword v238, v167, s[48:49] offset:128
	global_store_dword v238, v168, s[48:49] offset:256
	global_store_dword v238, v169, s[48:49] offset:384
	global_store_dword v239, v170, s[48:49]
	global_store_dword v239, v171, s[48:49] offset:128
	global_store_dword v239, v172, s[48:49] offset:256
	global_store_dword v239, v173, s[48:49] offset:384
	s_waitcnt vmcnt(32)
	v_mul_f32_e32 v174, 0x3fd744fd, v174
	v_mul_f32_e32 v175, 0x3fd744fd, v175
	v_mul_f32_e32 v176, 0x3fd744fd, v176
	v_mul_f32_e32 v177, 0x3fd744fd, v177
	v_mul_f32_e32 v184, 0x3fd744fd, v184
	v_mul_f32_e32 v185, 0x3fd744fd, v185
	v_mul_f32_e32 v186, 0x3fd744fd, v186
	v_mul_f32_e32 v187, 0x3fd744fd, v187
	v_mul_f32_e32 v188, 0x3fd744fd, v188
	v_mul_f32_e32 v189, 0x3fd744fd, v189
	v_mul_f32_e32 v190, 0x3fd744fd, v190
	v_mul_f32_e32 v191, 0x3fd744fd, v191
	v_mul_f32_e32 v192, 0x3fd744fd, v192
	v_mul_f32_e32 v193, 0x3fd744fd, v193
	v_mul_f32_e32 v194, 0x3fd744fd, v194
	v_mul_f32_e32 v195, 0x3fd744fd, v195
	v_mul_f32_e32 v196, 0x3fd744fd, v196
	v_mul_f32_e32 v197, 0x3fd744fd, v197
	v_mul_f32_e32 v198, 0x3fd744fd, v198
	v_mul_f32_e32 v199, 0x3fd744fd, v199
	v_mul_f32_e32 v200, 0x3fd744fd, v200
	v_mul_f32_e32 v201, 0x3fd744fd, v201
	v_mul_f32_e32 v202, 0x3fd744fd, v202
	v_mul_f32_e32 v203, 0x3fd744fd, v203
	v_mul_f32_e32 v224, 0x3fd744fd, v224
	v_mul_f32_e32 v225, 0x3fd744fd, v225
	v_mul_f32_e32 v226, 0x3fd744fd, v226
	v_mul_f32_e32 v227, 0x3fd744fd, v227
	v_mul_f32_e32 v228, 0x3fd744fd, v228
	v_mul_f32_e32 v229, 0x3fd744fd, v229
	v_mul_f32_e32 v230, 0x3fd744fd, v230
	v_mul_f32_e32 v231, 0x3fd744fd, v231
	v_fmac_f32_e32 v174, v58, v241
	v_fmac_f32_e32 v175, v24, v242
	v_fmac_f32_e32 v176, v42, v243
	v_fmac_f32_e32 v177, v8, v151
	v_fmac_f32_e32 v184, v59, v241
	v_fmac_f32_e32 v185, v25, v242
	v_fmac_f32_e32 v186, v43, v243
	v_fmac_f32_e32 v187, v9, v151
	v_fmac_f32_e32 v188, v60, v241
	v_fmac_f32_e32 v189, v26, v242
	v_fmac_f32_e32 v190, v44, v243
	v_fmac_f32_e32 v191, v10, v151
	v_fmac_f32_e32 v192, v61, v241
	v_fmac_f32_e32 v193, v27, v242
	v_fmac_f32_e32 v194, v45, v243
	v_fmac_f32_e32 v195, v11, v151
	v_fmac_f32_e32 v196, v62, v241
	v_fmac_f32_e32 v197, v28, v242
	v_fmac_f32_e32 v198, v46, v243
	v_fmac_f32_e32 v199, v12, v151
	v_fmac_f32_e32 v200, v63, v241
	v_fmac_f32_e32 v201, v29, v242
	v_fmac_f32_e32 v202, v47, v243
	v_fmac_f32_e32 v203, v13, v151
	v_fmac_f32_e32 v224, v64, v241
	v_fmac_f32_e32 v225, v30, v242
	v_fmac_f32_e32 v226, v48, v243
	v_fmac_f32_e32 v227, v14, v151
	v_fmac_f32_e32 v228, v65, v241
	v_fmac_f32_e32 v229, v31, v242
	v_fmac_f32_e32 v230, v49, v243
	v_fmac_f32_e32 v231, v15, v151
	global_store_dword v130, v174, s[48:49]
	global_store_dword v130, v175, s[48:49] offset:128
	global_store_dword v130, v176, s[48:49] offset:256
	global_store_dword v130, v177, s[48:49] offset:384
	global_store_dword v131, v184, s[48:49]
	global_store_dword v131, v185, s[48:49] offset:128
	global_store_dword v131, v186, s[48:49] offset:256
	global_store_dword v131, v187, s[48:49] offset:384
	global_store_dword v132, v188, s[48:49]
	global_store_dword v132, v189, s[48:49] offset:128
	global_store_dword v132, v190, s[48:49] offset:256
	global_store_dword v132, v191, s[48:49] offset:384
	global_store_dword v133, v192, s[48:49]
	global_store_dword v133, v193, s[48:49] offset:128
	global_store_dword v133, v194, s[48:49] offset:256
	global_store_dword v133, v195, s[48:49] offset:384
	global_store_dword v134, v196, s[48:49]
	global_store_dword v134, v197, s[48:49] offset:128
	global_store_dword v134, v198, s[48:49] offset:256
	global_store_dword v134, v199, s[48:49] offset:384
	global_store_dword v135, v200, s[48:49]
	global_store_dword v135, v201, s[48:49] offset:128
	global_store_dword v135, v202, s[48:49] offset:256
	global_store_dword v135, v203, s[48:49] offset:384
	global_store_dword v136, v224, s[48:49]
	global_store_dword v136, v225, s[48:49] offset:128
	global_store_dword v136, v226, s[48:49] offset:256
	global_store_dword v136, v227, s[48:49] offset:384
	global_store_dword v137, v228, s[48:49]
	global_store_dword v137, v229, s[48:49] offset:128
	global_store_dword v137, v230, s[48:49] offset:256
	global_store_dword v137, v231, s[48:49] offset:384
	s_cbranch_scc1 .LBB0_940

.LBB0_1018:
	s_add_i32 s3, s1, 1
	s_cmp_lt_u32 s1, 15
	s_cselect_b32 s1, s3, s1
	s_lshl_b32 s12, s1, 6
	s_lshl_b64 s[10:11], s[12:13], 1
	s_barrier
	s_waitcnt vmcnt(0)
	ds_write_b128 v204, v[174:177]
	ds_write_b128 v204, v[170:173] offset:4608
	ds_write_b128 v204, v[166:169] offset:9216
	ds_write_b128 v204, v[162:165] offset:13824
	ds_write_b128 v204, v[158:161] offset:18432
	ds_write_b128 v204, v[154:157] offset:23040
	ds_write_b128 v204, v[150:153] offset:27648
	ds_write_b128 v204, v[146:149] offset:32256
	ds_write_b128 v204, v[142:145] offset:36864
	ds_write_b128 v204, v[134:137] offset:41472
	ds_write_b128 v204, v[130:133] offset:46080
	ds_write_b128 v204, v[138:141] offset:50688
	v_lshl_add_u64 v[130:131], v[178:179], 0, s[10:11]
	s_add_u32 s100, s10, 0x10000
	s_addc_u32 s101, s11, 0
	v_lshl_add_u64 v[132:133], v[178:179], 0, s[100:101]
	s_add_u32 s100, s100, 0x10000
	s_addc_u32 s101, s101, 0
	v_lshl_add_u64 v[134:135], v[178:179], 0, s[100:101]
	s_add_u32 s100, s100, 0x10000
	s_addc_u32 s101, s101, 0
	v_lshl_add_u64 v[136:137], v[178:179], 0, s[100:101]
	s_add_u32 s100, s100, 0x10000
	s_addc_u32 s101, s101, 0
	v_lshl_add_u64 v[138:139], v[178:179], 0, s[100:101]
	s_add_u32 s100, s100, 0x10000
	s_addc_u32 s101, s101, 0
	v_lshl_add_u64 v[140:141], v[178:179], 0, s[100:101]
	s_add_u32 s100, s100, 0x10000
	s_addc_u32 s101, s101, 0
	v_lshl_add_u64 v[142:143], v[178:179], 0, s[100:101]
	s_add_u32 s100, s100, 0x10000
	s_addc_u32 s101, s101, 0
	v_lshl_add_u64 v[144:145], v[178:179], 0, s[100:101]
	s_waitcnt lgkmcnt(0)
	s_barrier
	v_lshl_add_u64 v[224:225], v[180:181], 0, s[10:11]
	s_add_u32 s100, s10, 0x10000
	s_addc_u32 s101, s11, 0
	v_lshl_add_u64 v[226:227], v[180:181], 0, s[100:101]
	s_add_u32 s100, s100, 0x10000
	s_addc_u32 s101, s101, 0
	v_lshl_add_u64 v[228:229], v[180:181], 0, s[100:101]
	s_add_u32 s100, s100, 0x10000
	s_addc_u32 s101, s101, 0
	v_lshl_add_u64 v[230:231], v[180:181], 0, s[100:101]
	global_load_dwordx4 v[174:177], v[130:131], off
	global_load_dwordx4 v[170:173], v[132:133], off
	global_load_dwordx4 v[166:169], v[134:135], off
	global_load_dwordx4 v[162:165], v[136:137], off
	global_load_dwordx4 v[158:161], v[138:139], off
	global_load_dwordx4 v[154:157], v[140:141], off
	global_load_dwordx4 v[150:153], v[142:143], off
	global_load_dwordx4 v[146:149], v[144:145], off
	global_load_dwordx4 v[142:145], v[224:225], off
	global_load_dwordx4 v[134:137], v[226:227], off
	global_load_dwordx4 v[130:133], v[228:229], off
	global_load_dwordx4 v[138:141], v[230:231], off
	s_setprio 2
	ds_read_b128 v[224:227], v182
	ds_read_b128 v[228:231], v183 offset:36864
	ds_read_b128 v[232:235], v183 offset:41472
	ds_read_b128 v[184:187], v182 offset:4608
	ds_read_b128 v[236:239], v183 offset:46080
	ds_read_b128 v[240:243], v183 offset:50688
	s_waitcnt lgkmcnt(4)
	v_mfma_f32_32x32x16_bf16 v[114:129], v[224:227], v[228:231], v[114:129]
	ds_read_b128 v[188:191], v183 offset:36896
	ds_read_b128 v[192:195], v183 offset:41504
	s_waitcnt lgkmcnt(5)
	v_mfma_f32_32x32x16_bf16 v[82:97], v[224:227], v[232:235], v[82:97]
	ds_read_b128 v[196:199], v183 offset:46112
	ds_read_b128 v[200:203], v183 offset:50720
	s_waitcnt lgkmcnt(5)
	v_mfma_f32_32x32x16_bf16 v[98:113], v[224:227], v[236:239], v[98:113]
	s_waitcnt lgkmcnt(4)
	v_mfma_f32_32x32x16_bf16 v[66:81], v[224:227], v[240:243], v[66:81]
	ds_read_b128 v[224:227], v182 offset:32
	v_mfma_f32_32x32x16_bf16 v[50:65], v[184:187], v[228:231], v[50:65]
	v_mfma_f32_32x32x16_bf16 v[16:31], v[184:187], v[232:235], v[16:31]
	v_mfma_f32_32x32x16_bf16 v[34:49], v[184:187], v[236:239], v[34:49]
	v_mfma_f32_32x32x16_bf16 v[0:15], v[184:187], v[240:243], v[0:15]
	ds_read_b128 v[184:187], v182 offset:4640
	s_waitcnt lgkmcnt(1)
	v_mfma_f32_32x32x16_bf16 v[114:129], v[224:227], v[188:191], v[114:129]
	ds_read_b128 v[228:231], v183 offset:36928
	ds_read_b128 v[232:235], v183 offset:41536
	v_mfma_f32_32x32x16_bf16 v[82:97], v[224:227], v[192:195], v[82:97]
	ds_read_b128 v[236:239], v183 offset:46144
	ds_read_b128 v[240:243], v183 offset:50752
	v_mfma_f32_32x32x16_bf16 v[98:113], v[224:227], v[196:199], v[98:113]
	v_mfma_f32_32x32x16_bf16 v[66:81], v[224:227], v[200:203], v[66:81]
	ds_read_b128 v[224:227], v182 offset:64
	s_waitcnt lgkmcnt(5)
	v_mfma_f32_32x32x16_bf16 v[50:65], v[184:187], v[188:191], v[50:65]
	v_mfma_f32_32x32x16_bf16 v[16:31], v[184:187], v[192:195], v[16:31]
	v_mfma_f32_32x32x16_bf16 v[34:49], v[184:187], v[196:199], v[34:49]
	v_mfma_f32_32x32x16_bf16 v[0:15], v[184:187], v[200:203], v[0:15]
	ds_read_b128 v[184:187], v182 offset:4672
	s_waitcnt lgkmcnt(1)
	v_mfma_f32_32x32x16_bf16 v[114:129], v[224:227], v[228:231], v[114:129]
	ds_read_b128 v[188:191], v183 offset:36960
	ds_read_b128 v[192:195], v183 offset:41568
	v_mfma_f32_32x32x16_bf16 v[82:97], v[224:227], v[232:235], v[82:97]
	ds_read_b128 v[196:199], v183 offset:46176
	ds_read_b128 v[200:203], v183 offset:50784
	v_mfma_f32_32x32x16_bf16 v[98:113], v[224:227], v[236:239], v[98:113]
	v_mfma_f32_32x32x16_bf16 v[66:81], v[224:227], v[240:243], v[66:81]
	ds_read_b128 v[224:227], v182 offset:96
	s_waitcnt lgkmcnt(5)
	v_mfma_f32_32x32x16_bf16 v[50:65], v[184:187], v[228:231], v[50:65]
	v_mfma_f32_32x32x16_bf16 v[16:31], v[184:187], v[232:235], v[16:31]
	v_mfma_f32_32x32x16_bf16 v[34:49], v[184:187], v[236:239], v[34:49]
	v_mfma_f32_32x32x16_bf16 v[0:15], v[184:187], v[240:243], v[0:15]
	ds_read_b128 v[184:187], v182 offset:4704
	s_waitcnt lgkmcnt(1)
	v_mfma_f32_32x32x16_bf16 v[114:129], v[224:227], v[188:191], v[114:129]
	v_mfma_f32_32x32x16_bf16 v[82:97], v[224:227], v[192:195], v[82:97]
	v_mfma_f32_32x32x16_bf16 v[98:113], v[224:227], v[196:199], v[98:113]
	v_mfma_f32_32x32x16_bf16 v[66:81], v[224:227], v[200:203], v[66:81]
	s_waitcnt lgkmcnt(0)
	v_mfma_f32_32x32x16_bf16 v[50:65], v[184:187], v[188:191], v[50:65]
	v_mfma_f32_32x32x16_bf16 v[16:31], v[184:187], v[192:195], v[16:31]
	v_mfma_f32_32x32x16_bf16 v[34:49], v[184:187], v[196:199], v[34:49]
	v_mfma_f32_32x32x16_bf16 v[0:15], v[184:187], v[200:203], v[0:15]
	s_setprio 0
	s_mov_b32 s1, s3
	s_cmp_lg_u32 s3, 16
	s_cbranch_scc1 .LBB0_1018
	s_lshl_b32 s1, s2, 8
	s_bfe_i32 s2, s2, 0x10017
	s_lshr_b32 s2, s2, 19
	v_writelane_b32 v251, s12, 29
	s_add_i32 s2, s1, s2
	s_and_b32 s2, s2, 0xffffe000
	v_writelane_b32 v251, s13, 30
	s_ashr_i32 s12, s8, 8
	s_add_i32 s12, s12, s9
	s_sub_i32 s17, s1, s2
	s_cmp_gt_i32 s0, 15
	s_mov_b64 s[2:3], -1
	s_barrier
	s_cbranch_scc0 .LBB0_1025
	s_cmp_gt_u32 s0, 31
	s_cbranch_scc0 .LBB0_1022
	v_mov_b32_e32 v32, v206
	v_readlane_b32 s24, v249, 18
	s_waitcnt vmcnt(1)
	v_and_b32_e32 v130, 0xffffffc0, v32
	v_lshrrev_b32_e32 v131, 3, v32
	v_and_or_b32 v130, v131, 4, v130
	v_add_u32_e32 v132, s1, v130
	s_lshl_b32 s1, s0, 8
	v_readlane_b32 s26, v249, 20
	v_and_b32_e32 v32, 31, v32
	v_readlane_b32 s27, v249, 21
	s_add_u32 s2, s26, s1
	s_addc_u32 s3, s27, 0
	v_lshlrev_b32_e32 v32, 1, v32
	v_lshl_add_u64 v[130:131], s[2:3], 0, v[32:33]
	v_mul_f32_e32 v32, 0xbfb8aa3b, v114
	v_exp_f32_e32 v32, v32
	s_movk_i32 s2, 0xe000
	s_mov_b32 s3, -1
	v_lshl_add_u64 v[130:131], v[130:131], 0, s[2:3]
	v_add_f32_e32 v32, 1.0, v32
	v_div_scale_f32 v134, s[2:3], v32, v32, v114
	v_rcp_f32_e32 v135, v134
	v_ashrrev_i32_e32 v133, 31, v132
	s_movk_i32 s1, 0x7fff
	v_readlane_b32 s25, v249, 19
	v_fma_f32 v136, -v134, v135, 1.0
	v_fmac_f32_e32 v135, v136, v135
	v_div_scale_f32 v136, vcc, v114, v32, v114
	v_mul_f32_e32 v137, v136, v135
	s_waitcnt vmcnt(0)
	v_fma_f32 v138, -v134, v137, v136
	v_fmac_f32_e32 v137, v138, v135
	v_fma_f32 v134, -v134, v137, v136
	v_div_fmas_f32 v134, v134, v135, v137
	v_div_fixup_f32 v32, v134, v32, v114
	v_bfe_u32 v134, v32, 16, 1
	v_add3_u32 v32, v32, v134, s1
	v_lshlrev_b64 v[134:135], 12, v[132:133]
	v_lshl_add_u64 v[134:135], v[130:131], 0, v[134:135]
	global_store_short_d16_hi v[134:135], v32, off
	v_mul_f32_e32 v32, 0xbfb8aa3b, v98
	v_exp_f32_e32 v32, v32
	v_readlane_b32 s28, v249, 22
	v_readlane_b32 s29, v249, 23
	v_readlane_b32 s30, v249, 24
	v_add_f32_e32 v32, 1.0, v32
	v_div_scale_f32 v133, s[2:3], v32, v32, v98
	v_rcp_f32_e32 v136, v133
	v_readlane_b32 s31, v249, 25
	v_fma_f32 v137, -v133, v136, 1.0
	v_fmac_f32_e32 v136, v137, v136
	v_div_scale_f32 v137, vcc, v98, v32, v98
	v_mul_f32_e32 v138, v137, v136
	v_fma_f32 v139, -v133, v138, v137
	v_fmac_f32_e32 v138, v139, v136
	v_fma_f32 v133, -v133, v138, v137
	v_div_fmas_f32 v133, v133, v136, v138
	v_div_fixup_f32 v32, v133, v32, v98
	v_bfe_u32 v133, v32, 16, 1
	v_add3_u32 v32, v32, v133, s1
	global_store_short_d16_hi v[134:135], v32, off offset:128
	v_mul_f32_e32 v32, 0xbfb8aa3b, v115
	v_exp_f32_e32 v32, v32
	v_or_b32_e32 v136, 1, v132
	v_ashrrev_i32_e32 v137, 31, v136
	v_lshlrev_b64 v[136:137], 12, v[136:137]
	v_add_f32_e32 v32, 1.0, v32
	v_div_scale_f32 v133, s[2:3], v32, v32, v115
	v_rcp_f32_e32 v138, v133
	v_lshl_add_u64 v[136:137], v[130:131], 0, v[136:137]
	v_fma_f32 v139, -v133, v138, 1.0
	v_fmac_f32_e32 v138, v139, v138
	v_div_scale_f32 v139, vcc, v115, v32, v115
	v_mul_f32_e32 v140, v139, v138
	v_fma_f32 v141, -v133, v140, v139
	v_fmac_f32_e32 v140, v141, v138
	v_fma_f32 v133, -v133, v140, v139
	v_div_fmas_f32 v133, v133, v138, v140
	v_div_fixup_f32 v32, v133, v32, v115
	v_bfe_u32 v133, v32, 16, 1
	v_add3_u32 v32, v32, v133, s1
	global_store_short_d16_hi v[136:137], v32, off
	v_mul_f32_e32 v32, 0xbfb8aa3b, v99
	v_exp_f32_e32 v32, v32
	s_nop 0
	v_add_f32_e32 v32, 1.0, v32
	v_div_scale_f32 v133, s[2:3], v32, v32, v99
	v_rcp_f32_e32 v138, v133
	s_nop 0
	v_fma_f32 v139, -v133, v138, 1.0
	v_fmac_f32_e32 v138, v139, v138
	v_div_scale_f32 v139, vcc, v99, v32, v99
	v_mul_f32_e32 v140, v139, v138
	v_fma_f32 v141, -v133, v140, v139
	v_fmac_f32_e32 v140, v141, v138
	v_fma_f32 v133, -v133, v140, v139
	v_div_fmas_f32 v133, v133, v138, v140
	v_div_fixup_f32 v32, v133, v32, v99
	v_bfe_u32 v133, v32, 16, 1
	v_add3_u32 v32, v32, v133, s1
	global_store_short_d16_hi v[136:137], v32, off offset:128
	v_mul_f32_e32 v32, 0xbfb8aa3b, v116
	v_exp_f32_e32 v32, v32
	v_or_b32_e32 v138, 2, v132
	v_ashrrev_i32_e32 v139, 31, v138
	v_lshlrev_b64 v[138:139], 12, v[138:139]
	v_add_f32_e32 v32, 1.0, v32
	v_div_scale_f32 v133, s[2:3], v32, v32, v116
	v_rcp_f32_e32 v140, v133
	v_lshl_add_u64 v[138:139], v[130:131], 0, v[138:139]
	v_fma_f32 v141, -v133, v140, 1.0
	v_fmac_f32_e32 v140, v141, v140
	v_div_scale_f32 v141, vcc, v116, v32, v116
	v_mul_f32_e32 v142, v141, v140
	v_fma_f32 v143, -v133, v142, v141
	v_fmac_f32_e32 v142, v143, v140
	v_fma_f32 v133, -v133, v142, v141
	v_div_fmas_f32 v133, v133, v140, v142
	v_div_fixup_f32 v32, v133, v32, v116
	v_bfe_u32 v133, v32, 16, 1
	v_add3_u32 v32, v32, v133, s1
	global_store_short_d16_hi v[138:139], v32, off
	v_mul_f32_e32 v32, 0xbfb8aa3b, v100
	v_exp_f32_e32 v32, v32
	s_nop 0
	v_add_f32_e32 v32, 1.0, v32
	v_div_scale_f32 v133, s[2:3], v32, v32, v100
	v_rcp_f32_e32 v140, v133
	s_nop 0
	v_fma_f32 v141, -v133, v140, 1.0
	v_fmac_f32_e32 v140, v141, v140
	v_div_scale_f32 v141, vcc, v100, v32, v100
	v_mul_f32_e32 v142, v141, v140
	v_fma_f32 v143, -v133, v142, v141
	v_fmac_f32_e32 v142, v143, v140
	v_fma_f32 v133, -v133, v142, v141
	v_div_fmas_f32 v133, v133, v140, v142
	v_div_fixup_f32 v32, v133, v32, v100
	v_bfe_u32 v133, v32, 16, 1
	v_add3_u32 v32, v32, v133, s1
	global_store_short_d16_hi v[138:139], v32, off offset:128
	v_mul_f32_e32 v32, 0xbfb8aa3b, v117
	v_exp_f32_e32 v32, v32
	v_or_b32_e32 v140, 3, v132
	v_ashrrev_i32_e32 v141, 31, v140
	v_lshlrev_b64 v[140:141], 12, v[140:141]
	v_add_f32_e32 v32, 1.0, v32
	v_div_scale_f32 v133, s[2:3], v32, v32, v117
	v_rcp_f32_e32 v142, v133
	v_lshl_add_u64 v[140:141], v[130:131], 0, v[140:141]
	v_fma_f32 v143, -v133, v142, 1.0
	v_fmac_f32_e32 v142, v143, v142
	v_div_scale_f32 v143, vcc, v117, v32, v117
	v_mul_f32_e32 v144, v143, v142
	v_fma_f32 v145, -v133, v144, v143
	v_fmac_f32_e32 v144, v145, v142
	v_fma_f32 v133, -v133, v144, v143
	v_div_fmas_f32 v133, v133, v142, v144
	v_div_fixup_f32 v32, v133, v32, v117
	v_bfe_u32 v133, v32, 16, 1
	v_add3_u32 v32, v32, v133, s1
	global_store_short_d16_hi v[140:141], v32, off
	v_mul_f32_e32 v32, 0xbfb8aa3b, v101
	v_exp_f32_e32 v32, v32
	s_nop 0
	v_add_f32_e32 v32, 1.0, v32
	v_div_scale_f32 v133, s[2:3], v32, v32, v101
	v_rcp_f32_e32 v142, v133
	s_nop 0
	v_fma_f32 v143, -v133, v142, 1.0
	v_fmac_f32_e32 v142, v143, v142
	v_div_scale_f32 v143, vcc, v101, v32, v101
	v_mul_f32_e32 v144, v143, v142
	v_fma_f32 v145, -v133, v144, v143
	v_fmac_f32_e32 v144, v145, v142
	v_fma_f32 v133, -v133, v144, v143
	v_div_fmas_f32 v133, v133, v142, v144
	v_div_fixup_f32 v32, v133, v32, v101
	v_bfe_u32 v133, v32, 16, 1
	v_add3_u32 v32, v32, v133, s1
	global_store_short_d16_hi v[140:141], v32, off offset:128
	v_mul_f32_e32 v32, 0xbfb8aa3b, v118
	v_exp_f32_e32 v32, v32
	v_or_b32_e32 v142, 8, v132
	v_ashrrev_i32_e32 v143, 31, v142
	v_lshlrev_b64 v[142:143], 12, v[142:143]
	v_add_f32_e32 v32, 1.0, v32
	v_div_scale_f32 v133, s[2:3], v32, v32, v118
	v_rcp_f32_e32 v144, v133
	v_lshl_add_u64 v[142:143], v[130:131], 0, v[142:143]
	v_fma_f32 v145, -v133, v144, 1.0
	v_fmac_f32_e32 v144, v145, v144
	v_div_scale_f32 v145, vcc, v118, v32, v118
	v_mul_f32_e32 v146, v145, v144
	v_fma_f32 v147, -v133, v146, v145
	v_fmac_f32_e32 v146, v147, v144
	v_fma_f32 v133, -v133, v146, v145
	v_div_fmas_f32 v133, v133, v144, v146
	v_div_fixup_f32 v32, v133, v32, v118
	v_bfe_u32 v133, v32, 16, 1
	v_add3_u32 v32, v32, v133, s1
	global_store_short_d16_hi v[142:143], v32, off
	v_mul_f32_e32 v32, 0xbfb8aa3b, v102
	v_exp_f32_e32 v32, v32
	s_nop 0
	v_add_f32_e32 v32, 1.0, v32
	v_div_scale_f32 v133, s[2:3], v32, v32, v102
	v_rcp_f32_e32 v144, v133
	s_nop 0
	v_fma_f32 v145, -v133, v144, 1.0
	v_fmac_f32_e32 v144, v145, v144
	v_div_scale_f32 v145, vcc, v102, v32, v102
	v_mul_f32_e32 v146, v145, v144
	v_fma_f32 v147, -v133, v146, v145
	v_fmac_f32_e32 v146, v147, v144
	v_fma_f32 v133, -v133, v146, v145
	v_div_fmas_f32 v133, v133, v144, v146
	v_div_fixup_f32 v32, v133, v32, v102
	v_bfe_u32 v133, v32, 16, 1
	v_add3_u32 v32, v32, v133, s1
	global_store_short_d16_hi v[142:143], v32, off offset:128
	v_mul_f32_e32 v32, 0xbfb8aa3b, v119
	v_exp_f32_e32 v32, v32
	v_or_b32_e32 v144, 9, v132
	v_ashrrev_i32_e32 v145, 31, v144
	v_lshlrev_b64 v[144:145], 12, v[144:145]
	v_add_f32_e32 v32, 1.0, v32
	v_div_scale_f32 v133, s[2:3], v32, v32, v119
	v_rcp_f32_e32 v146, v133
	v_lshl_add_u64 v[144:145], v[130:131], 0, v[144:145]
	v_fma_f32 v147, -v133, v146, 1.0
	v_fmac_f32_e32 v146, v147, v146
	v_div_scale_f32 v147, vcc, v119, v32, v119
	v_mul_f32_e32 v148, v147, v146
	v_fma_f32 v149, -v133, v148, v147
	v_fmac_f32_e32 v148, v149, v146
	v_fma_f32 v133, -v133, v148, v147
	v_div_fmas_f32 v133, v133, v146, v148
	v_div_fixup_f32 v32, v133, v32, v119
	v_bfe_u32 v133, v32, 16, 1
	v_add3_u32 v32, v32, v133, s1
	global_store_short_d16_hi v[144:145], v32, off
	v_mul_f32_e32 v32, 0xbfb8aa3b, v103
	v_exp_f32_e32 v32, v32
	s_nop 0
	v_add_f32_e32 v32, 1.0, v32
	v_div_scale_f32 v133, s[2:3], v32, v32, v103
	v_rcp_f32_e32 v146, v133
	s_nop 0
	v_fma_f32 v147, -v133, v146, 1.0
	v_fmac_f32_e32 v146, v147, v146
	v_div_scale_f32 v147, vcc, v103, v32, v103
	v_mul_f32_e32 v148, v147, v146
	v_fma_f32 v149, -v133, v148, v147
	v_fmac_f32_e32 v148, v149, v146
	v_fma_f32 v133, -v133, v148, v147
	v_div_fmas_f32 v133, v133, v146, v148
	v_div_fixup_f32 v32, v133, v32, v103
	v_bfe_u32 v133, v32, 16, 1
	v_add3_u32 v32, v32, v133, s1
	global_store_short_d16_hi v[144:145], v32, off offset:128
	v_mul_f32_e32 v32, 0xbfb8aa3b, v120
	v_exp_f32_e32 v32, v32
	v_or_b32_e32 v146, 10, v132
	v_ashrrev_i32_e32 v147, 31, v146
	v_lshlrev_b64 v[146:147], 12, v[146:147]
	v_add_f32_e32 v32, 1.0, v32
	v_div_scale_f32 v133, s[2:3], v32, v32, v120
	v_rcp_f32_e32 v148, v133
	v_lshl_add_u64 v[146:147], v[130:131], 0, v[146:147]
	v_fma_f32 v149, -v133, v148, 1.0
	v_fmac_f32_e32 v148, v149, v148
	v_div_scale_f32 v149, vcc, v120, v32, v120
	v_mul_f32_e32 v150, v149, v148
	v_fma_f32 v151, -v133, v150, v149
	v_fmac_f32_e32 v150, v151, v148
	v_fma_f32 v133, -v133, v150, v149
	v_div_fmas_f32 v133, v133, v148, v150
	v_div_fixup_f32 v32, v133, v32, v120
	v_bfe_u32 v133, v32, 16, 1
	v_add3_u32 v32, v32, v133, s1
	global_store_short_d16_hi v[146:147], v32, off
	v_mul_f32_e32 v32, 0xbfb8aa3b, v104
	v_exp_f32_e32 v32, v32
	s_nop 0
	v_add_f32_e32 v32, 1.0, v32
	v_div_scale_f32 v133, s[2:3], v32, v32, v104
	v_rcp_f32_e32 v148, v133
	s_nop 0
	v_fma_f32 v149, -v133, v148, 1.0
	v_fmac_f32_e32 v148, v149, v148
	v_div_scale_f32 v149, vcc, v104, v32, v104
	v_mul_f32_e32 v150, v149, v148
	v_fma_f32 v151, -v133, v150, v149
	v_fmac_f32_e32 v150, v151, v148
	v_fma_f32 v133, -v133, v150, v149
	v_div_fmas_f32 v133, v133, v148, v150
	v_div_fixup_f32 v32, v133, v32, v104
	v_bfe_u32 v133, v32, 16, 1
	v_add3_u32 v32, v32, v133, s1
	global_store_short_d16_hi v[146:147], v32, off offset:128
	v_mul_f32_e32 v32, 0xbfb8aa3b, v121
	v_exp_f32_e32 v32, v32
	v_or_b32_e32 v148, 11, v132
	v_ashrrev_i32_e32 v149, 31, v148
	v_lshlrev_b64 v[148:149], 12, v[148:149]
	v_add_f32_e32 v32, 1.0, v32
	v_div_scale_f32 v133, s[2:3], v32, v32, v121
	v_rcp_f32_e32 v150, v133
	v_lshl_add_u64 v[148:149], v[130:131], 0, v[148:149]
	v_fma_f32 v151, -v133, v150, 1.0
	v_fmac_f32_e32 v150, v151, v150
	v_div_scale_f32 v151, vcc, v121, v32, v121
	v_mul_f32_e32 v152, v151, v150
	v_fma_f32 v153, -v133, v152, v151
	v_fmac_f32_e32 v152, v153, v150
	v_fma_f32 v133, -v133, v152, v151
	v_div_fmas_f32 v133, v133, v150, v152
	v_div_fixup_f32 v32, v133, v32, v121
	v_bfe_u32 v133, v32, 16, 1
	v_add3_u32 v32, v32, v133, s1
	global_store_short_d16_hi v[148:149], v32, off
	v_mul_f32_e32 v32, 0xbfb8aa3b, v105
	v_exp_f32_e32 v32, v32
	s_nop 0
	v_add_f32_e32 v32, 1.0, v32
	v_div_scale_f32 v133, s[2:3], v32, v32, v105
	v_rcp_f32_e32 v150, v133
	s_nop 0
	v_fma_f32 v151, -v133, v150, 1.0
	v_fmac_f32_e32 v150, v151, v150
	v_div_scale_f32 v151, vcc, v105, v32, v105
	v_mul_f32_e32 v152, v151, v150
	v_fma_f32 v153, -v133, v152, v151
	v_fmac_f32_e32 v152, v153, v150
	v_fma_f32 v133, -v133, v152, v151
	v_div_fmas_f32 v133, v133, v150, v152
	v_div_fixup_f32 v32, v133, v32, v105
	v_bfe_u32 v133, v32, 16, 1
	v_add3_u32 v32, v32, v133, s1
	global_store_short_d16_hi v[148:149], v32, off offset:128
	v_mul_f32_e32 v32, 0xbfb8aa3b, v122
	v_exp_f32_e32 v32, v32
	v_or_b32_e32 v150, 16, v132
	v_ashrrev_i32_e32 v151, 31, v150
	v_lshlrev_b64 v[150:151], 12, v[150:151]
	v_add_f32_e32 v32, 1.0, v32
	v_div_scale_f32 v133, s[2:3], v32, v32, v122
	v_rcp_f32_e32 v152, v133
	v_lshl_add_u64 v[150:151], v[130:131], 0, v[150:151]
	v_fma_f32 v153, -v133, v152, 1.0
	v_fmac_f32_e32 v152, v153, v152
	v_div_scale_f32 v153, vcc, v122, v32, v122
	v_mul_f32_e32 v154, v153, v152
	v_fma_f32 v155, -v133, v154, v153
	v_fmac_f32_e32 v154, v155, v152
	v_fma_f32 v133, -v133, v154, v153
	v_div_fmas_f32 v133, v133, v152, v154
	v_div_fixup_f32 v32, v133, v32, v122
	v_bfe_u32 v133, v32, 16, 1
	v_add3_u32 v32, v32, v133, s1
	global_store_short_d16_hi v[150:151], v32, off
	v_mul_f32_e32 v32, 0xbfb8aa3b, v106
	v_exp_f32_e32 v32, v32
	s_nop 0
	v_add_f32_e32 v32, 1.0, v32
	v_div_scale_f32 v133, s[2:3], v32, v32, v106
	v_rcp_f32_e32 v152, v133
	s_nop 0
	v_fma_f32 v153, -v133, v152, 1.0
	v_fmac_f32_e32 v152, v153, v152
	v_div_scale_f32 v153, vcc, v106, v32, v106
	v_mul_f32_e32 v154, v153, v152
	v_fma_f32 v155, -v133, v154, v153
	v_fmac_f32_e32 v154, v155, v152
	v_fma_f32 v133, -v133, v154, v153
	v_div_fmas_f32 v133, v133, v152, v154
	v_div_fixup_f32 v32, v133, v32, v106
	v_bfe_u32 v133, v32, 16, 1
	v_add3_u32 v32, v32, v133, s1
	global_store_short_d16_hi v[150:151], v32, off offset:128
	v_mul_f32_e32 v32, 0xbfb8aa3b, v123
	v_exp_f32_e32 v32, v32
	v_or_b32_e32 v152, 17, v132
	v_ashrrev_i32_e32 v153, 31, v152
	v_lshlrev_b64 v[152:153], 12, v[152:153]
	v_add_f32_e32 v32, 1.0, v32
	v_div_scale_f32 v133, s[2:3], v32, v32, v123
	v_rcp_f32_e32 v154, v133
	v_lshl_add_u64 v[152:153], v[130:131], 0, v[152:153]
	v_fma_f32 v155, -v133, v154, 1.0
	v_fmac_f32_e32 v154, v155, v154
	v_div_scale_f32 v155, vcc, v123, v32, v123
	v_mul_f32_e32 v156, v155, v154
	v_fma_f32 v157, -v133, v156, v155
	v_fmac_f32_e32 v156, v157, v154
	v_fma_f32 v133, -v133, v156, v155
	v_div_fmas_f32 v133, v133, v154, v156
	v_div_fixup_f32 v32, v133, v32, v123
	v_bfe_u32 v133, v32, 16, 1
	v_add3_u32 v32, v32, v133, s1
	global_store_short_d16_hi v[152:153], v32, off
	v_mul_f32_e32 v32, 0xbfb8aa3b, v107
	v_exp_f32_e32 v32, v32
	s_nop 0
	v_add_f32_e32 v32, 1.0, v32
	v_div_scale_f32 v133, s[2:3], v32, v32, v107
	v_rcp_f32_e32 v154, v133
	s_nop 0
	v_fma_f32 v155, -v133, v154, 1.0
	v_fmac_f32_e32 v154, v155, v154
	v_div_scale_f32 v155, vcc, v107, v32, v107
	v_mul_f32_e32 v156, v155, v154
	v_fma_f32 v157, -v133, v156, v155
	v_fmac_f32_e32 v156, v157, v154
	v_fma_f32 v133, -v133, v156, v155
	v_div_fmas_f32 v133, v133, v154, v156
	v_div_fixup_f32 v32, v133, v32, v107
	v_bfe_u32 v133, v32, 16, 1
	v_add3_u32 v32, v32, v133, s1
	global_store_short_d16_hi v[152:153], v32, off offset:128
	v_mul_f32_e32 v32, 0xbfb8aa3b, v124
	v_exp_f32_e32 v32, v32
	v_or_b32_e32 v154, 18, v132
	v_ashrrev_i32_e32 v155, 31, v154
	v_lshlrev_b64 v[154:155], 12, v[154:155]
	v_add_f32_e32 v32, 1.0, v32
	v_div_scale_f32 v133, s[2:3], v32, v32, v124
	v_rcp_f32_e32 v156, v133
	v_lshl_add_u64 v[154:155], v[130:131], 0, v[154:155]
	v_fma_f32 v157, -v133, v156, 1.0
	v_fmac_f32_e32 v156, v157, v156
	v_div_scale_f32 v157, vcc, v124, v32, v124
	v_mul_f32_e32 v158, v157, v156
	v_fma_f32 v159, -v133, v158, v157
	v_fmac_f32_e32 v158, v159, v156
	v_fma_f32 v133, -v133, v158, v157
	v_div_fmas_f32 v133, v133, v156, v158
	v_div_fixup_f32 v32, v133, v32, v124
	v_bfe_u32 v133, v32, 16, 1
	v_add3_u32 v32, v32, v133, s1
	global_store_short_d16_hi v[154:155], v32, off
	v_mul_f32_e32 v32, 0xbfb8aa3b, v108
	v_exp_f32_e32 v32, v32
	s_nop 0
	v_add_f32_e32 v32, 1.0, v32
	v_div_scale_f32 v133, s[2:3], v32, v32, v108
	v_rcp_f32_e32 v156, v133
	s_nop 0
	v_fma_f32 v157, -v133, v156, 1.0
	v_fmac_f32_e32 v156, v157, v156
	v_div_scale_f32 v157, vcc, v108, v32, v108
	v_mul_f32_e32 v158, v157, v156
	v_fma_f32 v159, -v133, v158, v157
	v_fmac_f32_e32 v158, v159, v156
	v_fma_f32 v133, -v133, v158, v157
	v_div_fmas_f32 v133, v133, v156, v158
	v_div_fixup_f32 v32, v133, v32, v108
	v_bfe_u32 v133, v32, 16, 1
	v_add3_u32 v32, v32, v133, s1
	global_store_short_d16_hi v[154:155], v32, off offset:128
	v_mul_f32_e32 v32, 0xbfb8aa3b, v125
	v_exp_f32_e32 v32, v32
	v_or_b32_e32 v156, 19, v132
	v_ashrrev_i32_e32 v157, 31, v156
	v_lshlrev_b64 v[156:157], 12, v[156:157]
	v_add_f32_e32 v32, 1.0, v32
	v_div_scale_f32 v133, s[2:3], v32, v32, v125
	v_rcp_f32_e32 v158, v133
	v_lshl_add_u64 v[156:157], v[130:131], 0, v[156:157]
	v_fma_f32 v159, -v133, v158, 1.0
	v_fmac_f32_e32 v158, v159, v158
	v_div_scale_f32 v159, vcc, v125, v32, v125
	v_mul_f32_e32 v160, v159, v158
	v_fma_f32 v161, -v133, v160, v159
	v_fmac_f32_e32 v160, v161, v158
	v_fma_f32 v133, -v133, v160, v159
	v_div_fmas_f32 v133, v133, v158, v160
	v_div_fixup_f32 v32, v133, v32, v125
	v_bfe_u32 v133, v32, 16, 1
	v_add3_u32 v32, v32, v133, s1
	global_store_short_d16_hi v[156:157], v32, off
	v_mul_f32_e32 v32, 0xbfb8aa3b, v109
	v_exp_f32_e32 v32, v32
	s_nop 0
	v_add_f32_e32 v32, 1.0, v32
	v_div_scale_f32 v133, s[2:3], v32, v32, v109
	v_rcp_f32_e32 v158, v133
	s_nop 0
	v_fma_f32 v159, -v133, v158, 1.0
	v_fmac_f32_e32 v158, v159, v158
	v_div_scale_f32 v159, vcc, v109, v32, v109
	v_mul_f32_e32 v160, v159, v158
	v_fma_f32 v161, -v133, v160, v159
	v_fmac_f32_e32 v160, v161, v158
	v_fma_f32 v133, -v133, v160, v159
	v_div_fmas_f32 v133, v133, v158, v160
	v_div_fixup_f32 v32, v133, v32, v109
	v_bfe_u32 v133, v32, 16, 1
	v_add3_u32 v32, v32, v133, s1
	global_store_short_d16_hi v[156:157], v32, off offset:128
	v_mul_f32_e32 v32, 0xbfb8aa3b, v126
	v_exp_f32_e32 v32, v32
	v_or_b32_e32 v158, 24, v132
	v_ashrrev_i32_e32 v159, 31, v158
	v_lshlrev_b64 v[158:159], 12, v[158:159]
	v_add_f32_e32 v32, 1.0, v32
	v_div_scale_f32 v133, s[2:3], v32, v32, v126
	v_rcp_f32_e32 v160, v133
	v_lshl_add_u64 v[158:159], v[130:131], 0, v[158:159]
	v_fma_f32 v161, -v133, v160, 1.0
	v_fmac_f32_e32 v160, v161, v160
	v_div_scale_f32 v161, vcc, v126, v32, v126
	v_mul_f32_e32 v162, v161, v160
	v_fma_f32 v163, -v133, v162, v161
	v_fmac_f32_e32 v162, v163, v160
	v_fma_f32 v133, -v133, v162, v161
	v_div_fmas_f32 v133, v133, v160, v162
	v_div_fixup_f32 v32, v133, v32, v126
	v_bfe_u32 v133, v32, 16, 1
	v_add3_u32 v32, v32, v133, s1
	global_store_short_d16_hi v[158:159], v32, off
	v_mul_f32_e32 v32, 0xbfb8aa3b, v110
	v_exp_f32_e32 v32, v32
	s_nop 0
	v_add_f32_e32 v32, 1.0, v32
	v_div_scale_f32 v133, s[2:3], v32, v32, v110
	v_rcp_f32_e32 v160, v133
	s_nop 0
	v_fma_f32 v161, -v133, v160, 1.0
	v_fmac_f32_e32 v160, v161, v160
	v_div_scale_f32 v161, vcc, v110, v32, v110
	v_mul_f32_e32 v162, v161, v160
	v_fma_f32 v163, -v133, v162, v161
	v_fmac_f32_e32 v162, v163, v160
	v_fma_f32 v133, -v133, v162, v161
	v_div_fmas_f32 v133, v133, v160, v162
	v_div_fixup_f32 v32, v133, v32, v110
	v_bfe_u32 v133, v32, 16, 1
	v_add3_u32 v32, v32, v133, s1
	global_store_short_d16_hi v[158:159], v32, off offset:128
	v_mul_f32_e32 v32, 0xbfb8aa3b, v127
	v_exp_f32_e32 v32, v32
	v_or_b32_e32 v160, 25, v132
	v_ashrrev_i32_e32 v161, 31, v160
	v_lshlrev_b64 v[160:161], 12, v[160:161]
	v_add_f32_e32 v32, 1.0, v32
	v_div_scale_f32 v133, s[2:3], v32, v32, v127
	v_rcp_f32_e32 v162, v133
	v_lshl_add_u64 v[160:161], v[130:131], 0, v[160:161]
	v_fma_f32 v163, -v133, v162, 1.0
	v_fmac_f32_e32 v162, v163, v162
	v_div_scale_f32 v163, vcc, v127, v32, v127
	v_mul_f32_e32 v164, v163, v162
	v_fma_f32 v165, -v133, v164, v163
	v_fmac_f32_e32 v164, v165, v162
	v_fma_f32 v133, -v133, v164, v163
	v_div_fmas_f32 v133, v133, v162, v164
	v_div_fixup_f32 v32, v133, v32, v127
	v_bfe_u32 v133, v32, 16, 1
	v_add3_u32 v32, v32, v133, s1
	global_store_short_d16_hi v[160:161], v32, off
	v_mul_f32_e32 v32, 0xbfb8aa3b, v111
	v_exp_f32_e32 v32, v32
	s_nop 0
	v_add_f32_e32 v32, 1.0, v32
	v_div_scale_f32 v133, s[2:3], v32, v32, v111
	v_rcp_f32_e32 v162, v133
	s_nop 0
	v_fma_f32 v163, -v133, v162, 1.0
	v_fmac_f32_e32 v162, v163, v162
	v_div_scale_f32 v163, vcc, v111, v32, v111
	v_mul_f32_e32 v164, v163, v162
	v_fma_f32 v165, -v133, v164, v163
	v_fmac_f32_e32 v164, v165, v162
	v_fma_f32 v133, -v133, v164, v163
	v_div_fmas_f32 v133, v133, v162, v164
	v_div_fixup_f32 v32, v133, v32, v111
	v_bfe_u32 v133, v32, 16, 1
	v_add3_u32 v32, v32, v133, s1
	global_store_short_d16_hi v[160:161], v32, off offset:128
	v_mul_f32_e32 v32, 0xbfb8aa3b, v128
	v_exp_f32_e32 v32, v32
	v_or_b32_e32 v162, 26, v132
	v_ashrrev_i32_e32 v163, 31, v162
	v_lshlrev_b64 v[162:163], 12, v[162:163]
	v_add_f32_e32 v32, 1.0, v32
	v_div_scale_f32 v133, s[2:3], v32, v32, v128
	v_rcp_f32_e32 v164, v133
	v_lshl_add_u64 v[162:163], v[130:131], 0, v[162:163]
	v_fma_f32 v165, -v133, v164, 1.0
	v_fmac_f32_e32 v164, v165, v164
	v_div_scale_f32 v165, vcc, v128, v32, v128
	v_mul_f32_e32 v166, v165, v164
	v_fma_f32 v167, -v133, v166, v165
	v_fmac_f32_e32 v166, v167, v164
	v_fma_f32 v133, -v133, v166, v165
	v_div_fmas_f32 v133, v133, v164, v166
	v_div_fixup_f32 v32, v133, v32, v128
	v_bfe_u32 v133, v32, 16, 1
	v_add3_u32 v32, v32, v133, s1
	global_store_short_d16_hi v[162:163], v32, off
	v_mul_f32_e32 v32, 0xbfb8aa3b, v112
	v_exp_f32_e32 v32, v32
	s_nop 0
	v_add_f32_e32 v32, 1.0, v32
	v_div_scale_f32 v133, s[2:3], v32, v32, v112
	v_rcp_f32_e32 v164, v133
	s_nop 0
	v_fma_f32 v165, -v133, v164, 1.0
	v_fmac_f32_e32 v164, v165, v164
	v_div_scale_f32 v165, vcc, v112, v32, v112
	v_mul_f32_e32 v166, v165, v164
	v_fma_f32 v167, -v133, v166, v165
	v_fmac_f32_e32 v166, v167, v164
	v_fma_f32 v133, -v133, v166, v165
	v_div_fmas_f32 v133, v133, v164, v166
	v_div_fixup_f32 v32, v133, v32, v112
	v_bfe_u32 v133, v32, 16, 1
	v_add3_u32 v32, v32, v133, s1
	global_store_short_d16_hi v[162:163], v32, off offset:128
	v_mul_f32_e32 v32, 0xbfb8aa3b, v129
	v_exp_f32_e32 v32, v32
	v_or_b32_e32 v164, 27, v132
	v_ashrrev_i32_e32 v165, 31, v164
	v_lshlrev_b64 v[164:165], 12, v[164:165]
	v_add_f32_e32 v32, 1.0, v32
	v_div_scale_f32 v133, s[2:3], v32, v32, v129
	v_rcp_f32_e32 v166, v133
	v_lshl_add_u64 v[164:165], v[130:131], 0, v[164:165]
	v_fma_f32 v167, -v133, v166, 1.0
	v_fmac_f32_e32 v166, v167, v166
	v_div_scale_f32 v167, vcc, v129, v32, v129
	v_mul_f32_e32 v168, v167, v166
	v_fma_f32 v169, -v133, v168, v167
	v_fmac_f32_e32 v168, v169, v166
	v_fma_f32 v133, -v133, v168, v167
	v_div_fmas_f32 v133, v133, v166, v168
	v_div_fixup_f32 v32, v133, v32, v129
	v_bfe_u32 v133, v32, 16, 1
	v_add3_u32 v32, v32, v133, s1
	global_store_short_d16_hi v[164:165], v32, off
	v_mul_f32_e32 v32, 0xbfb8aa3b, v113
	v_exp_f32_e32 v32, v32
	s_nop 0
	v_add_f32_e32 v32, 1.0, v32
	v_div_scale_f32 v133, s[2:3], v32, v32, v113
	v_rcp_f32_e32 v166, v133
	s_nop 0
	v_fma_f32 v167, -v133, v166, 1.0
	v_fmac_f32_e32 v166, v167, v166
	v_div_scale_f32 v167, vcc, v113, v32, v113
	v_mul_f32_e32 v168, v167, v166
	v_fma_f32 v169, -v133, v168, v167
	v_fmac_f32_e32 v168, v169, v166
	v_fma_f32 v133, -v133, v168, v167
	v_div_fmas_f32 v133, v133, v166, v168
	v_div_fixup_f32 v32, v133, v32, v113
	v_bfe_u32 v133, v32, 16, 1
	v_add3_u32 v32, v32, v133, s1
	global_store_short_d16_hi v[164:165], v32, off offset:128
	v_mul_f32_e32 v32, 0xbfb8aa3b, v82
	v_exp_f32_e32 v32, v32
	s_nop 0
	v_add_f32_e32 v32, 1.0, v32
	v_div_scale_f32 v133, s[2:3], v32, v32, v82
	v_rcp_f32_e32 v166, v133
	s_nop 0
	v_fma_f32 v167, -v133, v166, 1.0
	v_fmac_f32_e32 v166, v167, v166
	v_div_scale_f32 v167, vcc, v82, v32, v82
	v_mul_f32_e32 v168, v167, v166
	v_fma_f32 v169, -v133, v168, v167
	v_fmac_f32_e32 v168, v169, v166
	v_fma_f32 v133, -v133, v168, v167
	v_div_fmas_f32 v133, v133, v166, v168
	v_div_fixup_f32 v32, v133, v32, v82
	v_bfe_u32 v133, v32, 16, 1
	v_add3_u32 v32, v32, v133, s1
	global_store_short_d16_hi v[134:135], v32, off offset:64
	v_mul_f32_e32 v32, 0xbfb8aa3b, v66
	v_exp_f32_e32 v32, v32
	s_nop 0
	v_add_f32_e32 v32, 1.0, v32
	v_div_scale_f32 v133, s[2:3], v32, v32, v66
	v_rcp_f32_e32 v166, v133
	s_nop 0
	v_fma_f32 v167, -v133, v166, 1.0
	v_fmac_f32_e32 v166, v167, v166
	v_div_scale_f32 v167, vcc, v66, v32, v66
	v_mul_f32_e32 v168, v167, v166
	v_fma_f32 v169, -v133, v168, v167
	v_fmac_f32_e32 v168, v169, v166
	v_fma_f32 v133, -v133, v168, v167
	v_div_fmas_f32 v133, v133, v166, v168
	v_div_fixup_f32 v32, v133, v32, v66
	v_bfe_u32 v133, v32, 16, 1
	v_add3_u32 v32, v32, v133, s1
	global_store_short_d16_hi v[134:135], v32, off offset:192
	v_mul_f32_e32 v32, 0xbfb8aa3b, v83
	v_exp_f32_e32 v32, v32
	s_nop 0
	v_add_f32_e32 v32, 1.0, v32
	v_div_scale_f32 v133, s[2:3], v32, v32, v83
	v_rcp_f32_e32 v134, v133
	s_nop 0
	v_fma_f32 v135, -v133, v134, 1.0
	v_fmac_f32_e32 v134, v135, v134
	v_div_scale_f32 v135, vcc, v83, v32, v83
	v_mul_f32_e32 v166, v135, v134
	v_fma_f32 v167, -v133, v166, v135
	v_fmac_f32_e32 v166, v167, v134
	v_fma_f32 v133, -v133, v166, v135
	v_div_fmas_f32 v133, v133, v134, v166
	v_div_fixup_f32 v32, v133, v32, v83
	v_bfe_u32 v133, v32, 16, 1
	v_add3_u32 v32, v32, v133, s1
	global_store_short_d16_hi v[136:137], v32, off offset:64
	v_mul_f32_e32 v32, 0xbfb8aa3b, v67
	v_exp_f32_e32 v32, v32
	s_nop 0
	v_add_f32_e32 v32, 1.0, v32
	v_div_scale_f32 v133, s[2:3], v32, v32, v67
	v_rcp_f32_e32 v134, v133
	s_nop 0
	v_fma_f32 v135, -v133, v134, 1.0
	v_fmac_f32_e32 v134, v135, v134
	v_div_scale_f32 v135, vcc, v67, v32, v67
	v_mul_f32_e32 v166, v135, v134
	v_fma_f32 v167, -v133, v166, v135
	v_fmac_f32_e32 v166, v167, v134
	v_fma_f32 v133, -v133, v166, v135
	v_div_fmas_f32 v133, v133, v134, v166
	v_div_fixup_f32 v32, v133, v32, v67
	v_bfe_u32 v133, v32, 16, 1
	v_add3_u32 v32, v32, v133, s1
	global_store_short_d16_hi v[136:137], v32, off offset:192
	v_mul_f32_e32 v32, 0xbfb8aa3b, v84
	v_exp_f32_e32 v32, v32
	s_nop 0
	v_add_f32_e32 v32, 1.0, v32
	v_div_scale_f32 v133, s[2:3], v32, v32, v84
	v_rcp_f32_e32 v134, v133
	s_nop 0
	v_fma_f32 v135, -v133, v134, 1.0
	v_fmac_f32_e32 v134, v135, v134
	v_div_scale_f32 v135, vcc, v84, v32, v84
	v_mul_f32_e32 v136, v135, v134
	v_fma_f32 v137, -v133, v136, v135
	v_fmac_f32_e32 v136, v137, v134
	v_fma_f32 v133, -v133, v136, v135
	v_div_fmas_f32 v133, v133, v134, v136
	v_div_fixup_f32 v32, v133, v32, v84
	v_bfe_u32 v133, v32, 16, 1
	v_add3_u32 v32, v32, v133, s1
	global_store_short_d16_hi v[138:139], v32, off offset:64
	v_mul_f32_e32 v32, 0xbfb8aa3b, v68
	v_exp_f32_e32 v32, v32
	s_nop 0
	v_add_f32_e32 v32, 1.0, v32
	v_div_scale_f32 v133, s[2:3], v32, v32, v68
	v_rcp_f32_e32 v134, v133
	s_nop 0
	v_fma_f32 v135, -v133, v134, 1.0
	v_fmac_f32_e32 v134, v135, v134
	v_div_scale_f32 v135, vcc, v68, v32, v68
	v_mul_f32_e32 v136, v135, v134
	v_fma_f32 v137, -v133, v136, v135
	v_fmac_f32_e32 v136, v137, v134
	v_fma_f32 v133, -v133, v136, v135
	v_div_fmas_f32 v133, v133, v134, v136
	v_div_fixup_f32 v32, v133, v32, v68
	v_bfe_u32 v133, v32, 16, 1
	v_add3_u32 v32, v32, v133, s1
	global_store_short_d16_hi v[138:139], v32, off offset:192
	v_mul_f32_e32 v32, 0xbfb8aa3b, v85
	v_exp_f32_e32 v32, v32
	s_nop 0
	v_add_f32_e32 v32, 1.0, v32
	v_div_scale_f32 v133, s[2:3], v32, v32, v85
	v_rcp_f32_e32 v134, v133
	s_nop 0
	v_fma_f32 v135, -v133, v134, 1.0
	v_fmac_f32_e32 v134, v135, v134
	v_div_scale_f32 v135, vcc, v85, v32, v85
	v_mul_f32_e32 v136, v135, v134
	v_fma_f32 v137, -v133, v136, v135
	v_fmac_f32_e32 v136, v137, v134
	v_fma_f32 v133, -v133, v136, v135
	v_div_fmas_f32 v133, v133, v134, v136
	v_div_fixup_f32 v32, v133, v32, v85
	v_bfe_u32 v133, v32, 16, 1
	v_add3_u32 v32, v32, v133, s1
	global_store_short_d16_hi v[140:141], v32, off offset:64
	v_mul_f32_e32 v32, 0xbfb8aa3b, v69
	v_exp_f32_e32 v32, v32
	s_nop 0
	v_add_f32_e32 v32, 1.0, v32
	v_div_scale_f32 v133, s[2:3], v32, v32, v69
	v_rcp_f32_e32 v134, v133
	s_nop 0
	v_fma_f32 v135, -v133, v134, 1.0
	v_fmac_f32_e32 v134, v135, v134
	v_div_scale_f32 v135, vcc, v69, v32, v69
	v_mul_f32_e32 v136, v135, v134
	v_fma_f32 v137, -v133, v136, v135
	v_fmac_f32_e32 v136, v137, v134
	v_fma_f32 v133, -v133, v136, v135
	v_div_fmas_f32 v133, v133, v134, v136
	v_div_fixup_f32 v32, v133, v32, v69
	v_bfe_u32 v133, v32, 16, 1
	v_add3_u32 v32, v32, v133, s1
	global_store_short_d16_hi v[140:141], v32, off offset:192
	v_mul_f32_e32 v32, 0xbfb8aa3b, v86
	v_exp_f32_e32 v32, v32
	s_nop 0
	v_add_f32_e32 v32, 1.0, v32
	v_div_scale_f32 v133, s[2:3], v32, v32, v86
	v_rcp_f32_e32 v134, v133
	s_nop 0
	v_fma_f32 v135, -v133, v134, 1.0
	v_fmac_f32_e32 v134, v135, v134
	v_div_scale_f32 v135, vcc, v86, v32, v86
	v_mul_f32_e32 v136, v135, v134
	v_fma_f32 v137, -v133, v136, v135
	v_fmac_f32_e32 v136, v137, v134
	v_fma_f32 v133, -v133, v136, v135
	v_div_fmas_f32 v133, v133, v134, v136
	v_div_fixup_f32 v32, v133, v32, v86
	v_bfe_u32 v133, v32, 16, 1
	v_add3_u32 v32, v32, v133, s1
	global_store_short_d16_hi v[142:143], v32, off offset:64
	v_mul_f32_e32 v32, 0xbfb8aa3b, v70
	v_exp_f32_e32 v32, v32
	s_nop 0
	v_add_f32_e32 v32, 1.0, v32
	v_div_scale_f32 v133, s[2:3], v32, v32, v70
	v_rcp_f32_e32 v134, v133
	s_nop 0
	v_fma_f32 v135, -v133, v134, 1.0
	v_fmac_f32_e32 v134, v135, v134
	v_div_scale_f32 v135, vcc, v70, v32, v70
	v_mul_f32_e32 v136, v135, v134
	v_fma_f32 v137, -v133, v136, v135
	v_fmac_f32_e32 v136, v137, v134
	v_fma_f32 v133, -v133, v136, v135
	v_div_fmas_f32 v133, v133, v134, v136
	v_div_fixup_f32 v32, v133, v32, v70
	v_bfe_u32 v133, v32, 16, 1
	v_add3_u32 v32, v32, v133, s1
	global_store_short_d16_hi v[142:143], v32, off offset:192
	v_mul_f32_e32 v32, 0xbfb8aa3b, v87
	v_exp_f32_e32 v32, v32
	s_nop 0
	v_add_f32_e32 v32, 1.0, v32
	v_div_scale_f32 v133, s[2:3], v32, v32, v87
	v_rcp_f32_e32 v134, v133
	s_nop 0
	v_fma_f32 v135, -v133, v134, 1.0
	v_fmac_f32_e32 v134, v135, v134
	v_div_scale_f32 v135, vcc, v87, v32, v87
	v_mul_f32_e32 v136, v135, v134
	v_fma_f32 v137, -v133, v136, v135
	v_fmac_f32_e32 v136, v137, v134
	v_fma_f32 v133, -v133, v136, v135
	v_div_fmas_f32 v133, v133, v134, v136
	v_div_fixup_f32 v32, v133, v32, v87
	v_bfe_u32 v133, v32, 16, 1
	v_add3_u32 v32, v32, v133, s1
	global_store_short_d16_hi v[144:145], v32, off offset:64
	v_mul_f32_e32 v32, 0xbfb8aa3b, v71
	v_exp_f32_e32 v32, v32
	s_nop 0
	v_add_f32_e32 v32, 1.0, v32
	v_div_scale_f32 v133, s[2:3], v32, v32, v71
	v_rcp_f32_e32 v134, v133
	s_nop 0
	v_fma_f32 v135, -v133, v134, 1.0
	v_fmac_f32_e32 v134, v135, v134
	v_div_scale_f32 v135, vcc, v71, v32, v71
	v_mul_f32_e32 v136, v135, v134
	v_fma_f32 v137, -v133, v136, v135
	v_fmac_f32_e32 v136, v137, v134
	v_fma_f32 v133, -v133, v136, v135
	v_div_fmas_f32 v133, v133, v134, v136
	v_div_fixup_f32 v32, v133, v32, v71
	v_bfe_u32 v133, v32, 16, 1
	v_add3_u32 v32, v32, v133, s1
	global_store_short_d16_hi v[144:145], v32, off offset:192
	v_mul_f32_e32 v32, 0xbfb8aa3b, v88
	v_exp_f32_e32 v32, v32
	s_nop 0
	v_add_f32_e32 v32, 1.0, v32
	v_div_scale_f32 v133, s[2:3], v32, v32, v88
	v_rcp_f32_e32 v134, v133
	s_nop 0
	v_fma_f32 v135, -v133, v134, 1.0
	v_fmac_f32_e32 v134, v135, v134
	v_div_scale_f32 v135, vcc, v88, v32, v88
	v_mul_f32_e32 v136, v135, v134
	v_fma_f32 v137, -v133, v136, v135
	v_fmac_f32_e32 v136, v137, v134
	v_fma_f32 v133, -v133, v136, v135
	v_div_fmas_f32 v133, v133, v134, v136
	v_div_fixup_f32 v32, v133, v32, v88
	v_bfe_u32 v133, v32, 16, 1
	v_add3_u32 v32, v32, v133, s1
	global_store_short_d16_hi v[146:147], v32, off offset:64
	v_mul_f32_e32 v32, 0xbfb8aa3b, v72
	v_exp_f32_e32 v32, v32
	s_nop 0
	v_add_f32_e32 v32, 1.0, v32
	v_div_scale_f32 v133, s[2:3], v32, v32, v72
	v_rcp_f32_e32 v134, v133
	s_nop 0
	v_fma_f32 v135, -v133, v134, 1.0
	v_fmac_f32_e32 v134, v135, v134
	v_div_scale_f32 v135, vcc, v72, v32, v72
	v_mul_f32_e32 v136, v135, v134
	v_fma_f32 v137, -v133, v136, v135
	v_fmac_f32_e32 v136, v137, v134
	v_fma_f32 v133, -v133, v136, v135
	v_div_fmas_f32 v133, v133, v134, v136
	v_div_fixup_f32 v32, v133, v32, v72
	v_bfe_u32 v133, v32, 16, 1
	v_add3_u32 v32, v32, v133, s1
	global_store_short_d16_hi v[146:147], v32, off offset:192
	v_mul_f32_e32 v32, 0xbfb8aa3b, v89
	v_exp_f32_e32 v32, v32
	s_nop 0
	v_add_f32_e32 v32, 1.0, v32
	v_div_scale_f32 v133, s[2:3], v32, v32, v89
	v_rcp_f32_e32 v134, v133
	s_nop 0
	v_fma_f32 v135, -v133, v134, 1.0
	v_fmac_f32_e32 v134, v135, v134
	v_div_scale_f32 v135, vcc, v89, v32, v89
	v_mul_f32_e32 v136, v135, v134
	v_fma_f32 v137, -v133, v136, v135
	v_fmac_f32_e32 v136, v137, v134
	v_fma_f32 v133, -v133, v136, v135
	v_div_fmas_f32 v133, v133, v134, v136
	v_div_fixup_f32 v32, v133, v32, v89
	v_bfe_u32 v133, v32, 16, 1
	v_add3_u32 v32, v32, v133, s1
	global_store_short_d16_hi v[148:149], v32, off offset:64
	v_mul_f32_e32 v32, 0xbfb8aa3b, v73
	v_exp_f32_e32 v32, v32
	s_nop 0
	v_add_f32_e32 v32, 1.0, v32
	v_div_scale_f32 v133, s[2:3], v32, v32, v73
	v_rcp_f32_e32 v134, v133
	s_nop 0
	v_fma_f32 v135, -v133, v134, 1.0
	v_fmac_f32_e32 v134, v135, v134
	v_div_scale_f32 v135, vcc, v73, v32, v73
	v_mul_f32_e32 v136, v135, v134
	v_fma_f32 v137, -v133, v136, v135
	v_fmac_f32_e32 v136, v137, v134
	v_fma_f32 v133, -v133, v136, v135
	v_div_fmas_f32 v133, v133, v134, v136
	v_div_fixup_f32 v32, v133, v32, v73
	v_bfe_u32 v133, v32, 16, 1
	v_add3_u32 v32, v32, v133, s1
	global_store_short_d16_hi v[148:149], v32, off offset:192
	v_mul_f32_e32 v32, 0xbfb8aa3b, v90
	v_exp_f32_e32 v32, v32
	s_nop 0
	v_add_f32_e32 v32, 1.0, v32
	v_div_scale_f32 v133, s[2:3], v32, v32, v90
	v_rcp_f32_e32 v134, v133
	s_nop 0
	v_fma_f32 v135, -v133, v134, 1.0
	v_fmac_f32_e32 v134, v135, v134
	v_div_scale_f32 v135, vcc, v90, v32, v90
	v_mul_f32_e32 v136, v135, v134
	v_fma_f32 v137, -v133, v136, v135
	v_fmac_f32_e32 v136, v137, v134
	v_fma_f32 v133, -v133, v136, v135
	v_div_fmas_f32 v133, v133, v134, v136
	v_div_fixup_f32 v32, v133, v32, v90
	v_bfe_u32 v133, v32, 16, 1
	v_add3_u32 v32, v32, v133, s1
	global_store_short_d16_hi v[150:151], v32, off offset:64
	v_mul_f32_e32 v32, 0xbfb8aa3b, v74
	v_exp_f32_e32 v32, v32
	s_nop 0
	v_add_f32_e32 v32, 1.0, v32
	v_div_scale_f32 v133, s[2:3], v32, v32, v74
	v_rcp_f32_e32 v134, v133
	s_nop 0
	v_fma_f32 v135, -v133, v134, 1.0
	v_fmac_f32_e32 v134, v135, v134
	v_div_scale_f32 v135, vcc, v74, v32, v74
	v_mul_f32_e32 v136, v135, v134
	v_fma_f32 v137, -v133, v136, v135
	v_fmac_f32_e32 v136, v137, v134
	v_fma_f32 v133, -v133, v136, v135
	v_div_fmas_f32 v133, v133, v134, v136
	v_div_fixup_f32 v32, v133, v32, v74
	v_bfe_u32 v133, v32, 16, 1
	v_add3_u32 v32, v32, v133, s1
	global_store_short_d16_hi v[150:151], v32, off offset:192
	v_mul_f32_e32 v32, 0xbfb8aa3b, v91
	v_exp_f32_e32 v32, v32
	s_nop 0
	v_add_f32_e32 v32, 1.0, v32
	v_div_scale_f32 v133, s[2:3], v32, v32, v91
	v_rcp_f32_e32 v134, v133
	s_nop 0
	v_fma_f32 v135, -v133, v134, 1.0
	v_fmac_f32_e32 v134, v135, v134
	v_div_scale_f32 v135, vcc, v91, v32, v91
	v_mul_f32_e32 v136, v135, v134
	v_fma_f32 v137, -v133, v136, v135
	v_fmac_f32_e32 v136, v137, v134
	v_fma_f32 v133, -v133, v136, v135
	v_div_fmas_f32 v133, v133, v134, v136
	v_div_fixup_f32 v32, v133, v32, v91
	v_bfe_u32 v133, v32, 16, 1
	v_add3_u32 v32, v32, v133, s1
	global_store_short_d16_hi v[152:153], v32, off offset:64
	v_mul_f32_e32 v32, 0xbfb8aa3b, v75
	v_exp_f32_e32 v32, v32
	s_nop 0
	v_add_f32_e32 v32, 1.0, v32
	v_div_scale_f32 v133, s[2:3], v32, v32, v75
	v_rcp_f32_e32 v134, v133
	s_nop 0
	v_fma_f32 v135, -v133, v134, 1.0
	v_fmac_f32_e32 v134, v135, v134
	v_div_scale_f32 v135, vcc, v75, v32, v75
	v_mul_f32_e32 v136, v135, v134
	v_fma_f32 v137, -v133, v136, v135
	v_fmac_f32_e32 v136, v137, v134
	v_fma_f32 v133, -v133, v136, v135
	v_div_fmas_f32 v133, v133, v134, v136
	v_div_fixup_f32 v32, v133, v32, v75
	v_bfe_u32 v133, v32, 16, 1
	v_add3_u32 v32, v32, v133, s1
	global_store_short_d16_hi v[152:153], v32, off offset:192
	v_mul_f32_e32 v32, 0xbfb8aa3b, v92
	v_exp_f32_e32 v32, v32
	s_nop 0
	v_add_f32_e32 v32, 1.0, v32
	v_div_scale_f32 v133, s[2:3], v32, v32, v92
	v_rcp_f32_e32 v134, v133
	s_nop 0
	v_fma_f32 v135, -v133, v134, 1.0
	v_fmac_f32_e32 v134, v135, v134
	v_div_scale_f32 v135, vcc, v92, v32, v92
	v_mul_f32_e32 v136, v135, v134
	v_fma_f32 v137, -v133, v136, v135
	v_fmac_f32_e32 v136, v137, v134
	v_fma_f32 v133, -v133, v136, v135
	v_div_fmas_f32 v133, v133, v134, v136
	v_div_fixup_f32 v32, v133, v32, v92
	v_bfe_u32 v133, v32, 16, 1
	v_add3_u32 v32, v32, v133, s1
	global_store_short_d16_hi v[154:155], v32, off offset:64
	v_mul_f32_e32 v32, 0xbfb8aa3b, v76
	v_exp_f32_e32 v32, v32
	s_nop 0
	v_add_f32_e32 v32, 1.0, v32
	v_div_scale_f32 v133, s[2:3], v32, v32, v76
	v_rcp_f32_e32 v134, v133
	s_nop 0
	v_fma_f32 v135, -v133, v134, 1.0
	v_fmac_f32_e32 v134, v135, v134
	v_div_scale_f32 v135, vcc, v76, v32, v76
	v_mul_f32_e32 v136, v135, v134
	v_fma_f32 v137, -v133, v136, v135
	v_fmac_f32_e32 v136, v137, v134
	v_fma_f32 v133, -v133, v136, v135
	v_div_fmas_f32 v133, v133, v134, v136
	v_div_fixup_f32 v32, v133, v32, v76
	v_bfe_u32 v133, v32, 16, 1
	v_add3_u32 v32, v32, v133, s1
	global_store_short_d16_hi v[154:155], v32, off offset:192
	v_mul_f32_e32 v32, 0xbfb8aa3b, v93
	v_exp_f32_e32 v32, v32
	s_nop 0
	v_add_f32_e32 v32, 1.0, v32
	v_div_scale_f32 v133, s[2:3], v32, v32, v93
	v_rcp_f32_e32 v134, v133
	s_nop 0
	v_fma_f32 v135, -v133, v134, 1.0
	v_fmac_f32_e32 v134, v135, v134
	v_div_scale_f32 v135, vcc, v93, v32, v93
	v_mul_f32_e32 v136, v135, v134
	v_fma_f32 v137, -v133, v136, v135
	v_fmac_f32_e32 v136, v137, v134
	v_fma_f32 v133, -v133, v136, v135
	v_div_fmas_f32 v133, v133, v134, v136
	v_div_fixup_f32 v32, v133, v32, v93
	v_bfe_u32 v133, v32, 16, 1
	v_add3_u32 v32, v32, v133, s1
	global_store_short_d16_hi v[156:157], v32, off offset:64
	v_mul_f32_e32 v32, 0xbfb8aa3b, v77
	v_exp_f32_e32 v32, v32
	s_nop 0
	v_add_f32_e32 v32, 1.0, v32
	v_div_scale_f32 v133, s[2:3], v32, v32, v77
	v_rcp_f32_e32 v134, v133
	s_nop 0
	v_fma_f32 v135, -v133, v134, 1.0
	v_fmac_f32_e32 v134, v135, v134
	v_div_scale_f32 v135, vcc, v77, v32, v77
	v_mul_f32_e32 v136, v135, v134
	v_fma_f32 v137, -v133, v136, v135
	v_fmac_f32_e32 v136, v137, v134
	v_fma_f32 v133, -v133, v136, v135
	v_div_fmas_f32 v133, v133, v134, v136
	v_div_fixup_f32 v32, v133, v32, v77
	v_bfe_u32 v133, v32, 16, 1
	v_add3_u32 v32, v32, v133, s1
	global_store_short_d16_hi v[156:157], v32, off offset:192
	v_mul_f32_e32 v32, 0xbfb8aa3b, v94
	v_exp_f32_e32 v32, v32
	s_nop 0
	v_add_f32_e32 v32, 1.0, v32
	v_div_scale_f32 v133, s[2:3], v32, v32, v94
	v_rcp_f32_e32 v134, v133
	s_nop 0
	v_fma_f32 v135, -v133, v134, 1.0
	v_fmac_f32_e32 v134, v135, v134
	v_div_scale_f32 v135, vcc, v94, v32, v94
	v_mul_f32_e32 v136, v135, v134
	v_fma_f32 v137, -v133, v136, v135
	v_fmac_f32_e32 v136, v137, v134
	v_fma_f32 v133, -v133, v136, v135
	v_div_fmas_f32 v133, v133, v134, v136
	v_div_fixup_f32 v32, v133, v32, v94
	v_bfe_u32 v133, v32, 16, 1
	v_add3_u32 v32, v32, v133, s1
	global_store_short_d16_hi v[158:159], v32, off offset:64
	v_mul_f32_e32 v32, 0xbfb8aa3b, v78
	v_exp_f32_e32 v32, v32
	s_nop 0
	v_add_f32_e32 v32, 1.0, v32
	v_div_scale_f32 v133, s[2:3], v32, v32, v78
	v_rcp_f32_e32 v134, v133
	s_nop 0
	v_fma_f32 v135, -v133, v134, 1.0
	v_fmac_f32_e32 v134, v135, v134
	v_div_scale_f32 v135, vcc, v78, v32, v78
	v_mul_f32_e32 v136, v135, v134
	v_fma_f32 v137, -v133, v136, v135
	v_fmac_f32_e32 v136, v137, v134
	v_fma_f32 v133, -v133, v136, v135
	v_div_fmas_f32 v133, v133, v134, v136
	v_div_fixup_f32 v32, v133, v32, v78
	v_bfe_u32 v133, v32, 16, 1
	v_add3_u32 v32, v32, v133, s1
	global_store_short_d16_hi v[158:159], v32, off offset:192
	v_mul_f32_e32 v32, 0xbfb8aa3b, v95
	v_exp_f32_e32 v32, v32
	s_nop 0
	v_add_f32_e32 v32, 1.0, v32
	v_div_scale_f32 v133, s[2:3], v32, v32, v95
	v_rcp_f32_e32 v134, v133
	s_nop 0
	v_fma_f32 v135, -v133, v134, 1.0
	v_fmac_f32_e32 v134, v135, v134
	v_div_scale_f32 v135, vcc, v95, v32, v95
	v_mul_f32_e32 v136, v135, v134
	v_fma_f32 v137, -v133, v136, v135
	v_fmac_f32_e32 v136, v137, v134
	v_fma_f32 v133, -v133, v136, v135
	v_div_fmas_f32 v133, v133, v134, v136
	v_div_fixup_f32 v32, v133, v32, v95
	v_bfe_u32 v133, v32, 16, 1
	v_add3_u32 v32, v32, v133, s1
	global_store_short_d16_hi v[160:161], v32, off offset:64
	v_mul_f32_e32 v32, 0xbfb8aa3b, v79
	v_exp_f32_e32 v32, v32
	s_nop 0
	v_add_f32_e32 v32, 1.0, v32
	v_div_scale_f32 v133, s[2:3], v32, v32, v79
	v_rcp_f32_e32 v134, v133
	s_nop 0
	v_fma_f32 v135, -v133, v134, 1.0
	v_fmac_f32_e32 v134, v135, v134
	v_div_scale_f32 v135, vcc, v79, v32, v79
	v_mul_f32_e32 v136, v135, v134
	v_fma_f32 v137, -v133, v136, v135
	v_fmac_f32_e32 v136, v137, v134
	v_fma_f32 v133, -v133, v136, v135
	v_div_fmas_f32 v133, v133, v134, v136
	v_div_fixup_f32 v32, v133, v32, v79
	v_bfe_u32 v133, v32, 16, 1
	v_add3_u32 v32, v32, v133, s1
	global_store_short_d16_hi v[160:161], v32, off offset:192
	v_mul_f32_e32 v32, 0xbfb8aa3b, v96
	v_exp_f32_e32 v32, v32
	s_nop 0
	v_add_f32_e32 v32, 1.0, v32
	v_div_scale_f32 v133, s[2:3], v32, v32, v96
	v_rcp_f32_e32 v134, v133
	s_nop 0
	v_fma_f32 v135, -v133, v134, 1.0
	v_fmac_f32_e32 v134, v135, v134
	v_div_scale_f32 v135, vcc, v96, v32, v96
	v_mul_f32_e32 v136, v135, v134
	v_fma_f32 v137, -v133, v136, v135
	v_fmac_f32_e32 v136, v137, v134
	v_fma_f32 v133, -v133, v136, v135
	v_div_fmas_f32 v133, v133, v134, v136
	v_div_fixup_f32 v32, v133, v32, v96
	v_bfe_u32 v133, v32, 16, 1
	v_add3_u32 v32, v32, v133, s1
	global_store_short_d16_hi v[162:163], v32, off offset:64
	v_mul_f32_e32 v32, 0xbfb8aa3b, v80
	v_exp_f32_e32 v32, v32
	s_nop 0
	v_add_f32_e32 v32, 1.0, v32
	v_div_scale_f32 v133, s[2:3], v32, v32, v80
	v_rcp_f32_e32 v134, v133
	s_nop 0
	v_fma_f32 v135, -v133, v134, 1.0
	v_fmac_f32_e32 v134, v135, v134
	v_div_scale_f32 v135, vcc, v80, v32, v80
	v_mul_f32_e32 v136, v135, v134
	v_fma_f32 v137, -v133, v136, v135
	v_fmac_f32_e32 v136, v137, v134
	v_fma_f32 v133, -v133, v136, v135
	v_div_fmas_f32 v133, v133, v134, v136
	v_div_fixup_f32 v32, v133, v32, v80
	v_bfe_u32 v133, v32, 16, 1
	v_add3_u32 v32, v32, v133, s1
	global_store_short_d16_hi v[162:163], v32, off offset:192
	v_mul_f32_e32 v32, 0xbfb8aa3b, v97
	v_exp_f32_e32 v32, v32
	s_nop 0
	v_add_f32_e32 v32, 1.0, v32
	v_div_scale_f32 v133, s[2:3], v32, v32, v97
	v_rcp_f32_e32 v134, v133
	s_nop 0
	v_fma_f32 v135, -v133, v134, 1.0
	v_fmac_f32_e32 v134, v135, v134
	v_div_scale_f32 v135, vcc, v97, v32, v97
	v_mul_f32_e32 v136, v135, v134
	v_fma_f32 v137, -v133, v136, v135
	v_fmac_f32_e32 v136, v137, v134
	v_fma_f32 v133, -v133, v136, v135
	v_div_fmas_f32 v133, v133, v134, v136
	v_div_fixup_f32 v32, v133, v32, v97
	v_bfe_u32 v133, v32, 16, 1
	v_add3_u32 v32, v32, v133, s1
	global_store_short_d16_hi v[164:165], v32, off offset:64
	v_mul_f32_e32 v32, 0xbfb8aa3b, v81
	v_exp_f32_e32 v32, v32
	s_nop 0
	v_add_f32_e32 v32, 1.0, v32
	v_div_scale_f32 v133, s[2:3], v32, v32, v81
	v_rcp_f32_e32 v134, v133
	s_nop 0
	v_fma_f32 v135, -v133, v134, 1.0
	v_fmac_f32_e32 v134, v135, v134
	v_div_scale_f32 v135, vcc, v81, v32, v81
	v_mul_f32_e32 v136, v135, v134
	v_fma_f32 v137, -v133, v136, v135
	v_fmac_f32_e32 v136, v137, v134
	v_fma_f32 v133, -v133, v136, v135
	v_div_fmas_f32 v133, v133, v134, v136
	v_div_fixup_f32 v32, v133, v32, v81
	v_bfe_u32 v133, v32, 16, 1
	v_add3_u32 v32, v32, v133, s1
	global_store_short_d16_hi v[164:165], v32, off offset:192
	v_mul_f32_e32 v32, 0xbfb8aa3b, v50
	v_exp_f32_e32 v32, v32
	v_or_b32_e32 v134, 32, v132
	v_ashrrev_i32_e32 v135, 31, v134
	v_lshlrev_b64 v[134:135], 12, v[134:135]
	v_add_f32_e32 v32, 1.0, v32
	v_div_scale_f32 v133, s[2:3], v32, v32, v50
	v_rcp_f32_e32 v136, v133
	v_lshl_add_u64 v[134:135], v[130:131], 0, v[134:135]
	v_fma_f32 v137, -v133, v136, 1.0
	v_fmac_f32_e32 v136, v137, v136
	v_div_scale_f32 v137, vcc, v50, v32, v50
	v_mul_f32_e32 v138, v137, v136
	v_fma_f32 v139, -v133, v138, v137
	v_fmac_f32_e32 v138, v139, v136
	v_fma_f32 v133, -v133, v138, v137
	v_div_fmas_f32 v133, v133, v136, v138
	v_div_fixup_f32 v32, v133, v32, v50
	v_bfe_u32 v133, v32, 16, 1
	v_add3_u32 v32, v32, v133, s1
	global_store_short_d16_hi v[134:135], v32, off
	v_mul_f32_e32 v32, 0xbfb8aa3b, v34
	v_exp_f32_e32 v32, v32
	s_nop 0
	v_add_f32_e32 v32, 1.0, v32
	v_div_scale_f32 v133, s[2:3], v32, v32, v34
	v_rcp_f32_e32 v136, v133
	s_nop 0
	v_fma_f32 v137, -v133, v136, 1.0
	v_fmac_f32_e32 v136, v137, v136
	v_div_scale_f32 v137, vcc, v34, v32, v34
	v_mul_f32_e32 v138, v137, v136
	v_fma_f32 v139, -v133, v138, v137
	v_fmac_f32_e32 v138, v139, v136
	v_fma_f32 v133, -v133, v138, v137
	v_div_fmas_f32 v133, v133, v136, v138
	v_div_fixup_f32 v32, v133, v32, v34
	v_bfe_u32 v133, v32, 16, 1
	v_add3_u32 v32, v32, v133, s1
	global_store_short_d16_hi v[134:135], v32, off offset:128
	v_mul_f32_e32 v32, 0xbfb8aa3b, v51
	v_exp_f32_e32 v32, v32
	v_or_b32_e32 v136, 33, v132
	v_ashrrev_i32_e32 v137, 31, v136
	v_lshlrev_b64 v[136:137], 12, v[136:137]
	v_add_f32_e32 v32, 1.0, v32
	v_div_scale_f32 v133, s[2:3], v32, v32, v51
	v_rcp_f32_e32 v138, v133
	v_lshl_add_u64 v[136:137], v[130:131], 0, v[136:137]
	v_fma_f32 v139, -v133, v138, 1.0
	v_fmac_f32_e32 v138, v139, v138
	v_div_scale_f32 v139, vcc, v51, v32, v51
	v_mul_f32_e32 v140, v139, v138
	v_fma_f32 v141, -v133, v140, v139
	v_fmac_f32_e32 v140, v141, v138
	v_fma_f32 v133, -v133, v140, v139
	v_div_fmas_f32 v133, v133, v138, v140
	v_div_fixup_f32 v32, v133, v32, v51
	v_bfe_u32 v133, v32, 16, 1
	v_add3_u32 v32, v32, v133, s1
	global_store_short_d16_hi v[136:137], v32, off
	v_mul_f32_e32 v32, 0xbfb8aa3b, v35
	v_exp_f32_e32 v32, v32
	s_nop 0
	v_add_f32_e32 v32, 1.0, v32
	v_div_scale_f32 v133, s[2:3], v32, v32, v35
	v_rcp_f32_e32 v138, v133
	s_nop 0
	v_fma_f32 v139, -v133, v138, 1.0
	v_fmac_f32_e32 v138, v139, v138
	v_div_scale_f32 v139, vcc, v35, v32, v35
	v_mul_f32_e32 v140, v139, v138
	v_fma_f32 v141, -v133, v140, v139
	v_fmac_f32_e32 v140, v141, v138
	v_fma_f32 v133, -v133, v140, v139
	v_div_fmas_f32 v133, v133, v138, v140
	v_div_fixup_f32 v32, v133, v32, v35
	v_bfe_u32 v133, v32, 16, 1
	v_add3_u32 v32, v32, v133, s1
	global_store_short_d16_hi v[136:137], v32, off offset:128
	v_mul_f32_e32 v32, 0xbfb8aa3b, v52
	v_exp_f32_e32 v32, v32
	v_or_b32_e32 v138, 34, v132
	v_ashrrev_i32_e32 v139, 31, v138
	v_lshlrev_b64 v[138:139], 12, v[138:139]
	v_add_f32_e32 v32, 1.0, v32
	v_div_scale_f32 v133, s[2:3], v32, v32, v52
	v_rcp_f32_e32 v140, v133
	v_lshl_add_u64 v[138:139], v[130:131], 0, v[138:139]
	v_fma_f32 v141, -v133, v140, 1.0
	v_fmac_f32_e32 v140, v141, v140
	v_div_scale_f32 v141, vcc, v52, v32, v52
	v_mul_f32_e32 v142, v141, v140
	v_fma_f32 v143, -v133, v142, v141
	v_fmac_f32_e32 v142, v143, v140
	v_fma_f32 v133, -v133, v142, v141
	v_div_fmas_f32 v133, v133, v140, v142
	v_div_fixup_f32 v32, v133, v32, v52
	v_bfe_u32 v133, v32, 16, 1
	v_add3_u32 v32, v32, v133, s1
	global_store_short_d16_hi v[138:139], v32, off
	v_mul_f32_e32 v32, 0xbfb8aa3b, v36
	v_exp_f32_e32 v32, v32
	s_nop 0
	v_add_f32_e32 v32, 1.0, v32
	v_div_scale_f32 v133, s[2:3], v32, v32, v36
	v_rcp_f32_e32 v140, v133
	s_nop 0
	v_fma_f32 v141, -v133, v140, 1.0
	v_fmac_f32_e32 v140, v141, v140
	v_div_scale_f32 v141, vcc, v36, v32, v36
	v_mul_f32_e32 v142, v141, v140
	v_fma_f32 v143, -v133, v142, v141
	v_fmac_f32_e32 v142, v143, v140
	v_fma_f32 v133, -v133, v142, v141
	v_div_fmas_f32 v133, v133, v140, v142
	v_div_fixup_f32 v32, v133, v32, v36
	v_bfe_u32 v133, v32, 16, 1
	v_add3_u32 v32, v32, v133, s1
	global_store_short_d16_hi v[138:139], v32, off offset:128
	v_mul_f32_e32 v32, 0xbfb8aa3b, v53
	v_exp_f32_e32 v32, v32
	v_or_b32_e32 v140, 35, v132
	v_ashrrev_i32_e32 v141, 31, v140
	v_lshlrev_b64 v[140:141], 12, v[140:141]
	v_add_f32_e32 v32, 1.0, v32
	v_div_scale_f32 v133, s[2:3], v32, v32, v53
	v_rcp_f32_e32 v142, v133
	v_lshl_add_u64 v[140:141], v[130:131], 0, v[140:141]
	v_fma_f32 v143, -v133, v142, 1.0
	v_fmac_f32_e32 v142, v143, v142
	v_div_scale_f32 v143, vcc, v53, v32, v53
	v_mul_f32_e32 v144, v143, v142
	v_fma_f32 v145, -v133, v144, v143
	v_fmac_f32_e32 v144, v145, v142
	v_fma_f32 v133, -v133, v144, v143
	v_div_fmas_f32 v133, v133, v142, v144
	v_div_fixup_f32 v32, v133, v32, v53
	v_bfe_u32 v133, v32, 16, 1
	v_add3_u32 v32, v32, v133, s1
	global_store_short_d16_hi v[140:141], v32, off
	v_mul_f32_e32 v32, 0xbfb8aa3b, v37
	v_exp_f32_e32 v32, v32
	s_nop 0
	v_add_f32_e32 v32, 1.0, v32
	v_div_scale_f32 v133, s[2:3], v32, v32, v37
	v_rcp_f32_e32 v142, v133
	s_nop 0
	v_fma_f32 v143, -v133, v142, 1.0
	v_fmac_f32_e32 v142, v143, v142
	v_div_scale_f32 v143, vcc, v37, v32, v37
	v_mul_f32_e32 v144, v143, v142
	v_fma_f32 v145, -v133, v144, v143
	v_fmac_f32_e32 v144, v145, v142
	v_fma_f32 v133, -v133, v144, v143
	v_div_fmas_f32 v133, v133, v142, v144
	v_div_fixup_f32 v32, v133, v32, v37
	v_bfe_u32 v133, v32, 16, 1
	v_add3_u32 v32, v32, v133, s1
	global_store_short_d16_hi v[140:141], v32, off offset:128
	v_mul_f32_e32 v32, 0xbfb8aa3b, v54
	v_exp_f32_e32 v32, v32
	v_or_b32_e32 v142, 40, v132
	v_ashrrev_i32_e32 v143, 31, v142
	v_lshlrev_b64 v[142:143], 12, v[142:143]
	v_add_f32_e32 v32, 1.0, v32
	v_div_scale_f32 v133, s[2:3], v32, v32, v54
	v_rcp_f32_e32 v144, v133
	v_lshl_add_u64 v[142:143], v[130:131], 0, v[142:143]
	v_fma_f32 v145, -v133, v144, 1.0
	v_fmac_f32_e32 v144, v145, v144
	v_div_scale_f32 v145, vcc, v54, v32, v54
	v_mul_f32_e32 v146, v145, v144
	v_fma_f32 v147, -v133, v146, v145
	v_fmac_f32_e32 v146, v147, v144
	v_fma_f32 v133, -v133, v146, v145
	v_div_fmas_f32 v133, v133, v144, v146
	v_div_fixup_f32 v32, v133, v32, v54
	v_bfe_u32 v133, v32, 16, 1
	v_add3_u32 v32, v32, v133, s1
	global_store_short_d16_hi v[142:143], v32, off
	v_mul_f32_e32 v32, 0xbfb8aa3b, v38
	v_exp_f32_e32 v32, v32
	s_nop 0
	v_add_f32_e32 v32, 1.0, v32
	v_div_scale_f32 v133, s[2:3], v32, v32, v38
	v_rcp_f32_e32 v144, v133
	s_nop 0
	v_fma_f32 v145, -v133, v144, 1.0
	v_fmac_f32_e32 v144, v145, v144
	v_div_scale_f32 v145, vcc, v38, v32, v38
	v_mul_f32_e32 v146, v145, v144
	v_fma_f32 v147, -v133, v146, v145
	v_fmac_f32_e32 v146, v147, v144
	v_fma_f32 v133, -v133, v146, v145
	v_div_fmas_f32 v133, v133, v144, v146
	v_div_fixup_f32 v32, v133, v32, v38
	v_bfe_u32 v133, v32, 16, 1
	v_add3_u32 v32, v32, v133, s1
	global_store_short_d16_hi v[142:143], v32, off offset:128
	v_mul_f32_e32 v32, 0xbfb8aa3b, v55
	v_exp_f32_e32 v32, v32
	v_or_b32_e32 v144, 41, v132
	v_ashrrev_i32_e32 v145, 31, v144
	v_lshlrev_b64 v[144:145], 12, v[144:145]
	v_add_f32_e32 v32, 1.0, v32
	v_div_scale_f32 v133, s[2:3], v32, v32, v55
	v_rcp_f32_e32 v146, v133
	v_lshl_add_u64 v[144:145], v[130:131], 0, v[144:145]
	v_fma_f32 v147, -v133, v146, 1.0
	v_fmac_f32_e32 v146, v147, v146
	v_div_scale_f32 v147, vcc, v55, v32, v55
	v_mul_f32_e32 v148, v147, v146
	v_fma_f32 v149, -v133, v148, v147
	v_fmac_f32_e32 v148, v149, v146
	v_fma_f32 v133, -v133, v148, v147
	v_div_fmas_f32 v133, v133, v146, v148
	v_div_fixup_f32 v32, v133, v32, v55
	v_bfe_u32 v133, v32, 16, 1
	v_add3_u32 v32, v32, v133, s1
	global_store_short_d16_hi v[144:145], v32, off
	v_mul_f32_e32 v32, 0xbfb8aa3b, v39
	v_exp_f32_e32 v32, v32
	s_nop 0
	v_add_f32_e32 v32, 1.0, v32
	v_div_scale_f32 v133, s[2:3], v32, v32, v39
	v_rcp_f32_e32 v146, v133
	s_nop 0
	v_fma_f32 v147, -v133, v146, 1.0
	v_fmac_f32_e32 v146, v147, v146
	v_div_scale_f32 v147, vcc, v39, v32, v39
	v_mul_f32_e32 v148, v147, v146
	v_fma_f32 v149, -v133, v148, v147
	v_fmac_f32_e32 v148, v149, v146
	v_fma_f32 v133, -v133, v148, v147
	v_div_fmas_f32 v133, v133, v146, v148
	v_div_fixup_f32 v32, v133, v32, v39
	v_bfe_u32 v133, v32, 16, 1
	v_add3_u32 v32, v32, v133, s1
	global_store_short_d16_hi v[144:145], v32, off offset:128
	v_mul_f32_e32 v32, 0xbfb8aa3b, v56
	v_exp_f32_e32 v32, v32
	v_or_b32_e32 v146, 42, v132
	v_ashrrev_i32_e32 v147, 31, v146
	v_lshlrev_b64 v[146:147], 12, v[146:147]
	v_add_f32_e32 v32, 1.0, v32
	v_div_scale_f32 v133, s[2:3], v32, v32, v56
	v_rcp_f32_e32 v148, v133
	v_lshl_add_u64 v[146:147], v[130:131], 0, v[146:147]
	v_fma_f32 v149, -v133, v148, 1.0
	v_fmac_f32_e32 v148, v149, v148
	v_div_scale_f32 v149, vcc, v56, v32, v56
	v_mul_f32_e32 v150, v149, v148
	v_fma_f32 v151, -v133, v150, v149
	v_fmac_f32_e32 v150, v151, v148
	v_fma_f32 v133, -v133, v150, v149
	v_div_fmas_f32 v133, v133, v148, v150
	v_div_fixup_f32 v32, v133, v32, v56
	v_bfe_u32 v133, v32, 16, 1
	v_add3_u32 v32, v32, v133, s1
	global_store_short_d16_hi v[146:147], v32, off
	v_mul_f32_e32 v32, 0xbfb8aa3b, v40
	v_exp_f32_e32 v32, v32
	s_nop 0
	v_add_f32_e32 v32, 1.0, v32
	v_div_scale_f32 v133, s[2:3], v32, v32, v40
	v_rcp_f32_e32 v148, v133
	s_nop 0
	v_fma_f32 v149, -v133, v148, 1.0
	v_fmac_f32_e32 v148, v149, v148
	v_div_scale_f32 v149, vcc, v40, v32, v40
	v_mul_f32_e32 v150, v149, v148
	v_fma_f32 v151, -v133, v150, v149
	v_fmac_f32_e32 v150, v151, v148
	v_fma_f32 v133, -v133, v150, v149
	v_div_fmas_f32 v133, v133, v148, v150
	v_div_fixup_f32 v32, v133, v32, v40
	v_bfe_u32 v133, v32, 16, 1
	v_add3_u32 v32, v32, v133, s1
	global_store_short_d16_hi v[146:147], v32, off offset:128
	v_mul_f32_e32 v32, 0xbfb8aa3b, v57
	v_exp_f32_e32 v32, v32
	v_or_b32_e32 v148, 43, v132
	v_ashrrev_i32_e32 v149, 31, v148
	v_lshlrev_b64 v[148:149], 12, v[148:149]
	v_add_f32_e32 v32, 1.0, v32
	v_div_scale_f32 v133, s[2:3], v32, v32, v57
	v_rcp_f32_e32 v150, v133
	v_lshl_add_u64 v[148:149], v[130:131], 0, v[148:149]
	v_fma_f32 v151, -v133, v150, 1.0
	v_fmac_f32_e32 v150, v151, v150
	v_div_scale_f32 v151, vcc, v57, v32, v57
	v_mul_f32_e32 v152, v151, v150
	v_fma_f32 v153, -v133, v152, v151
	v_fmac_f32_e32 v152, v153, v150
	v_fma_f32 v133, -v133, v152, v151
	v_div_fmas_f32 v133, v133, v150, v152
	v_div_fixup_f32 v32, v133, v32, v57
	v_bfe_u32 v133, v32, 16, 1
	v_add3_u32 v32, v32, v133, s1
	global_store_short_d16_hi v[148:149], v32, off
	v_mul_f32_e32 v32, 0xbfb8aa3b, v41
	v_exp_f32_e32 v32, v32
	s_nop 0
	v_add_f32_e32 v32, 1.0, v32
	v_div_scale_f32 v133, s[2:3], v32, v32, v41
	v_rcp_f32_e32 v150, v133
	s_nop 0
	v_fma_f32 v151, -v133, v150, 1.0
	v_fmac_f32_e32 v150, v151, v150
	v_div_scale_f32 v151, vcc, v41, v32, v41
	v_mul_f32_e32 v152, v151, v150
	v_fma_f32 v153, -v133, v152, v151
	v_fmac_f32_e32 v152, v153, v150
	v_fma_f32 v133, -v133, v152, v151
	v_div_fmas_f32 v133, v133, v150, v152
	v_div_fixup_f32 v32, v133, v32, v41
	v_bfe_u32 v133, v32, 16, 1
	v_add3_u32 v32, v32, v133, s1
	global_store_short_d16_hi v[148:149], v32, off offset:128
	v_mul_f32_e32 v32, 0xbfb8aa3b, v58
	v_exp_f32_e32 v32, v32
	v_or_b32_e32 v150, 48, v132
	v_ashrrev_i32_e32 v151, 31, v150
	v_lshlrev_b64 v[150:151], 12, v[150:151]
	v_add_f32_e32 v32, 1.0, v32
	v_div_scale_f32 v133, s[2:3], v32, v32, v58
	v_rcp_f32_e32 v152, v133
	v_lshl_add_u64 v[150:151], v[130:131], 0, v[150:151]
	v_fma_f32 v153, -v133, v152, 1.0
	v_fmac_f32_e32 v152, v153, v152
	v_div_scale_f32 v153, vcc, v58, v32, v58
	v_mul_f32_e32 v154, v153, v152
	v_fma_f32 v155, -v133, v154, v153
	v_fmac_f32_e32 v154, v155, v152
	v_fma_f32 v133, -v133, v154, v153
	v_div_fmas_f32 v133, v133, v152, v154
	v_div_fixup_f32 v32, v133, v32, v58
	v_bfe_u32 v133, v32, 16, 1
	v_add3_u32 v32, v32, v133, s1
	global_store_short_d16_hi v[150:151], v32, off
	v_mul_f32_e32 v32, 0xbfb8aa3b, v42
	v_exp_f32_e32 v32, v32
	s_nop 0
	v_add_f32_e32 v32, 1.0, v32
	v_div_scale_f32 v133, s[2:3], v32, v32, v42
	v_rcp_f32_e32 v152, v133
	s_nop 0
	v_fma_f32 v153, -v133, v152, 1.0
	v_fmac_f32_e32 v152, v153, v152
	v_div_scale_f32 v153, vcc, v42, v32, v42
	v_mul_f32_e32 v154, v153, v152
	v_fma_f32 v155, -v133, v154, v153
	v_fmac_f32_e32 v154, v155, v152
	v_fma_f32 v133, -v133, v154, v153
	v_div_fmas_f32 v133, v133, v152, v154
	v_div_fixup_f32 v32, v133, v32, v42
	v_bfe_u32 v133, v32, 16, 1
	v_add3_u32 v32, v32, v133, s1
	global_store_short_d16_hi v[150:151], v32, off offset:128
	v_mul_f32_e32 v32, 0xbfb8aa3b, v59
	v_exp_f32_e32 v32, v32
	v_or_b32_e32 v152, 49, v132
	v_ashrrev_i32_e32 v153, 31, v152
	v_lshlrev_b64 v[152:153], 12, v[152:153]
	v_add_f32_e32 v32, 1.0, v32
	v_div_scale_f32 v133, s[2:3], v32, v32, v59
	v_rcp_f32_e32 v154, v133
	v_lshl_add_u64 v[152:153], v[130:131], 0, v[152:153]
	v_fma_f32 v155, -v133, v154, 1.0
	v_fmac_f32_e32 v154, v155, v154
	v_div_scale_f32 v155, vcc, v59, v32, v59
	v_mul_f32_e32 v156, v155, v154
	v_fma_f32 v157, -v133, v156, v155
	v_fmac_f32_e32 v156, v157, v154
	v_fma_f32 v133, -v133, v156, v155
	v_div_fmas_f32 v133, v133, v154, v156
	v_div_fixup_f32 v32, v133, v32, v59
	v_bfe_u32 v133, v32, 16, 1
	v_add3_u32 v32, v32, v133, s1
	global_store_short_d16_hi v[152:153], v32, off
	v_mul_f32_e32 v32, 0xbfb8aa3b, v43
	v_exp_f32_e32 v32, v32
	s_nop 0
	v_add_f32_e32 v32, 1.0, v32
	v_div_scale_f32 v133, s[2:3], v32, v32, v43
	v_rcp_f32_e32 v154, v133
	s_nop 0
	v_fma_f32 v155, -v133, v154, 1.0
	v_fmac_f32_e32 v154, v155, v154
	v_div_scale_f32 v155, vcc, v43, v32, v43
	v_mul_f32_e32 v156, v155, v154
	v_fma_f32 v157, -v133, v156, v155
	v_fmac_f32_e32 v156, v157, v154
	v_fma_f32 v133, -v133, v156, v155
	v_div_fmas_f32 v133, v133, v154, v156
	v_div_fixup_f32 v32, v133, v32, v43
	v_bfe_u32 v133, v32, 16, 1
	v_add3_u32 v32, v32, v133, s1
	global_store_short_d16_hi v[152:153], v32, off offset:128
	v_mul_f32_e32 v32, 0xbfb8aa3b, v60
	v_exp_f32_e32 v32, v32
	v_or_b32_e32 v154, 50, v132
	v_ashrrev_i32_e32 v155, 31, v154
	v_lshlrev_b64 v[154:155], 12, v[154:155]
	v_add_f32_e32 v32, 1.0, v32
	v_div_scale_f32 v133, s[2:3], v32, v32, v60
	v_rcp_f32_e32 v156, v133
	v_lshl_add_u64 v[154:155], v[130:131], 0, v[154:155]
	v_fma_f32 v157, -v133, v156, 1.0
	v_fmac_f32_e32 v156, v157, v156
	v_div_scale_f32 v157, vcc, v60, v32, v60
	v_mul_f32_e32 v158, v157, v156
	v_fma_f32 v159, -v133, v158, v157
	v_fmac_f32_e32 v158, v159, v156
	v_fma_f32 v133, -v133, v158, v157
	v_div_fmas_f32 v133, v133, v156, v158
	v_div_fixup_f32 v32, v133, v32, v60
	v_bfe_u32 v133, v32, 16, 1
	v_add3_u32 v32, v32, v133, s1
	global_store_short_d16_hi v[154:155], v32, off
	v_mul_f32_e32 v32, 0xbfb8aa3b, v44
	v_exp_f32_e32 v32, v32
	s_nop 0
	v_add_f32_e32 v32, 1.0, v32
	v_div_scale_f32 v133, s[2:3], v32, v32, v44
	v_rcp_f32_e32 v156, v133
	s_nop 0
	v_fma_f32 v157, -v133, v156, 1.0
	v_fmac_f32_e32 v156, v157, v156
	v_div_scale_f32 v157, vcc, v44, v32, v44
	v_mul_f32_e32 v158, v157, v156
	v_fma_f32 v159, -v133, v158, v157
	v_fmac_f32_e32 v158, v159, v156
	v_fma_f32 v133, -v133, v158, v157
	v_div_fmas_f32 v133, v133, v156, v158
	v_div_fixup_f32 v32, v133, v32, v44
	v_bfe_u32 v133, v32, 16, 1
	v_add3_u32 v32, v32, v133, s1
	global_store_short_d16_hi v[154:155], v32, off offset:128
	v_mul_f32_e32 v32, 0xbfb8aa3b, v61
	v_exp_f32_e32 v32, v32
	v_or_b32_e32 v156, 51, v132
	v_ashrrev_i32_e32 v157, 31, v156
	v_lshlrev_b64 v[156:157], 12, v[156:157]
	v_add_f32_e32 v32, 1.0, v32
	v_div_scale_f32 v133, s[2:3], v32, v32, v61
	v_rcp_f32_e32 v158, v133
	v_lshl_add_u64 v[156:157], v[130:131], 0, v[156:157]
	v_fma_f32 v159, -v133, v158, 1.0
	v_fmac_f32_e32 v158, v159, v158
	v_div_scale_f32 v159, vcc, v61, v32, v61
	v_mul_f32_e32 v160, v159, v158
	v_fma_f32 v161, -v133, v160, v159
	v_fmac_f32_e32 v160, v161, v158
	v_fma_f32 v133, -v133, v160, v159
	v_div_fmas_f32 v133, v133, v158, v160
	v_div_fixup_f32 v32, v133, v32, v61
	v_bfe_u32 v133, v32, 16, 1
	v_add3_u32 v32, v32, v133, s1
	global_store_short_d16_hi v[156:157], v32, off
	v_mul_f32_e32 v32, 0xbfb8aa3b, v45
	v_exp_f32_e32 v32, v32
	s_nop 0
	v_add_f32_e32 v32, 1.0, v32
	v_div_scale_f32 v133, s[2:3], v32, v32, v45
	v_rcp_f32_e32 v158, v133
	s_nop 0
	v_fma_f32 v159, -v133, v158, 1.0
	v_fmac_f32_e32 v158, v159, v158
	v_div_scale_f32 v159, vcc, v45, v32, v45
	v_mul_f32_e32 v160, v159, v158
	v_fma_f32 v161, -v133, v160, v159
	v_fmac_f32_e32 v160, v161, v158
	v_fma_f32 v133, -v133, v160, v159
	v_div_fmas_f32 v133, v133, v158, v160
	v_div_fixup_f32 v32, v133, v32, v45
	v_bfe_u32 v133, v32, 16, 1
	v_add3_u32 v32, v32, v133, s1
	global_store_short_d16_hi v[156:157], v32, off offset:128
	v_mul_f32_e32 v32, 0xbfb8aa3b, v62
	v_exp_f32_e32 v32, v32
	v_or_b32_e32 v158, 56, v132
	v_ashrrev_i32_e32 v159, 31, v158
	v_lshlrev_b64 v[158:159], 12, v[158:159]
	v_add_f32_e32 v32, 1.0, v32
	v_div_scale_f32 v133, s[2:3], v32, v32, v62
	v_rcp_f32_e32 v160, v133
	v_lshl_add_u64 v[158:159], v[130:131], 0, v[158:159]
	v_fma_f32 v161, -v133, v160, 1.0
	v_fmac_f32_e32 v160, v161, v160
	v_div_scale_f32 v161, vcc, v62, v32, v62
	v_mul_f32_e32 v162, v161, v160
	v_fma_f32 v163, -v133, v162, v161
	v_fmac_f32_e32 v162, v163, v160
	v_fma_f32 v133, -v133, v162, v161
	v_div_fmas_f32 v133, v133, v160, v162
	v_div_fixup_f32 v32, v133, v32, v62
	v_bfe_u32 v133, v32, 16, 1
	v_add3_u32 v32, v32, v133, s1
	global_store_short_d16_hi v[158:159], v32, off
	v_mul_f32_e32 v32, 0xbfb8aa3b, v46
	v_exp_f32_e32 v32, v32
	s_nop 0
	v_add_f32_e32 v32, 1.0, v32
	v_div_scale_f32 v133, s[2:3], v32, v32, v46
	v_rcp_f32_e32 v160, v133
	s_nop 0
	v_fma_f32 v161, -v133, v160, 1.0
	v_fmac_f32_e32 v160, v161, v160
	v_div_scale_f32 v161, vcc, v46, v32, v46
	v_mul_f32_e32 v162, v161, v160
	v_fma_f32 v163, -v133, v162, v161
	v_fmac_f32_e32 v162, v163, v160
	v_fma_f32 v133, -v133, v162, v161
	v_div_fmas_f32 v133, v133, v160, v162
	v_div_fixup_f32 v32, v133, v32, v46
	v_bfe_u32 v133, v32, 16, 1
	v_add3_u32 v32, v32, v133, s1
	global_store_short_d16_hi v[158:159], v32, off offset:128
	v_mul_f32_e32 v32, 0xbfb8aa3b, v63
	v_exp_f32_e32 v32, v32
	v_or_b32_e32 v160, 57, v132
	v_ashrrev_i32_e32 v161, 31, v160
	v_lshlrev_b64 v[160:161], 12, v[160:161]
	v_add_f32_e32 v32, 1.0, v32
	v_div_scale_f32 v133, s[2:3], v32, v32, v63
	v_rcp_f32_e32 v162, v133
	v_lshl_add_u64 v[160:161], v[130:131], 0, v[160:161]
	v_fma_f32 v163, -v133, v162, 1.0
	v_fmac_f32_e32 v162, v163, v162
	v_div_scale_f32 v163, vcc, v63, v32, v63
	v_mul_f32_e32 v164, v163, v162
	v_fma_f32 v165, -v133, v164, v163
	v_fmac_f32_e32 v164, v165, v162
	v_fma_f32 v133, -v133, v164, v163
	v_div_fmas_f32 v133, v133, v162, v164
	v_div_fixup_f32 v32, v133, v32, v63
	v_bfe_u32 v133, v32, 16, 1
	v_add3_u32 v32, v32, v133, s1
	global_store_short_d16_hi v[160:161], v32, off
	v_mul_f32_e32 v32, 0xbfb8aa3b, v47
	v_exp_f32_e32 v32, v32
	s_nop 0
	v_add_f32_e32 v32, 1.0, v32
	v_div_scale_f32 v133, s[2:3], v32, v32, v47
	v_rcp_f32_e32 v162, v133
	s_nop 0
	v_fma_f32 v163, -v133, v162, 1.0
	v_fmac_f32_e32 v162, v163, v162
	v_div_scale_f32 v163, vcc, v47, v32, v47
	v_mul_f32_e32 v164, v163, v162
	v_fma_f32 v165, -v133, v164, v163
	v_fmac_f32_e32 v164, v165, v162
	v_fma_f32 v133, -v133, v164, v163
	v_div_fmas_f32 v133, v133, v162, v164
	v_div_fixup_f32 v32, v133, v32, v47
	v_bfe_u32 v133, v32, 16, 1
	v_add3_u32 v32, v32, v133, s1
	global_store_short_d16_hi v[160:161], v32, off offset:128
	v_mul_f32_e32 v32, 0xbfb8aa3b, v64
	v_exp_f32_e32 v32, v32
	v_or_b32_e32 v162, 58, v132
	v_ashrrev_i32_e32 v163, 31, v162
	v_lshlrev_b64 v[162:163], 12, v[162:163]
	v_add_f32_e32 v32, 1.0, v32
	v_div_scale_f32 v133, s[2:3], v32, v32, v64
	v_rcp_f32_e32 v164, v133
	v_lshl_add_u64 v[162:163], v[130:131], 0, v[162:163]
	v_or_b32_e32 v132, 59, v132
	v_fma_f32 v165, -v133, v164, 1.0
	v_fmac_f32_e32 v164, v165, v164
	v_div_scale_f32 v165, vcc, v64, v32, v64
	v_mul_f32_e32 v166, v165, v164
	v_fma_f32 v167, -v133, v166, v165
	v_fmac_f32_e32 v166, v167, v164
	v_fma_f32 v133, -v133, v166, v165
	v_div_fmas_f32 v133, v133, v164, v166
	v_div_fixup_f32 v32, v133, v32, v64
	v_bfe_u32 v133, v32, 16, 1
	v_add3_u32 v32, v32, v133, s1
	global_store_short_d16_hi v[162:163], v32, off
	v_mul_f32_e32 v32, 0xbfb8aa3b, v48
	v_exp_f32_e32 v32, v32
	s_nop 0
	v_add_f32_e32 v32, 1.0, v32
	v_div_scale_f32 v133, s[2:3], v32, v32, v48
	v_rcp_f32_e32 v164, v133
	s_nop 0
	v_fma_f32 v165, -v133, v164, 1.0
	v_fmac_f32_e32 v164, v165, v164
	v_div_scale_f32 v165, vcc, v48, v32, v48
	v_mul_f32_e32 v166, v165, v164
	v_fma_f32 v167, -v133, v166, v165
	v_fmac_f32_e32 v166, v167, v164
	v_fma_f32 v133, -v133, v166, v165
	v_div_fmas_f32 v133, v133, v164, v166
	v_div_fixup_f32 v32, v133, v32, v48
	v_bfe_u32 v133, v32, 16, 1
	v_add3_u32 v32, v32, v133, s1
	global_store_short_d16_hi v[162:163], v32, off offset:128
	v_mul_f32_e32 v32, 0xbfb8aa3b, v65
	v_exp_f32_e32 v32, v32
	v_ashrrev_i32_e32 v133, 31, v132
	v_lshlrev_b64 v[132:133], 12, v[132:133]
	v_lshl_add_u64 v[130:131], v[130:131], 0, v[132:133]
	v_add_f32_e32 v32, 1.0, v32
	v_div_scale_f32 v164, s[2:3], v32, v32, v65
	v_rcp_f32_e32 v165, v164
	s_nop 0
	v_fma_f32 v166, -v164, v165, 1.0
	v_fmac_f32_e32 v165, v166, v165
	v_div_scale_f32 v166, vcc, v65, v32, v65
	v_mul_f32_e32 v167, v166, v165
	v_fma_f32 v168, -v164, v167, v166
	v_fmac_f32_e32 v167, v168, v165
	v_fma_f32 v164, -v164, v167, v166
	v_div_fmas_f32 v164, v164, v165, v167
	v_div_fixup_f32 v32, v164, v32, v65
	v_bfe_u32 v164, v32, 16, 1
	v_add3_u32 v32, v32, v164, s1
	global_store_short_d16_hi v[130:131], v32, off
	v_mul_f32_e32 v32, 0xbfb8aa3b, v49
	v_exp_f32_e32 v32, v32
	s_nop 0
	v_add_f32_e32 v32, 1.0, v32
	v_div_scale_f32 v132, s[2:3], v32, v32, v49
	v_rcp_f32_e32 v133, v132
	s_nop 0
	v_fma_f32 v164, -v132, v133, 1.0
	v_fmac_f32_e32 v133, v164, v133
	v_div_scale_f32 v164, vcc, v49, v32, v49
	v_mul_f32_e32 v165, v164, v133
	v_fma_f32 v166, -v132, v165, v164
	v_fmac_f32_e32 v165, v166, v133
	v_fma_f32 v132, -v132, v165, v164
	v_div_fmas_f32 v132, v132, v133, v165
	v_div_fixup_f32 v32, v132, v32, v49
	v_bfe_u32 v132, v32, 16, 1
	v_add3_u32 v32, v32, v132, s1
	global_store_short_d16_hi v[130:131], v32, off offset:128
	v_mul_f32_e32 v32, 0xbfb8aa3b, v16
	v_exp_f32_e32 v32, v32
	s_nop 0
	v_add_f32_e32 v32, 1.0, v32
	v_div_scale_f32 v132, s[2:3], v32, v32, v16
	v_rcp_f32_e32 v133, v132
	s_nop 0
	v_fma_f32 v164, -v132, v133, 1.0
	v_fmac_f32_e32 v133, v164, v133
	v_div_scale_f32 v164, vcc, v16, v32, v16
	v_mul_f32_e32 v165, v164, v133
	v_fma_f32 v166, -v132, v165, v164
	v_fmac_f32_e32 v165, v166, v133
	v_fma_f32 v132, -v132, v165, v164
	v_div_fmas_f32 v132, v132, v133, v165
	v_div_fixup_f32 v32, v132, v32, v16
	v_bfe_u32 v132, v32, 16, 1
	v_add3_u32 v32, v32, v132, s1
	global_store_short_d16_hi v[134:135], v32, off offset:64
	v_mul_f32_e32 v32, 0xbfb8aa3b, v0
	v_exp_f32_e32 v32, v32
	s_nop 0
	v_add_f32_e32 v32, 1.0, v32
	v_div_scale_f32 v132, s[2:3], v32, v32, v0
	v_rcp_f32_e32 v133, v132
	s_nop 0
	v_fma_f32 v164, -v132, v133, 1.0
	v_fmac_f32_e32 v133, v164, v133
	v_div_scale_f32 v164, vcc, v0, v32, v0
	v_mul_f32_e32 v165, v164, v133
	v_fma_f32 v166, -v132, v165, v164
	v_fmac_f32_e32 v165, v166, v133
	v_fma_f32 v132, -v132, v165, v164
	v_div_fmas_f32 v132, v132, v133, v165
	v_div_fixup_f32 v32, v132, v32, v0
	v_bfe_u32 v132, v32, 16, 1
	v_add3_u32 v32, v32, v132, s1
	global_store_short_d16_hi v[134:135], v32, off offset:192
	v_mul_f32_e32 v32, 0xbfb8aa3b, v17
	v_exp_f32_e32 v32, v32
	s_nop 0
	v_add_f32_e32 v32, 1.0, v32
	v_div_scale_f32 v132, s[2:3], v32, v32, v17
	v_rcp_f32_e32 v133, v132
	s_nop 0
	v_fma_f32 v134, -v132, v133, 1.0
	v_fmac_f32_e32 v133, v134, v133
	v_div_scale_f32 v134, vcc, v17, v32, v17
	v_mul_f32_e32 v135, v134, v133
	v_fma_f32 v164, -v132, v135, v134
	v_fmac_f32_e32 v135, v164, v133
	v_fma_f32 v132, -v132, v135, v134
	v_div_fmas_f32 v132, v132, v133, v135
	v_div_fixup_f32 v32, v132, v32, v17
	v_bfe_u32 v132, v32, 16, 1
	v_add3_u32 v32, v32, v132, s1
	global_store_short_d16_hi v[136:137], v32, off offset:64
	v_mul_f32_e32 v32, 0xbfb8aa3b, v1
	v_exp_f32_e32 v32, v32
	s_nop 0
	v_add_f32_e32 v32, 1.0, v32
	v_div_scale_f32 v132, s[2:3], v32, v32, v1
	v_rcp_f32_e32 v133, v132
	s_nop 0
	v_fma_f32 v134, -v132, v133, 1.0
	v_fmac_f32_e32 v133, v134, v133
	v_div_scale_f32 v134, vcc, v1, v32, v1
	v_mul_f32_e32 v135, v134, v133
	v_fma_f32 v164, -v132, v135, v134
	v_fmac_f32_e32 v135, v164, v133
	v_fma_f32 v132, -v132, v135, v134
	v_div_fmas_f32 v132, v132, v133, v135
	v_div_fixup_f32 v32, v132, v32, v1
	v_bfe_u32 v132, v32, 16, 1
	v_add3_u32 v32, v32, v132, s1
	global_store_short_d16_hi v[136:137], v32, off offset:192
	v_mul_f32_e32 v32, 0xbfb8aa3b, v18
	v_exp_f32_e32 v32, v32
	s_nop 0
	v_add_f32_e32 v32, 1.0, v32
	v_div_scale_f32 v132, s[2:3], v32, v32, v18
	v_rcp_f32_e32 v133, v132
	s_nop 0
	v_fma_f32 v134, -v132, v133, 1.0
	v_fmac_f32_e32 v133, v134, v133
	v_div_scale_f32 v134, vcc, v18, v32, v18
	v_mul_f32_e32 v135, v134, v133
	v_fma_f32 v136, -v132, v135, v134
	v_fmac_f32_e32 v135, v136, v133
	v_fma_f32 v132, -v132, v135, v134
	v_div_fmas_f32 v132, v132, v133, v135
	v_div_fixup_f32 v32, v132, v32, v18
	v_bfe_u32 v132, v32, 16, 1
	v_add3_u32 v32, v32, v132, s1
	global_store_short_d16_hi v[138:139], v32, off offset:64
	v_mul_f32_e32 v32, 0xbfb8aa3b, v2
	v_exp_f32_e32 v32, v32
	s_nop 0
	v_add_f32_e32 v32, 1.0, v32
	v_div_scale_f32 v132, s[2:3], v32, v32, v2
	v_rcp_f32_e32 v133, v132
	s_nop 0
	v_fma_f32 v134, -v132, v133, 1.0
	v_fmac_f32_e32 v133, v134, v133
	v_div_scale_f32 v134, vcc, v2, v32, v2
	v_mul_f32_e32 v135, v134, v133
	v_fma_f32 v136, -v132, v135, v134
	v_fmac_f32_e32 v135, v136, v133
	v_fma_f32 v132, -v132, v135, v134
	v_div_fmas_f32 v132, v132, v133, v135
	v_div_fixup_f32 v32, v132, v32, v2
	v_bfe_u32 v132, v32, 16, 1
	v_add3_u32 v32, v32, v132, s1
	global_store_short_d16_hi v[138:139], v32, off offset:192
	v_mul_f32_e32 v32, 0xbfb8aa3b, v19
	v_exp_f32_e32 v32, v32
	s_nop 0
	v_add_f32_e32 v32, 1.0, v32
	v_div_scale_f32 v132, s[2:3], v32, v32, v19
	v_rcp_f32_e32 v133, v132
	s_nop 0
	v_fma_f32 v134, -v132, v133, 1.0
	v_fmac_f32_e32 v133, v134, v133
	v_div_scale_f32 v134, vcc, v19, v32, v19
	v_mul_f32_e32 v135, v134, v133
	v_fma_f32 v136, -v132, v135, v134
	v_fmac_f32_e32 v135, v136, v133
	v_fma_f32 v132, -v132, v135, v134
	v_div_fmas_f32 v132, v132, v133, v135
	v_div_fixup_f32 v32, v132, v32, v19
	v_bfe_u32 v132, v32, 16, 1
	v_add3_u32 v32, v32, v132, s1
	global_store_short_d16_hi v[140:141], v32, off offset:64
	v_mul_f32_e32 v32, 0xbfb8aa3b, v3
	v_exp_f32_e32 v32, v32
	s_nop 0
	v_add_f32_e32 v32, 1.0, v32
	v_div_scale_f32 v132, s[2:3], v32, v32, v3
	v_rcp_f32_e32 v133, v132
	s_nop 0
	v_fma_f32 v134, -v132, v133, 1.0
	v_fmac_f32_e32 v133, v134, v133
	v_div_scale_f32 v134, vcc, v3, v32, v3
	v_mul_f32_e32 v135, v134, v133
	v_fma_f32 v136, -v132, v135, v134
	v_fmac_f32_e32 v135, v136, v133
	v_fma_f32 v132, -v132, v135, v134
	v_div_fmas_f32 v132, v132, v133, v135
	v_div_fixup_f32 v32, v132, v32, v3
	v_bfe_u32 v132, v32, 16, 1
	v_add3_u32 v32, v32, v132, s1
	global_store_short_d16_hi v[140:141], v32, off offset:192
	v_mul_f32_e32 v32, 0xbfb8aa3b, v20
	v_exp_f32_e32 v32, v32
	s_nop 0
	v_add_f32_e32 v32, 1.0, v32
	v_div_scale_f32 v132, s[2:3], v32, v32, v20
	v_rcp_f32_e32 v133, v132
	s_nop 0
	v_fma_f32 v134, -v132, v133, 1.0
	v_fmac_f32_e32 v133, v134, v133
	v_div_scale_f32 v134, vcc, v20, v32, v20
	v_mul_f32_e32 v135, v134, v133
	v_fma_f32 v136, -v132, v135, v134
	v_fmac_f32_e32 v135, v136, v133
	v_fma_f32 v132, -v132, v135, v134
	v_div_fmas_f32 v132, v132, v133, v135
	v_div_fixup_f32 v32, v132, v32, v20
	v_bfe_u32 v132, v32, 16, 1
	v_add3_u32 v32, v32, v132, s1
	global_store_short_d16_hi v[142:143], v32, off offset:64
	v_mul_f32_e32 v32, 0xbfb8aa3b, v4
	v_exp_f32_e32 v32, v32
	s_nop 0
	v_add_f32_e32 v32, 1.0, v32
	v_div_scale_f32 v132, s[2:3], v32, v32, v4
	v_rcp_f32_e32 v133, v132
	s_nop 0
	v_fma_f32 v134, -v132, v133, 1.0
	v_fmac_f32_e32 v133, v134, v133
	v_div_scale_f32 v134, vcc, v4, v32, v4
	v_mul_f32_e32 v135, v134, v133
	v_fma_f32 v136, -v132, v135, v134
	v_fmac_f32_e32 v135, v136, v133
	v_fma_f32 v132, -v132, v135, v134
	v_div_fmas_f32 v132, v132, v133, v135
	v_div_fixup_f32 v32, v132, v32, v4
	v_bfe_u32 v132, v32, 16, 1
	v_add3_u32 v32, v32, v132, s1
	global_store_short_d16_hi v[142:143], v32, off offset:192
	v_mul_f32_e32 v32, 0xbfb8aa3b, v21
	v_exp_f32_e32 v32, v32
	s_nop 0
	v_add_f32_e32 v32, 1.0, v32
	v_div_scale_f32 v132, s[2:3], v32, v32, v21
	v_rcp_f32_e32 v133, v132
	s_nop 0
	v_fma_f32 v134, -v132, v133, 1.0
	v_fmac_f32_e32 v133, v134, v133
	v_div_scale_f32 v134, vcc, v21, v32, v21
	v_mul_f32_e32 v135, v134, v133
	v_fma_f32 v136, -v132, v135, v134
	v_fmac_f32_e32 v135, v136, v133
	v_fma_f32 v132, -v132, v135, v134
	v_div_fmas_f32 v132, v132, v133, v135
	v_div_fixup_f32 v32, v132, v32, v21
	v_bfe_u32 v132, v32, 16, 1
	v_add3_u32 v32, v32, v132, s1
	global_store_short_d16_hi v[144:145], v32, off offset:64
	v_mul_f32_e32 v32, 0xbfb8aa3b, v5
	v_exp_f32_e32 v32, v32
	s_nop 0
	v_add_f32_e32 v32, 1.0, v32
	v_div_scale_f32 v132, s[2:3], v32, v32, v5
	v_rcp_f32_e32 v133, v132
	s_nop 0
	v_fma_f32 v134, -v132, v133, 1.0
	v_fmac_f32_e32 v133, v134, v133
	v_div_scale_f32 v134, vcc, v5, v32, v5
	v_mul_f32_e32 v135, v134, v133
	v_fma_f32 v136, -v132, v135, v134
	v_fmac_f32_e32 v135, v136, v133
	v_fma_f32 v132, -v132, v135, v134
	v_div_fmas_f32 v132, v132, v133, v135
	v_div_fixup_f32 v32, v132, v32, v5
	v_bfe_u32 v132, v32, 16, 1
	v_add3_u32 v32, v32, v132, s1
	global_store_short_d16_hi v[144:145], v32, off offset:192
	v_mul_f32_e32 v32, 0xbfb8aa3b, v22
	v_exp_f32_e32 v32, v32
	s_nop 0
	v_add_f32_e32 v32, 1.0, v32
	v_div_scale_f32 v132, s[2:3], v32, v32, v22
	v_rcp_f32_e32 v133, v132
	s_nop 0
	v_fma_f32 v134, -v132, v133, 1.0
	v_fmac_f32_e32 v133, v134, v133
	v_div_scale_f32 v134, vcc, v22, v32, v22
	v_mul_f32_e32 v135, v134, v133
	v_fma_f32 v136, -v132, v135, v134
	v_fmac_f32_e32 v135, v136, v133
	v_fma_f32 v132, -v132, v135, v134
	v_div_fmas_f32 v132, v132, v133, v135
	v_div_fixup_f32 v32, v132, v32, v22
	v_bfe_u32 v132, v32, 16, 1
	v_add3_u32 v32, v32, v132, s1
	global_store_short_d16_hi v[146:147], v32, off offset:64
	v_mul_f32_e32 v32, 0xbfb8aa3b, v6
	v_exp_f32_e32 v32, v32
	s_nop 0
	v_add_f32_e32 v32, 1.0, v32
	v_div_scale_f32 v132, s[2:3], v32, v32, v6
	v_rcp_f32_e32 v133, v132
	s_nop 0
	v_fma_f32 v134, -v132, v133, 1.0
	v_fmac_f32_e32 v133, v134, v133
	v_div_scale_f32 v134, vcc, v6, v32, v6
	v_mul_f32_e32 v135, v134, v133
	v_fma_f32 v136, -v132, v135, v134
	v_fmac_f32_e32 v135, v136, v133
	v_fma_f32 v132, -v132, v135, v134
	v_div_fmas_f32 v132, v132, v133, v135
	v_div_fixup_f32 v32, v132, v32, v6
	v_bfe_u32 v132, v32, 16, 1
	v_add3_u32 v32, v32, v132, s1
	global_store_short_d16_hi v[146:147], v32, off offset:192
	v_mul_f32_e32 v32, 0xbfb8aa3b, v23
	v_exp_f32_e32 v32, v32
	s_nop 0
	v_add_f32_e32 v32, 1.0, v32
	v_div_scale_f32 v132, s[2:3], v32, v32, v23
	v_rcp_f32_e32 v133, v132
	s_nop 0
	v_fma_f32 v134, -v132, v133, 1.0
	v_fmac_f32_e32 v133, v134, v133
	v_div_scale_f32 v134, vcc, v23, v32, v23
	v_mul_f32_e32 v135, v134, v133
	v_fma_f32 v136, -v132, v135, v134
	v_fmac_f32_e32 v135, v136, v133
	v_fma_f32 v132, -v132, v135, v134
	v_div_fmas_f32 v132, v132, v133, v135
	v_div_fixup_f32 v32, v132, v32, v23
	v_bfe_u32 v132, v32, 16, 1
	v_add3_u32 v32, v32, v132, s1
	global_store_short_d16_hi v[148:149], v32, off offset:64
	v_mul_f32_e32 v32, 0xbfb8aa3b, v7
	v_exp_f32_e32 v32, v32
	s_nop 0
	v_add_f32_e32 v32, 1.0, v32
	v_div_scale_f32 v132, s[2:3], v32, v32, v7
	v_rcp_f32_e32 v133, v132
	s_nop 0
	v_fma_f32 v134, -v132, v133, 1.0
	v_fmac_f32_e32 v133, v134, v133
	v_div_scale_f32 v134, vcc, v7, v32, v7
	v_mul_f32_e32 v135, v134, v133
	v_fma_f32 v136, -v132, v135, v134
	v_fmac_f32_e32 v135, v136, v133
	v_fma_f32 v132, -v132, v135, v134
	v_div_fmas_f32 v132, v132, v133, v135
	v_div_fixup_f32 v32, v132, v32, v7
	v_bfe_u32 v132, v32, 16, 1
	v_add3_u32 v32, v32, v132, s1
	global_store_short_d16_hi v[148:149], v32, off offset:192
	v_mul_f32_e32 v32, 0xbfb8aa3b, v24
	v_exp_f32_e32 v32, v32
	s_nop 0
	v_add_f32_e32 v32, 1.0, v32
	v_div_scale_f32 v132, s[2:3], v32, v32, v24
	v_rcp_f32_e32 v133, v132
	s_nop 0
	v_fma_f32 v134, -v132, v133, 1.0
	v_fmac_f32_e32 v133, v134, v133
	v_div_scale_f32 v134, vcc, v24, v32, v24
	v_mul_f32_e32 v135, v134, v133
	v_fma_f32 v136, -v132, v135, v134
	v_fmac_f32_e32 v135, v136, v133
	v_fma_f32 v132, -v132, v135, v134
	v_div_fmas_f32 v132, v132, v133, v135
	v_div_fixup_f32 v32, v132, v32, v24
	v_bfe_u32 v132, v32, 16, 1
	v_add3_u32 v32, v32, v132, s1
	global_store_short_d16_hi v[150:151], v32, off offset:64
	v_mul_f32_e32 v32, 0xbfb8aa3b, v8
	v_exp_f32_e32 v32, v32
	s_nop 0
	v_add_f32_e32 v32, 1.0, v32
	v_div_scale_f32 v132, s[2:3], v32, v32, v8
	v_rcp_f32_e32 v133, v132
	s_nop 0
	v_fma_f32 v134, -v132, v133, 1.0
	v_fmac_f32_e32 v133, v134, v133
	v_div_scale_f32 v134, vcc, v8, v32, v8
	v_mul_f32_e32 v135, v134, v133
	v_fma_f32 v136, -v132, v135, v134
	v_fmac_f32_e32 v135, v136, v133
	v_fma_f32 v132, -v132, v135, v134
	v_div_fmas_f32 v132, v132, v133, v135
	v_div_fixup_f32 v32, v132, v32, v8
	v_bfe_u32 v132, v32, 16, 1
	v_add3_u32 v32, v32, v132, s1
	global_store_short_d16_hi v[150:151], v32, off offset:192
	v_mul_f32_e32 v32, 0xbfb8aa3b, v25
	v_exp_f32_e32 v32, v32
	s_nop 0
	v_add_f32_e32 v32, 1.0, v32
	v_div_scale_f32 v132, s[2:3], v32, v32, v25
	v_rcp_f32_e32 v133, v132
	s_nop 0
	v_fma_f32 v134, -v132, v133, 1.0
	v_fmac_f32_e32 v133, v134, v133
	v_div_scale_f32 v134, vcc, v25, v32, v25
	v_mul_f32_e32 v135, v134, v133
	v_fma_f32 v136, -v132, v135, v134
	v_fmac_f32_e32 v135, v136, v133
	v_fma_f32 v132, -v132, v135, v134
	v_div_fmas_f32 v132, v132, v133, v135
	v_div_fixup_f32 v32, v132, v32, v25
	v_bfe_u32 v132, v32, 16, 1
	v_add3_u32 v32, v32, v132, s1
	global_store_short_d16_hi v[152:153], v32, off offset:64
	v_mul_f32_e32 v32, 0xbfb8aa3b, v9
	v_exp_f32_e32 v32, v32
	s_nop 0
	v_add_f32_e32 v32, 1.0, v32
	v_div_scale_f32 v132, s[2:3], v32, v32, v9
	v_rcp_f32_e32 v133, v132
	s_nop 0
	v_fma_f32 v134, -v132, v133, 1.0
	v_fmac_f32_e32 v133, v134, v133
	v_div_scale_f32 v134, vcc, v9, v32, v9
	v_mul_f32_e32 v135, v134, v133
	v_fma_f32 v136, -v132, v135, v134
	v_fmac_f32_e32 v135, v136, v133
	v_fma_f32 v132, -v132, v135, v134
	v_div_fmas_f32 v132, v132, v133, v135
	v_div_fixup_f32 v32, v132, v32, v9
	v_bfe_u32 v132, v32, 16, 1
	v_add3_u32 v32, v32, v132, s1
	global_store_short_d16_hi v[152:153], v32, off offset:192
	v_mul_f32_e32 v32, 0xbfb8aa3b, v26
	v_exp_f32_e32 v32, v32
	s_nop 0
	v_add_f32_e32 v32, 1.0, v32
	v_div_scale_f32 v132, s[2:3], v32, v32, v26
	v_rcp_f32_e32 v133, v132
	s_nop 0
	v_fma_f32 v134, -v132, v133, 1.0
	v_fmac_f32_e32 v133, v134, v133
	v_div_scale_f32 v134, vcc, v26, v32, v26
	v_mul_f32_e32 v135, v134, v133
	v_fma_f32 v136, -v132, v135, v134
	v_fmac_f32_e32 v135, v136, v133
	v_fma_f32 v132, -v132, v135, v134
	v_div_fmas_f32 v132, v132, v133, v135
	v_div_fixup_f32 v32, v132, v32, v26
	v_bfe_u32 v132, v32, 16, 1
	v_add3_u32 v32, v32, v132, s1
	global_store_short_d16_hi v[154:155], v32, off offset:64
	v_mul_f32_e32 v32, 0xbfb8aa3b, v10
	v_exp_f32_e32 v32, v32
	s_nop 0
	v_add_f32_e32 v32, 1.0, v32
	v_div_scale_f32 v132, s[2:3], v32, v32, v10
	v_rcp_f32_e32 v133, v132
	s_nop 0
	v_fma_f32 v134, -v132, v133, 1.0
	v_fmac_f32_e32 v133, v134, v133
	v_div_scale_f32 v134, vcc, v10, v32, v10
	v_mul_f32_e32 v135, v134, v133
	v_fma_f32 v136, -v132, v135, v134
	v_fmac_f32_e32 v135, v136, v133
	v_fma_f32 v132, -v132, v135, v134
	v_div_fmas_f32 v132, v132, v133, v135
	v_div_fixup_f32 v32, v132, v32, v10
	v_bfe_u32 v132, v32, 16, 1
	v_add3_u32 v32, v32, v132, s1
	global_store_short_d16_hi v[154:155], v32, off offset:192
	v_mul_f32_e32 v32, 0xbfb8aa3b, v27
	v_exp_f32_e32 v32, v32
	s_nop 0
	v_add_f32_e32 v32, 1.0, v32
	v_div_scale_f32 v132, s[2:3], v32, v32, v27
	v_rcp_f32_e32 v133, v132
	s_nop 0
	v_fma_f32 v134, -v132, v133, 1.0
	v_fmac_f32_e32 v133, v134, v133
	v_div_scale_f32 v134, vcc, v27, v32, v27
	v_mul_f32_e32 v135, v134, v133
	v_fma_f32 v136, -v132, v135, v134
	v_fmac_f32_e32 v135, v136, v133
	v_fma_f32 v132, -v132, v135, v134
	v_div_fmas_f32 v132, v132, v133, v135
	v_div_fixup_f32 v32, v132, v32, v27
	v_bfe_u32 v132, v32, 16, 1
	v_add3_u32 v32, v32, v132, s1
	global_store_short_d16_hi v[156:157], v32, off offset:64
	v_mul_f32_e32 v32, 0xbfb8aa3b, v11
	v_exp_f32_e32 v32, v32
	s_nop 0
	v_add_f32_e32 v32, 1.0, v32
	v_div_scale_f32 v132, s[2:3], v32, v32, v11
	v_rcp_f32_e32 v133, v132
	s_nop 0
	v_fma_f32 v134, -v132, v133, 1.0
	v_fmac_f32_e32 v133, v134, v133
	v_div_scale_f32 v134, vcc, v11, v32, v11
	v_mul_f32_e32 v135, v134, v133
	v_fma_f32 v136, -v132, v135, v134
	v_fmac_f32_e32 v135, v136, v133
	v_fma_f32 v132, -v132, v135, v134
	v_div_fmas_f32 v132, v132, v133, v135
	v_div_fixup_f32 v32, v132, v32, v11
	v_bfe_u32 v132, v32, 16, 1
	v_add3_u32 v32, v32, v132, s1
	global_store_short_d16_hi v[156:157], v32, off offset:192
	v_mul_f32_e32 v32, 0xbfb8aa3b, v28
	v_exp_f32_e32 v32, v32
	s_nop 0
	v_add_f32_e32 v32, 1.0, v32
	v_div_scale_f32 v132, s[2:3], v32, v32, v28
	v_rcp_f32_e32 v133, v132
	s_nop 0
	v_fma_f32 v134, -v132, v133, 1.0
	v_fmac_f32_e32 v133, v134, v133
	v_div_scale_f32 v134, vcc, v28, v32, v28
	v_mul_f32_e32 v135, v134, v133
	v_fma_f32 v136, -v132, v135, v134
	v_fmac_f32_e32 v135, v136, v133
	v_fma_f32 v132, -v132, v135, v134
	v_div_fmas_f32 v132, v132, v133, v135
	v_div_fixup_f32 v32, v132, v32, v28
	v_bfe_u32 v132, v32, 16, 1
	v_add3_u32 v32, v32, v132, s1
	global_store_short_d16_hi v[158:159], v32, off offset:64
	v_mul_f32_e32 v32, 0xbfb8aa3b, v12
	v_exp_f32_e32 v32, v32
	s_nop 0
	v_add_f32_e32 v32, 1.0, v32
	v_div_scale_f32 v132, s[2:3], v32, v32, v12
	v_rcp_f32_e32 v133, v132
	s_nop 0
	v_fma_f32 v134, -v132, v133, 1.0
	v_fmac_f32_e32 v133, v134, v133
	v_div_scale_f32 v134, vcc, v12, v32, v12
	v_mul_f32_e32 v135, v134, v133
	v_fma_f32 v136, -v132, v135, v134
	v_fmac_f32_e32 v135, v136, v133
	v_fma_f32 v132, -v132, v135, v134
	v_div_fmas_f32 v132, v132, v133, v135
	v_div_fixup_f32 v32, v132, v32, v12
	v_bfe_u32 v132, v32, 16, 1
	v_add3_u32 v32, v32, v132, s1
	global_store_short_d16_hi v[158:159], v32, off offset:192
	v_mul_f32_e32 v32, 0xbfb8aa3b, v29
	v_exp_f32_e32 v32, v32
	s_nop 0
	v_add_f32_e32 v32, 1.0, v32
	v_div_scale_f32 v132, s[2:3], v32, v32, v29
	v_rcp_f32_e32 v133, v132
	s_nop 0
	v_fma_f32 v134, -v132, v133, 1.0
	v_fmac_f32_e32 v133, v134, v133
	v_div_scale_f32 v134, vcc, v29, v32, v29
	v_mul_f32_e32 v135, v134, v133
	v_fma_f32 v136, -v132, v135, v134
	v_fmac_f32_e32 v135, v136, v133
	v_fma_f32 v132, -v132, v135, v134
	v_div_fmas_f32 v132, v132, v133, v135
	v_div_fixup_f32 v32, v132, v32, v29
	v_bfe_u32 v132, v32, 16, 1
	v_add3_u32 v32, v32, v132, s1
	global_store_short_d16_hi v[160:161], v32, off offset:64
	v_mul_f32_e32 v32, 0xbfb8aa3b, v13
	v_exp_f32_e32 v32, v32
	s_nop 0
	v_add_f32_e32 v32, 1.0, v32
	v_div_scale_f32 v132, s[2:3], v32, v32, v13
	v_rcp_f32_e32 v133, v132
	s_nop 0
	v_fma_f32 v134, -v132, v133, 1.0
	v_fmac_f32_e32 v133, v134, v133
	v_div_scale_f32 v134, vcc, v13, v32, v13
	v_mul_f32_e32 v135, v134, v133
	v_fma_f32 v136, -v132, v135, v134
	v_fmac_f32_e32 v135, v136, v133
	v_fma_f32 v132, -v132, v135, v134
	v_div_fmas_f32 v132, v132, v133, v135
	v_div_fixup_f32 v32, v132, v32, v13
	v_bfe_u32 v132, v32, 16, 1
	v_add3_u32 v32, v32, v132, s1
	global_store_short_d16_hi v[160:161], v32, off offset:192
	v_mul_f32_e32 v32, 0xbfb8aa3b, v30
	v_exp_f32_e32 v32, v32
	s_nop 0
	v_add_f32_e32 v32, 1.0, v32
	v_div_scale_f32 v132, s[2:3], v32, v32, v30
	v_rcp_f32_e32 v133, v132
	s_nop 0
	v_fma_f32 v134, -v132, v133, 1.0
	v_fmac_f32_e32 v133, v134, v133
	v_div_scale_f32 v134, vcc, v30, v32, v30
	v_mul_f32_e32 v135, v134, v133
	v_fma_f32 v136, -v132, v135, v134
	v_fmac_f32_e32 v135, v136, v133
	v_fma_f32 v132, -v132, v135, v134
	v_div_fmas_f32 v132, v132, v133, v135
	v_div_fixup_f32 v32, v132, v32, v30
	v_bfe_u32 v132, v32, 16, 1
	v_add3_u32 v32, v32, v132, s1
	global_store_short_d16_hi v[162:163], v32, off offset:64
	v_mul_f32_e32 v32, 0xbfb8aa3b, v14
	v_exp_f32_e32 v32, v32
	s_nop 0
	v_add_f32_e32 v32, 1.0, v32
	v_div_scale_f32 v132, s[2:3], v32, v32, v14
	v_rcp_f32_e32 v133, v132
	s_nop 0
	v_fma_f32 v134, -v132, v133, 1.0
	v_fmac_f32_e32 v133, v134, v133
	v_div_scale_f32 v134, vcc, v14, v32, v14
	v_mul_f32_e32 v135, v134, v133
	v_fma_f32 v136, -v132, v135, v134
	v_fmac_f32_e32 v135, v136, v133
	v_fma_f32 v132, -v132, v135, v134
	v_div_fmas_f32 v132, v132, v133, v135
	v_div_fixup_f32 v32, v132, v32, v14
	v_bfe_u32 v132, v32, 16, 1
	v_add3_u32 v32, v32, v132, s1
	global_store_short_d16_hi v[162:163], v32, off offset:192
	v_mul_f32_e32 v32, 0xbfb8aa3b, v31
	v_exp_f32_e32 v32, v32
	s_nop 0
	v_add_f32_e32 v32, 1.0, v32
	v_div_scale_f32 v132, s[2:3], v32, v32, v31
	v_rcp_f32_e32 v133, v132
	s_nop 0
	v_fma_f32 v134, -v132, v133, 1.0
	v_fmac_f32_e32 v133, v134, v133
	v_div_scale_f32 v134, vcc, v31, v32, v31
	v_mul_f32_e32 v135, v134, v133
	v_fma_f32 v136, -v132, v135, v134
	v_fmac_f32_e32 v135, v136, v133
	v_fma_f32 v132, -v132, v135, v134
	v_div_fmas_f32 v132, v132, v133, v135
	v_div_fixup_f32 v32, v132, v32, v31
	v_bfe_u32 v132, v32, 16, 1
	v_add3_u32 v32, v32, v132, s1
	global_store_short_d16_hi v[130:131], v32, off offset:64
	v_mul_f32_e32 v32, 0xbfb8aa3b, v15
	v_exp_f32_e32 v32, v32
	s_nop 0
	v_add_f32_e32 v32, 1.0, v32
	v_div_scale_f32 v132, s[2:3], v32, v32, v15
	v_rcp_f32_e32 v133, v132
	s_mov_b64 s[2:3], 0
	v_fma_f32 v134, -v132, v133, 1.0
	v_fmac_f32_e32 v133, v134, v133
	v_div_scale_f32 v134, vcc, v15, v32, v15
	v_mul_f32_e32 v135, v134, v133
	v_fma_f32 v136, -v132, v135, v134
	v_fmac_f32_e32 v135, v136, v133
	v_fma_f32 v132, -v132, v135, v134
	v_div_fmas_f32 v132, v132, v133, v135
	v_div_fixup_f32 v32, v132, v32, v15
	v_bfe_u32 v132, v32, 16, 1
	v_add3_u32 v32, v32, v132, s1
	global_store_short_d16_hi v[130:131], v32, off offset:192

.LBB0_1407:
	s_setprio 2
	ds_read_b128 v[162:165], v134
	ds_read_b128 v[166:169], v135 offset:36864
	ds_read_b128 v[170:173], v135 offset:46080
	v_cndmask_b32_e64 v137, 0, 1, s[6:7]
	v_cmp_ne_u32_e64 s[0:1], 1, v137
	s_andn2_b64 vcc, exec, s[6:7]
	s_waitcnt lgkmcnt(1)
	v_mfma_f32_32x32x16_bf16 v[50:65], v[162:165], v[166:169], v[50:65]
	s_waitcnt lgkmcnt(0)
	v_mfma_f32_32x32x16_bf16 v[34:49], v[162:165], v[170:173], v[34:49]
	ds_read_b128 v[162:165], v134 offset:4608
	s_waitcnt lgkmcnt(0)
	v_mfma_f32_32x32x16_bf16 v[0:15], v[162:165], v[166:169], v[0:15]
	v_mfma_f32_32x32x16_bf16 v[16:31], v[162:165], v[170:173], v[16:31]
	ds_read_b128 v[162:165], v134 offset:32
	ds_read_b128 v[166:169], v135 offset:36896
	ds_read_b128 v[170:173], v135 offset:46112
	s_waitcnt lgkmcnt(1)
	v_mfma_f32_32x32x16_bf16 v[50:65], v[162:165], v[166:169], v[50:65]
	s_waitcnt lgkmcnt(0)
	v_mfma_f32_32x32x16_bf16 v[34:49], v[162:165], v[170:173], v[34:49]
	ds_read_b128 v[162:165], v134 offset:4640
	s_waitcnt lgkmcnt(0)
	v_mfma_f32_32x32x16_bf16 v[0:15], v[162:165], v[166:169], v[0:15]
	v_mfma_f32_32x32x16_bf16 v[16:31], v[162:165], v[170:173], v[16:31]
	ds_read_b128 v[162:165], v134 offset:64
	ds_read_b128 v[166:169], v135 offset:36928
	ds_read_b128 v[170:173], v135 offset:46144
	s_waitcnt lgkmcnt(1)
	v_mfma_f32_32x32x16_bf16 v[50:65], v[162:165], v[166:169], v[50:65]
	s_waitcnt lgkmcnt(0)
	v_mfma_f32_32x32x16_bf16 v[34:49], v[162:165], v[170:173], v[34:49]
	ds_read_b128 v[162:165], v134 offset:4672
	s_waitcnt lgkmcnt(0)
	v_mfma_f32_32x32x16_bf16 v[0:15], v[162:165], v[166:169], v[0:15]
	v_mfma_f32_32x32x16_bf16 v[16:31], v[162:165], v[170:173], v[16:31]
	ds_read_b128 v[162:165], v134 offset:96
	ds_read_b128 v[166:169], v135 offset:36960
	ds_read_b128 v[170:173], v135 offset:46176
	s_waitcnt lgkmcnt(1)
	v_mfma_f32_32x32x16_bf16 v[50:65], v[162:165], v[166:169], v[50:65]
	s_waitcnt lgkmcnt(0)
	v_mfma_f32_32x32x16_bf16 v[34:49], v[162:165], v[170:173], v[34:49]
	s_setprio 0
	ds_read_b128 v[162:165], v134 offset:4704
	s_waitcnt vmcnt(7)
	ds_write_b128 v136, v[98:101] offset:18432
	s_waitcnt vmcnt(3)
	ds_write_b128 v136, v[106:109] offset:55296
	ds_write_b128 v136, v[102:105] offset:23040
	s_waitcnt vmcnt(2)
	ds_write_b128 v136, v[118:121] offset:59904
	ds_write_b128 v136, v[110:113] offset:27648
	s_waitcnt vmcnt(1)
	ds_write_b128 v136, v[122:125] offset:64512
	ds_write_b128 v136, v[114:117] offset:32256
	s_waitcnt vmcnt(0)
	ds_write_b128 v32, v[126:129] offset:13824
	s_waitcnt lgkmcnt(0)
	s_barrier
	v_mfma_f32_32x32x16_bf16 v[0:15], v[162:165], v[166:169], v[0:15]
	v_mfma_f32_32x32x16_bf16 v[16:31], v[162:165], v[170:173], v[16:31]
	s_cbranch_vccnz .LBB0_1409
	global_load_dwordx4 v[98:101], v[130:131], off offset:384
	global_load_dwordx4 v[106:109], v[132:133], off offset:384
	global_load_dwordx4 v[102:105], v[150:151], off
	global_load_dwordx4 v[118:121], v[152:153], off
	global_load_dwordx4 v[110:113], v[154:155], off
	global_load_dwordx4 v[122:125], v[156:157], off
	global_load_dwordx4 v[114:117], v[158:159], off
	global_load_dwordx4 v[126:129], v[160:161], off
.LBB0_1409:
	s_setprio 2
	ds_read_b128 v[162:165], v134 offset:18432
	ds_read_b128 v[166:169], v135 offset:55296
	ds_read_b128 v[170:173], v135 offset:64512
	s_and_b64 vcc, exec, s[0:1]
	s_waitcnt lgkmcnt(1)
	v_mfma_f32_32x32x16_bf16 v[50:65], v[162:165], v[166:169], v[50:65]
	s_waitcnt lgkmcnt(0)
	v_mfma_f32_32x32x16_bf16 v[34:49], v[162:165], v[170:173], v[34:49]
	ds_read_b128 v[162:165], v134 offset:23040
	s_waitcnt lgkmcnt(0)
	v_mfma_f32_32x32x16_bf16 v[0:15], v[162:165], v[166:169], v[0:15]
	v_mfma_f32_32x32x16_bf16 v[16:31], v[162:165], v[170:173], v[16:31]
	ds_read_b128 v[162:165], v134 offset:18464
	ds_read_b128 v[166:169], v135 offset:55328
	ds_read_b128 v[170:173], v135 offset:64544
	s_waitcnt lgkmcnt(1)
	v_mfma_f32_32x32x16_bf16 v[50:65], v[162:165], v[166:169], v[50:65]
	s_waitcnt lgkmcnt(0)
	v_mfma_f32_32x32x16_bf16 v[34:49], v[162:165], v[170:173], v[34:49]
	ds_read_b128 v[162:165], v134 offset:23072
	s_waitcnt lgkmcnt(0)
	v_mfma_f32_32x32x16_bf16 v[0:15], v[162:165], v[166:169], v[0:15]
	v_mfma_f32_32x32x16_bf16 v[16:31], v[162:165], v[170:173], v[16:31]
	ds_read_b128 v[162:165], v134 offset:18496
	ds_read_b128 v[166:169], v135 offset:55360
	ds_read_b128 v[170:173], v135 offset:64576
	s_waitcnt lgkmcnt(1)
	v_mfma_f32_32x32x16_bf16 v[50:65], v[162:165], v[166:169], v[50:65]
	s_waitcnt lgkmcnt(0)
	v_mfma_f32_32x32x16_bf16 v[34:49], v[162:165], v[170:173], v[34:49]
	ds_read_b128 v[162:165], v134 offset:23104
	s_waitcnt lgkmcnt(0)
	v_mfma_f32_32x32x16_bf16 v[0:15], v[162:165], v[166:169], v[0:15]
	v_mfma_f32_32x32x16_bf16 v[16:31], v[162:165], v[170:173], v[16:31]
	ds_read_b128 v[162:165], v134 offset:18528
	ds_read_b128 v[166:169], v135 offset:55392
	ds_read_b128 v[170:173], v135 offset:64608
	s_waitcnt lgkmcnt(1)
	v_mfma_f32_32x32x16_bf16 v[50:65], v[162:165], v[166:169], v[50:65]
	s_waitcnt lgkmcnt(0)
	v_mfma_f32_32x32x16_bf16 v[34:49], v[162:165], v[170:173], v[34:49]
	ds_read_b128 v[162:165], v134 offset:23136
	s_waitcnt lgkmcnt(0)
	v_mfma_f32_32x32x16_bf16 v[0:15], v[162:165], v[166:169], v[0:15]
	v_mfma_f32_32x32x16_bf16 v[16:31], v[162:165], v[170:173], v[16:31]
	s_setprio 0
	s_cbranch_vccnz .LBB0_1404
	ds_write_b128 v136, v[66:69]
	ds_write_b128 v136, v[70:73] offset:36864
	ds_write_b128 v136, v[74:77] offset:4608
	ds_write_b128 v136, v[78:81] offset:41472
	ds_write_b128 v136, v[82:85] offset:9216
	ds_write_b128 v136, v[86:89] offset:46080
	ds_write_b128 v136, v[90:93] offset:13824
	ds_write_b128 v136, v[94:97] offset:50688
	s_branch .LBB0_1404

.LBB0_1564:
	s_setprio 2
	ds_read_b128 v[162:165], v134
	ds_read_b128 v[166:169], v135 offset:36864
	ds_read_b128 v[170:173], v135 offset:46080
	v_cndmask_b32_e64 v137, 0, 1, s[8:9]
	v_cmp_ne_u32_e64 s[0:1], 1, v137
	s_andn2_b64 vcc, exec, s[8:9]
	s_waitcnt lgkmcnt(1)
	v_mfma_f32_32x32x16_bf16 v[50:65], v[162:165], v[166:169], v[50:65]
	s_waitcnt lgkmcnt(0)
	v_mfma_f32_32x32x16_bf16 v[34:49], v[162:165], v[170:173], v[34:49]
	ds_read_b128 v[162:165], v134 offset:4608
	s_waitcnt lgkmcnt(0)
	v_mfma_f32_32x32x16_bf16 v[16:31], v[162:165], v[166:169], v[16:31]
	v_mfma_f32_32x32x16_bf16 v[0:15], v[162:165], v[170:173], v[0:15]
	ds_read_b128 v[162:165], v134 offset:32
	ds_read_b128 v[166:169], v135 offset:36896
	ds_read_b128 v[170:173], v135 offset:46112
	s_waitcnt lgkmcnt(1)
	v_mfma_f32_32x32x16_bf16 v[50:65], v[162:165], v[166:169], v[50:65]
	s_waitcnt lgkmcnt(0)
	v_mfma_f32_32x32x16_bf16 v[34:49], v[162:165], v[170:173], v[34:49]
	ds_read_b128 v[162:165], v134 offset:4640
	s_waitcnt lgkmcnt(0)
	v_mfma_f32_32x32x16_bf16 v[16:31], v[162:165], v[166:169], v[16:31]
	v_mfma_f32_32x32x16_bf16 v[0:15], v[162:165], v[170:173], v[0:15]
	ds_read_b128 v[162:165], v134 offset:64
	ds_read_b128 v[166:169], v135 offset:36928
	ds_read_b128 v[170:173], v135 offset:46144
	s_waitcnt lgkmcnt(1)
	v_mfma_f32_32x32x16_bf16 v[50:65], v[162:165], v[166:169], v[50:65]
	s_waitcnt lgkmcnt(0)
	v_mfma_f32_32x32x16_bf16 v[34:49], v[162:165], v[170:173], v[34:49]
	ds_read_b128 v[162:165], v134 offset:4672
	s_waitcnt lgkmcnt(0)
	v_mfma_f32_32x32x16_bf16 v[16:31], v[162:165], v[166:169], v[16:31]
	v_mfma_f32_32x32x16_bf16 v[0:15], v[162:165], v[170:173], v[0:15]
	ds_read_b128 v[162:165], v134 offset:96
	ds_read_b128 v[166:169], v135 offset:36960
	ds_read_b128 v[170:173], v135 offset:46176
	s_waitcnt lgkmcnt(1)
	v_mfma_f32_32x32x16_bf16 v[50:65], v[162:165], v[166:169], v[50:65]
	s_waitcnt lgkmcnt(0)
	v_mfma_f32_32x32x16_bf16 v[34:49], v[162:165], v[170:173], v[34:49]
	s_setprio 0
	ds_read_b128 v[162:165], v134 offset:4704
	s_waitcnt vmcnt(7)
	ds_write_b128 v136, v[94:97] offset:18432
	s_waitcnt vmcnt(6)
	ds_write_b128 v136, v[98:101] offset:55296
	s_waitcnt vmcnt(5)
	ds_write_b128 v136, v[102:105] offset:23040
	s_waitcnt vmcnt(4)
	ds_write_b128 v136, v[110:113] offset:59904
	s_waitcnt vmcnt(3)
	ds_write_b128 v136, v[114:117] offset:27648
	s_waitcnt vmcnt(2)
	ds_write_b128 v136, v[118:121] offset:64512
	s_waitcnt vmcnt(1)
	ds_write_b128 v136, v[122:125] offset:32256
	s_waitcnt vmcnt(0)
	ds_write_b128 v32, v[126:129] offset:13824
	s_waitcnt lgkmcnt(0)
	s_barrier
	v_mfma_f32_32x32x16_bf16 v[16:31], v[162:165], v[166:169], v[16:31]
	v_mfma_f32_32x32x16_bf16 v[0:15], v[162:165], v[170:173], v[0:15]
	s_cbranch_vccnz .LBB0_1566
	global_load_dwordx4 v[94:97], v[130:131], off offset:384
	global_load_dwordx4 v[98:101], v[132:133], off offset:384
	global_load_dwordx4 v[102:105], v[150:151], off
	global_load_dwordx4 v[110:113], v[152:153], off
	global_load_dwordx4 v[114:117], v[154:155], off
	global_load_dwordx4 v[118:121], v[156:157], off
	global_load_dwordx4 v[122:125], v[158:159], off
	global_load_dwordx4 v[126:129], v[160:161], off
.LBB0_1566:
	s_setprio 2
	ds_read_b128 v[162:165], v134 offset:18432
	ds_read_b128 v[166:169], v135 offset:55296
	ds_read_b128 v[170:173], v135 offset:64512
	s_and_b64 vcc, exec, s[0:1]
	s_waitcnt lgkmcnt(1)
	v_mfma_f32_32x32x16_bf16 v[50:65], v[162:165], v[166:169], v[50:65]
	s_waitcnt lgkmcnt(0)
	v_mfma_f32_32x32x16_bf16 v[34:49], v[162:165], v[170:173], v[34:49]
	ds_read_b128 v[162:165], v134 offset:23040
	s_waitcnt lgkmcnt(0)
	v_mfma_f32_32x32x16_bf16 v[16:31], v[162:165], v[166:169], v[16:31]
	v_mfma_f32_32x32x16_bf16 v[0:15], v[162:165], v[170:173], v[0:15]
	ds_read_b128 v[162:165], v134 offset:18464
	ds_read_b128 v[166:169], v135 offset:55328
	ds_read_b128 v[170:173], v135 offset:64544
	s_waitcnt lgkmcnt(1)
	v_mfma_f32_32x32x16_bf16 v[50:65], v[162:165], v[166:169], v[50:65]
	s_waitcnt lgkmcnt(0)
	v_mfma_f32_32x32x16_bf16 v[34:49], v[162:165], v[170:173], v[34:49]
	ds_read_b128 v[162:165], v134 offset:23072
	s_waitcnt lgkmcnt(0)
	v_mfma_f32_32x32x16_bf16 v[16:31], v[162:165], v[166:169], v[16:31]
	v_mfma_f32_32x32x16_bf16 v[0:15], v[162:165], v[170:173], v[0:15]
	ds_read_b128 v[162:165], v134 offset:18496
	ds_read_b128 v[166:169], v135 offset:55360
	ds_read_b128 v[170:173], v135 offset:64576
	s_waitcnt lgkmcnt(1)
	v_mfma_f32_32x32x16_bf16 v[50:65], v[162:165], v[166:169], v[50:65]
	s_waitcnt lgkmcnt(0)
	v_mfma_f32_32x32x16_bf16 v[34:49], v[162:165], v[170:173], v[34:49]
	ds_read_b128 v[162:165], v134 offset:23104
	s_waitcnt lgkmcnt(0)
	v_mfma_f32_32x32x16_bf16 v[16:31], v[162:165], v[166:169], v[16:31]
	v_mfma_f32_32x32x16_bf16 v[0:15], v[162:165], v[170:173], v[0:15]
	ds_read_b128 v[162:165], v134 offset:18528
	ds_read_b128 v[166:169], v135 offset:55392
	ds_read_b128 v[170:173], v135 offset:64608
	s_waitcnt lgkmcnt(1)
	v_mfma_f32_32x32x16_bf16 v[50:65], v[162:165], v[166:169], v[50:65]
	s_waitcnt lgkmcnt(0)
	v_mfma_f32_32x32x16_bf16 v[34:49], v[162:165], v[170:173], v[34:49]
	ds_read_b128 v[162:165], v134 offset:23136
	s_waitcnt lgkmcnt(0)
	v_mfma_f32_32x32x16_bf16 v[16:31], v[162:165], v[166:169], v[16:31]
	v_mfma_f32_32x32x16_bf16 v[0:15], v[162:165], v[170:173], v[0:15]
	s_setprio 0
	s_cbranch_vccnz .LBB0_1561
	ds_write_b128 v136, v[66:69]
	ds_write_b128 v136, v[70:73] offset:36864
	ds_write_b128 v136, v[74:77] offset:4608
	ds_write_b128 v136, v[78:81] offset:41472
	ds_write_b128 v136, v[82:85] offset:9216
	ds_write_b128 v136, v[86:89] offset:46080
	ds_write_b128 v136, v[90:93] offset:13824
	ds_write_b128 v136, v[106:109] offset:50688
	s_branch .LBB0_1561

.LBB0_1696:
	s_add_i32 s7, s3, 1
	s_cmp_lt_u32 s3, 31
	s_cselect_b32 s3, s7, s3
	s_lshl_b32 s16, s3, 6
	s_lshl_b64 s[14:15], s[16:17], 1
	s_barrier
	s_waitcnt vmcnt(0)
	ds_write_b128 v204, v[174:177]
	ds_write_b128 v204, v[170:173] offset:4608
	ds_write_b128 v204, v[166:169] offset:9216
	ds_write_b128 v204, v[162:165] offset:13824
	ds_write_b128 v204, v[158:161] offset:18432
	ds_write_b128 v204, v[154:157] offset:23040
	ds_write_b128 v204, v[150:153] offset:27648
	ds_write_b128 v204, v[146:149] offset:32256
	ds_write_b128 v204, v[142:145] offset:36864
	ds_write_b128 v204, v[134:137] offset:41472
	ds_write_b128 v204, v[130:133] offset:46080
	ds_write_b128 v204, v[138:141] offset:50688
	v_lshl_add_u64 v[130:131], v[178:179], 0, s[14:15]
	s_add_u32 s100, s14, 0x20000
	s_addc_u32 s101, s15, 0
	v_lshl_add_u64 v[132:133], v[178:179], 0, s[100:101]
	s_add_u32 s100, s100, 0x20000
	s_addc_u32 s101, s101, 0
	v_lshl_add_u64 v[134:135], v[178:179], 0, s[100:101]
	s_add_u32 s100, s100, 0x20000
	s_addc_u32 s101, s101, 0
	v_lshl_add_u64 v[136:137], v[178:179], 0, s[100:101]
	s_add_u32 s100, s100, 0x20000
	s_addc_u32 s101, s101, 0
	v_lshl_add_u64 v[138:139], v[178:179], 0, s[100:101]
	s_add_u32 s100, s100, 0x20000
	s_addc_u32 s101, s101, 0
	v_lshl_add_u64 v[140:141], v[178:179], 0, s[100:101]
	s_add_u32 s100, s100, 0x20000
	s_addc_u32 s101, s101, 0
	v_lshl_add_u64 v[142:143], v[178:179], 0, s[100:101]
	s_add_u32 s100, s100, 0x20000
	s_addc_u32 s101, s101, 0
	v_lshl_add_u64 v[144:145], v[178:179], 0, s[100:101]
	s_waitcnt lgkmcnt(0)
	s_barrier
	v_lshl_add_u64 v[224:225], v[180:181], 0, s[14:15]
	s_add_u32 s100, s14, 0x20000
	s_addc_u32 s101, s15, 0
	v_lshl_add_u64 v[226:227], v[180:181], 0, s[100:101]
	s_add_u32 s100, s100, 0x20000
	s_addc_u32 s101, s101, 0
	v_lshl_add_u64 v[228:229], v[180:181], 0, s[100:101]
	s_add_u32 s100, s100, 0x20000
	s_addc_u32 s101, s101, 0
	v_lshl_add_u64 v[230:231], v[180:181], 0, s[100:101]
	global_load_dwordx4 v[174:177], v[130:131], off
	global_load_dwordx4 v[170:173], v[132:133], off
	global_load_dwordx4 v[166:169], v[134:135], off
	global_load_dwordx4 v[162:165], v[136:137], off
	global_load_dwordx4 v[158:161], v[138:139], off
	global_load_dwordx4 v[154:157], v[140:141], off
	global_load_dwordx4 v[150:153], v[142:143], off
	global_load_dwordx4 v[146:149], v[144:145], off
	global_load_dwordx4 v[142:145], v[224:225], off
	global_load_dwordx4 v[134:137], v[226:227], off
	global_load_dwordx4 v[130:133], v[228:229], off
	global_load_dwordx4 v[138:141], v[230:231], off
	s_setprio 2
	ds_read_b128 v[224:227], v182
	ds_read_b128 v[228:231], v183 offset:36864
	ds_read_b128 v[232:235], v183 offset:41472
	ds_read_b128 v[184:187], v182 offset:4608
	ds_read_b128 v[236:239], v183 offset:46080
	ds_read_b128 v[240:243], v183 offset:50688
	s_waitcnt lgkmcnt(4)
	v_mfma_f32_32x32x16_bf16 v[114:129], v[224:227], v[228:231], v[114:129]
	ds_read_b128 v[188:191], v183 offset:36896
	ds_read_b128 v[192:195], v183 offset:41504
	s_waitcnt lgkmcnt(5)
	v_mfma_f32_32x32x16_bf16 v[82:97], v[224:227], v[232:235], v[82:97]
	ds_read_b128 v[196:199], v183 offset:46112
	ds_read_b128 v[200:203], v183 offset:50720
	s_waitcnt lgkmcnt(5)
	v_mfma_f32_32x32x16_bf16 v[98:113], v[224:227], v[236:239], v[98:113]
	s_waitcnt lgkmcnt(4)
	v_mfma_f32_32x32x16_bf16 v[66:81], v[224:227], v[240:243], v[66:81]
	ds_read_b128 v[224:227], v182 offset:32
	v_mfma_f32_32x32x16_bf16 v[50:65], v[184:187], v[228:231], v[50:65]
	v_mfma_f32_32x32x16_bf16 v[16:31], v[184:187], v[232:235], v[16:31]
	v_mfma_f32_32x32x16_bf16 v[34:49], v[184:187], v[236:239], v[34:49]
	v_mfma_f32_32x32x16_bf16 v[0:15], v[184:187], v[240:243], v[0:15]
	ds_read_b128 v[184:187], v182 offset:4640
	s_waitcnt lgkmcnt(1)
	v_mfma_f32_32x32x16_bf16 v[114:129], v[224:227], v[188:191], v[114:129]
	ds_read_b128 v[228:231], v183 offset:36928
	ds_read_b128 v[232:235], v183 offset:41536
	v_mfma_f32_32x32x16_bf16 v[82:97], v[224:227], v[192:195], v[82:97]
	ds_read_b128 v[236:239], v183 offset:46144
	ds_read_b128 v[240:243], v183 offset:50752
	v_mfma_f32_32x32x16_bf16 v[98:113], v[224:227], v[196:199], v[98:113]
	v_mfma_f32_32x32x16_bf16 v[66:81], v[224:227], v[200:203], v[66:81]
	ds_read_b128 v[224:227], v182 offset:64
	s_waitcnt lgkmcnt(5)
	v_mfma_f32_32x32x16_bf16 v[50:65], v[184:187], v[188:191], v[50:65]
	v_mfma_f32_32x32x16_bf16 v[16:31], v[184:187], v[192:195], v[16:31]
	v_mfma_f32_32x32x16_bf16 v[34:49], v[184:187], v[196:199], v[34:49]
	v_mfma_f32_32x32x16_bf16 v[0:15], v[184:187], v[200:203], v[0:15]
	ds_read_b128 v[184:187], v182 offset:4672
	s_waitcnt lgkmcnt(1)
	v_mfma_f32_32x32x16_bf16 v[114:129], v[224:227], v[228:231], v[114:129]
	ds_read_b128 v[188:191], v183 offset:36960
	ds_read_b128 v[192:195], v183 offset:41568
	v_mfma_f32_32x32x16_bf16 v[82:97], v[224:227], v[232:235], v[82:97]
	ds_read_b128 v[196:199], v183 offset:46176
	ds_read_b128 v[200:203], v183 offset:50784
	v_mfma_f32_32x32x16_bf16 v[98:113], v[224:227], v[236:239], v[98:113]
	v_mfma_f32_32x32x16_bf16 v[66:81], v[224:227], v[240:243], v[66:81]
	ds_read_b128 v[224:227], v182 offset:96
	s_waitcnt lgkmcnt(5)
	v_mfma_f32_32x32x16_bf16 v[50:65], v[184:187], v[228:231], v[50:65]
	v_mfma_f32_32x32x16_bf16 v[16:31], v[184:187], v[232:235], v[16:31]
	v_mfma_f32_32x32x16_bf16 v[34:49], v[184:187], v[236:239], v[34:49]
	v_mfma_f32_32x32x16_bf16 v[0:15], v[184:187], v[240:243], v[0:15]
	ds_read_b128 v[184:187], v182 offset:4704
	s_waitcnt lgkmcnt(1)
	v_mfma_f32_32x32x16_bf16 v[114:129], v[224:227], v[188:191], v[114:129]
	v_mfma_f32_32x32x16_bf16 v[82:97], v[224:227], v[192:195], v[82:97]
	v_mfma_f32_32x32x16_bf16 v[98:113], v[224:227], v[196:199], v[98:113]
	v_mfma_f32_32x32x16_bf16 v[66:81], v[224:227], v[200:203], v[66:81]
	s_waitcnt lgkmcnt(0)
	v_mfma_f32_32x32x16_bf16 v[50:65], v[184:187], v[188:191], v[50:65]
	v_mfma_f32_32x32x16_bf16 v[16:31], v[184:187], v[192:195], v[16:31]
	v_mfma_f32_32x32x16_bf16 v[34:49], v[184:187], v[196:199], v[34:49]
	v_mfma_f32_32x32x16_bf16 v[0:15], v[184:187], v[200:203], v[0:15]
	s_setprio 0
	s_mov_b32 s3, s7
	s_cmp_lg_u32 s7, 32
	s_cbranch_scc1 .LBB0_1696
	s_lshl_b32 s3, s6, 7
	s_lshr_b32 s6, s13, 24
	s_add_i32 s6, s12, s6
	s_lshr_b32 s6, s6, 8
	s_add_i32 s6, s6, s10
	v_mov_b32_e32 v32, v206
	s_barrier
	s_mulk_i32 s6, 0x1800
	s_ashr_i32 s7, s6, 31
	s_waitcnt vmcnt(1)
	v_and_b32_e32 v131, 0xffffffc0, v32
	v_lshrrev_b32_e32 v132, 3, v32
	v_readlane_b32 s36, v248, 46
	v_and_or_b32 v130, v32, 31, s3
	v_and_or_b32 v32, v132, 4, v131
	s_lshl_b64 s[6:7], s[6:7], 2
	v_readlane_b32 s40, v248, 50
	v_lshl_add_u32 v132, s2, 8, v32
	v_readlane_b32 s41, v248, 51
	s_add_u32 s6, s40, s6
	v_ashrrev_i32_e32 v133, 31, v132
	s_addc_u32 s7, s41, s7
	v_ashrrev_i32_e32 v131, 31, v130
	v_lshlrev_b64 v[136:137], 10, v[132:133]
	s_add_u32 s6, s6, 0x2000
	v_lshl_add_u64 v[136:137], v[136:137], 0, v[130:131]
	s_addc_u32 s7, s7, 0
	s_waitcnt vmcnt(0)
	v_lshlrev_b64 v[138:139], 2, v[136:137]
	v_lshl_add_u64 v[134:135], v[130:131], 2, s[6:7]
	v_lshl_add_u64 v[136:137], s[0:1], 0, v[138:139]
	v_readlane_b32 s48, v248, 58
	v_readlane_b32 s49, v248, 59
	v_writelane_b32 v251, s16, 29
	v_readlane_b32 s37, v248, 47
	v_readlane_b32 s38, v248, 48
	v_writelane_b32 v251, s17, 30
	v_readlane_b32 s39, v248, 49
	v_readlane_b32 s2, v251, 24
	s_add_i32 s11, s11, s2
	s_cmpk_lt_i32 s11, 0x200
	v_readlane_b32 s42, v248, 52
	v_readlane_b32 s43, v248, 53
	v_readlane_b32 s44, v248, 54
	v_readlane_b32 s45, v248, 55
	v_readlane_b32 s46, v248, 56
	v_readlane_b32 s47, v248, 57
	v_readlane_b32 s50, v248, 60
	v_readlane_b32 s51, v248, 61
	v_readlane_b32 s3, v251, 25
	s_waitcnt vmcnt(0)
	v_lshlrev_b32_e32 v240, 2, v130
	v_lshl_add_u32 v240, v132, 12, v240
	s_nop 2
	global_load_dword v241, v[134:135], off
	global_load_dword v242, v[134:135], off offset:128
	global_load_dword v243, v[134:135], off offset:256
	global_load_dword v151, v[134:135], off offset:384
	v_mov_b32_e32 v232, v240
	v_add_u32_e32 v233, 0x1000, v240
	v_add_u32_e32 v234, 0x2000, v240
	v_add_u32_e32 v235, 0x3000, v240
	v_add_u32_e32 v236, 0x8000, v240
	v_add_u32_e32 v237, 0x9000, v240
	v_add_u32_e32 v238, 0xa000, v240
	v_add_u32_e32 v239, 0xb000, v240
	global_load_dword v138, v232, s[0:1]
	global_load_dword v139, v232, s[0:1] offset:128
	global_load_dword v140, v232, s[0:1] offset:256
	global_load_dword v141, v232, s[0:1] offset:384
	global_load_dword v142, v233, s[0:1]
	global_load_dword v143, v233, s[0:1] offset:128
	global_load_dword v144, v233, s[0:1] offset:256
	global_load_dword v145, v233, s[0:1] offset:384
	global_load_dword v146, v234, s[0:1]
	global_load_dword v147, v234, s[0:1] offset:128
	global_load_dword v152, v234, s[0:1] offset:256
	global_load_dword v153, v234, s[0:1] offset:384
	global_load_dword v154, v235, s[0:1]
	global_load_dword v155, v235, s[0:1] offset:128
	global_load_dword v156, v235, s[0:1] offset:256
	global_load_dword v157, v235, s[0:1] offset:384
	global_load_dword v158, v236, s[0:1]
	global_load_dword v159, v236, s[0:1] offset:128
	global_load_dword v160, v236, s[0:1] offset:256
	global_load_dword v161, v236, s[0:1] offset:384
	global_load_dword v162, v237, s[0:1]
	global_load_dword v163, v237, s[0:1] offset:128
	global_load_dword v164, v237, s[0:1] offset:256
	global_load_dword v165, v237, s[0:1] offset:384
	global_load_dword v166, v238, s[0:1]
	global_load_dword v167, v238, s[0:1] offset:128
	global_load_dword v168, v238, s[0:1] offset:256
	global_load_dword v169, v238, s[0:1] offset:384
	global_load_dword v170, v239, s[0:1]
	global_load_dword v171, v239, s[0:1] offset:128
	global_load_dword v172, v239, s[0:1] offset:256
	global_load_dword v173, v239, s[0:1] offset:384
	v_add_u32_e32 v130, 0x10000, v240
	v_add_u32_e32 v131, 0x11000, v240
	v_add_u32_e32 v132, 0x12000, v240
	v_add_u32_e32 v133, 0x13000, v240
	v_add_u32_e32 v134, 0x18000, v240
	v_add_u32_e32 v135, 0x19000, v240
	v_add_u32_e32 v136, 0x1a000, v240
	v_add_u32_e32 v137, 0x1b000, v240
	global_load_dword v174, v130, s[0:1]
	global_load_dword v175, v130, s[0:1] offset:128
	global_load_dword v176, v130, s[0:1] offset:256
	global_load_dword v177, v130, s[0:1] offset:384
	global_load_dword v184, v131, s[0:1]
	global_load_dword v185, v131, s[0:1] offset:128
	global_load_dword v186, v131, s[0:1] offset:256
	global_load_dword v187, v131, s[0:1] offset:384
	global_load_dword v188, v132, s[0:1]
	global_load_dword v189, v132, s[0:1] offset:128
	global_load_dword v190, v132, s[0:1] offset:256
	global_load_dword v191, v132, s[0:1] offset:384
	global_load_dword v192, v133, s[0:1]
	global_load_dword v193, v133, s[0:1] offset:128
	global_load_dword v194, v133, s[0:1] offset:256
	global_load_dword v195, v133, s[0:1] offset:384
	global_load_dword v196, v134, s[0:1]
	global_load_dword v197, v134, s[0:1] offset:128
	global_load_dword v198, v134, s[0:1] offset:256
	global_load_dword v199, v134, s[0:1] offset:384
	global_load_dword v200, v135, s[0:1]
	global_load_dword v201, v135, s[0:1] offset:128
	global_load_dword v202, v135, s[0:1] offset:256
	global_load_dword v203, v135, s[0:1] offset:384
	global_load_dword v224, v136, s[0:1]
	global_load_dword v225, v136, s[0:1] offset:128
	global_load_dword v226, v136, s[0:1] offset:256
	global_load_dword v227, v136, s[0:1] offset:384
	global_load_dword v228, v137, s[0:1]
	global_load_dword v229, v137, s[0:1] offset:128
	global_load_dword v230, v137, s[0:1] offset:256
	global_load_dword v231, v137, s[0:1] offset:384
	s_waitcnt vmcnt(32)
	v_mul_f32_e32 v138, 0x3fd744fd, v138
	v_mul_f32_e32 v139, 0x3fd744fd, v139
	v_mul_f32_e32 v140, 0x3fd744fd, v140
	v_mul_f32_e32 v141, 0x3fd744fd, v141
	v_mul_f32_e32 v142, 0x3fd744fd, v142
	v_mul_f32_e32 v143, 0x3fd744fd, v143
	v_mul_f32_e32 v144, 0x3fd744fd, v144
	v_mul_f32_e32 v145, 0x3fd744fd, v145
	v_mul_f32_e32 v146, 0x3fd744fd, v146
	v_mul_f32_e32 v147, 0x3fd744fd, v147
	v_mul_f32_e32 v152, 0x3fd744fd, v152
	v_mul_f32_e32 v153, 0x3fd744fd, v153
	v_mul_f32_e32 v154, 0x3fd744fd, v154
	v_mul_f32_e32 v155, 0x3fd744fd, v155
	v_mul_f32_e32 v156, 0x3fd744fd, v156
	v_mul_f32_e32 v157, 0x3fd744fd, v157
	v_mul_f32_e32 v158, 0x3fd744fd, v158
	v_mul_f32_e32 v159, 0x3fd744fd, v159
	v_mul_f32_e32 v160, 0x3fd744fd, v160
	v_mul_f32_e32 v161, 0x3fd744fd, v161
	v_mul_f32_e32 v162, 0x3fd744fd, v162
	v_mul_f32_e32 v163, 0x3fd744fd, v163
	v_mul_f32_e32 v164, 0x3fd744fd, v164
	v_mul_f32_e32 v165, 0x3fd744fd, v165
	v_mul_f32_e32 v166, 0x3fd744fd, v166
	v_mul_f32_e32 v167, 0x3fd744fd, v167
	v_mul_f32_e32 v168, 0x3fd744fd, v168
	v_mul_f32_e32 v169, 0x3fd744fd, v169
	v_mul_f32_e32 v170, 0x3fd744fd, v170
	v_mul_f32_e32 v171, 0x3fd744fd, v171
	v_mul_f32_e32 v172, 0x3fd744fd, v172
	v_mul_f32_e32 v173, 0x3fd744fd, v173
	v_fmac_f32_e32 v138, v114, v241
	v_fmac_f32_e32 v139, v82, v242
	v_fmac_f32_e32 v140, v98, v243
	v_fmac_f32_e32 v141, v66, v151
	v_fmac_f32_e32 v142, v115, v241
	v_fmac_f32_e32 v143, v83, v242
	v_fmac_f32_e32 v144, v99, v243
	v_fmac_f32_e32 v145, v67, v151
	v_fmac_f32_e32 v146, v116, v241
	v_fmac_f32_e32 v147, v84, v242
	v_fmac_f32_e32 v152, v100, v243
	v_fmac_f32_e32 v153, v68, v151
	v_fmac_f32_e32 v154, v117, v241
	v_fmac_f32_e32 v155, v85, v242
	v_fmac_f32_e32 v156, v101, v243
	v_fmac_f32_e32 v157, v69, v151
	v_fmac_f32_e32 v158, v118, v241
	v_fmac_f32_e32 v159, v86, v242
	v_fmac_f32_e32 v160, v102, v243
	v_fmac_f32_e32 v161, v70, v151
	v_fmac_f32_e32 v162, v119, v241
	v_fmac_f32_e32 v163, v87, v242
	v_fmac_f32_e32 v164, v103, v243
	v_fmac_f32_e32 v165, v71, v151
	v_fmac_f32_e32 v166, v120, v241
	v_fmac_f32_e32 v167, v88, v242
	v_fmac_f32_e32 v168, v104, v243
	v_fmac_f32_e32 v169, v72, v151
	v_fmac_f32_e32 v170, v121, v241
	v_fmac_f32_e32 v171, v89, v242
	v_fmac_f32_e32 v172, v105, v243
	v_fmac_f32_e32 v173, v73, v151
	global_store_dword v232, v138, s[48:49]
	global_store_dword v232, v139, s[48:49] offset:128
	global_store_dword v232, v140, s[48:49] offset:256
	global_store_dword v232, v141, s[48:49] offset:384
	global_store_dword v233, v142, s[48:49]
	global_store_dword v233, v143, s[48:49] offset:128
	global_store_dword v233, v144, s[48:49] offset:256
	global_store_dword v233, v145, s[48:49] offset:384
	global_store_dword v234, v146, s[48:49]
	global_store_dword v234, v147, s[48:49] offset:128
	global_store_dword v234, v152, s[48:49] offset:256
	global_store_dword v234, v153, s[48:49] offset:384
	global_store_dword v235, v154, s[48:49]
	global_store_dword v235, v155, s[48:49] offset:128
	global_store_dword v235, v156, s[48:49] offset:256
	global_store_dword v235, v157, s[48:49] offset:384
	global_store_dword v236, v158, s[48:49]
	global_store_dword v236, v159, s[48:49] offset:128
	global_store_dword v236, v160, s[48:49] offset:256
	global_store_dword v236, v161, s[48:49] offset:384
	global_store_dword v237, v162, s[48:49]
	global_store_dword v237, v163, s[48:49] offset:128
	global_store_dword v237, v164, s[48:49] offset:256
	global_store_dword v237, v165, s[48:49] offset:384
	global_store_dword v238, v166, s[48:49]
	global_store_dword v238, v167, s[48:49] offset:128
	global_store_dword v238, v168, s[48:49] offset:256
	global_store_dword v238, v169, s[48:49] offset:384
	global_store_dword v239, v170, s[48:49]
	global_store_dword v239, v171, s[48:49] offset:128
	global_store_dword v239, v172, s[48:49] offset:256
	global_store_dword v239, v173, s[48:49] offset:384
	v_add_u32_e32 v232, 0x20000, v240
	v_add_u32_e32 v233, 0x21000, v240
	v_add_u32_e32 v234, 0x22000, v240
	v_add_u32_e32 v235, 0x23000, v240
	v_add_u32_e32 v236, 0x28000, v240
	v_add_u32_e32 v237, 0x29000, v240
	v_add_u32_e32 v238, 0x2a000, v240
	v_add_u32_e32 v239, 0x2b000, v240
	global_load_dword v138, v232, s[0:1]
	global_load_dword v139, v232, s[0:1] offset:128
	global_load_dword v140, v232, s[0:1] offset:256
	global_load_dword v141, v232, s[0:1] offset:384
	global_load_dword v142, v233, s[0:1]
	global_load_dword v143, v233, s[0:1] offset:128
	global_load_dword v144, v233, s[0:1] offset:256
	global_load_dword v145, v233, s[0:1] offset:384
	global_load_dword v146, v234, s[0:1]
	global_load_dword v147, v234, s[0:1] offset:128
	global_load_dword v152, v234, s[0:1] offset:256
	global_load_dword v153, v234, s[0:1] offset:384
	global_load_dword v154, v235, s[0:1]
	global_load_dword v155, v235, s[0:1] offset:128
	global_load_dword v156, v235, s[0:1] offset:256
	global_load_dword v157, v235, s[0:1] offset:384
	global_load_dword v158, v236, s[0:1]
	global_load_dword v159, v236, s[0:1] offset:128
	global_load_dword v160, v236, s[0:1] offset:256
	global_load_dword v161, v236, s[0:1] offset:384
	global_load_dword v162, v237, s[0:1]
	global_load_dword v163, v237, s[0:1] offset:128
	global_load_dword v164, v237, s[0:1] offset:256
	global_load_dword v165, v237, s[0:1] offset:384
	global_load_dword v166, v238, s[0:1]
	global_load_dword v167, v238, s[0:1] offset:128
	global_load_dword v168, v238, s[0:1] offset:256
	global_load_dword v169, v238, s[0:1] offset:384
	global_load_dword v170, v239, s[0:1]
	global_load_dword v171, v239, s[0:1] offset:128
	global_load_dword v172, v239, s[0:1] offset:256
	global_load_dword v173, v239, s[0:1] offset:384
	s_waitcnt vmcnt(63)
	v_mul_f32_e32 v174, 0x3fd744fd, v174
	v_mul_f32_e32 v175, 0x3fd744fd, v175
	v_mul_f32_e32 v176, 0x3fd744fd, v176
	v_mul_f32_e32 v177, 0x3fd744fd, v177
	v_mul_f32_e32 v184, 0x3fd744fd, v184
	v_mul_f32_e32 v185, 0x3fd744fd, v185
	v_mul_f32_e32 v186, 0x3fd744fd, v186
	v_mul_f32_e32 v187, 0x3fd744fd, v187
	v_mul_f32_e32 v188, 0x3fd744fd, v188
	v_mul_f32_e32 v189, 0x3fd744fd, v189
	v_mul_f32_e32 v190, 0x3fd744fd, v190
	v_mul_f32_e32 v191, 0x3fd744fd, v191
	v_mul_f32_e32 v192, 0x3fd744fd, v192
	v_mul_f32_e32 v193, 0x3fd744fd, v193
	v_mul_f32_e32 v194, 0x3fd744fd, v194
	v_mul_f32_e32 v195, 0x3fd744fd, v195
	v_mul_f32_e32 v196, 0x3fd744fd, v196
	v_mul_f32_e32 v197, 0x3fd744fd, v197
	v_mul_f32_e32 v198, 0x3fd744fd, v198
	v_mul_f32_e32 v199, 0x3fd744fd, v199
	v_mul_f32_e32 v200, 0x3fd744fd, v200
	v_mul_f32_e32 v201, 0x3fd744fd, v201
	v_mul_f32_e32 v202, 0x3fd744fd, v202
	v_mul_f32_e32 v203, 0x3fd744fd, v203
	v_mul_f32_e32 v224, 0x3fd744fd, v224
	v_mul_f32_e32 v225, 0x3fd744fd, v225
	v_mul_f32_e32 v226, 0x3fd744fd, v226
	v_mul_f32_e32 v227, 0x3fd744fd, v227
	v_mul_f32_e32 v228, 0x3fd744fd, v228
	v_mul_f32_e32 v229, 0x3fd744fd, v229
	v_mul_f32_e32 v230, 0x3fd744fd, v230
	v_mul_f32_e32 v231, 0x3fd744fd, v231
	v_fmac_f32_e32 v174, v122, v241
	v_fmac_f32_e32 v175, v90, v242
	v_fmac_f32_e32 v176, v106, v243
	v_fmac_f32_e32 v177, v74, v151
	v_fmac_f32_e32 v184, v123, v241
	v_fmac_f32_e32 v185, v91, v242
	v_fmac_f32_e32 v186, v107, v243
	v_fmac_f32_e32 v187, v75, v151
	v_fmac_f32_e32 v188, v124, v241
	v_fmac_f32_e32 v189, v92, v242
	v_fmac_f32_e32 v190, v108, v243
	v_fmac_f32_e32 v191, v76, v151
	v_fmac_f32_e32 v192, v125, v241
	v_fmac_f32_e32 v193, v93, v242
	v_fmac_f32_e32 v194, v109, v243
	v_fmac_f32_e32 v195, v77, v151
	v_fmac_f32_e32 v196, v126, v241
	v_fmac_f32_e32 v197, v94, v242
	v_fmac_f32_e32 v198, v110, v243
	v_fmac_f32_e32 v199, v78, v151
	v_fmac_f32_e32 v200, v127, v241
	v_fmac_f32_e32 v201, v95, v242
	v_fmac_f32_e32 v202, v111, v243
	v_fmac_f32_e32 v203, v79, v151
	v_fmac_f32_e32 v224, v128, v241
	v_fmac_f32_e32 v225, v96, v242
	v_fmac_f32_e32 v226, v112, v243
	v_fmac_f32_e32 v227, v80, v151
	v_fmac_f32_e32 v228, v129, v241
	v_fmac_f32_e32 v229, v97, v242
	v_fmac_f32_e32 v230, v113, v243
	v_fmac_f32_e32 v231, v81, v151
	global_store_dword v130, v174, s[48:49]
	global_store_dword v130, v175, s[48:49] offset:128
	global_store_dword v130, v176, s[48:49] offset:256
	global_store_dword v130, v177, s[48:49] offset:384
	global_store_dword v131, v184, s[48:49]
	global_store_dword v131, v185, s[48:49] offset:128
	global_store_dword v131, v186, s[48:49] offset:256
	global_store_dword v131, v187, s[48:49] offset:384
	global_store_dword v132, v188, s[48:49]
	global_store_dword v132, v189, s[48:49] offset:128
	global_store_dword v132, v190, s[48:49] offset:256
	global_store_dword v132, v191, s[48:49] offset:384
	global_store_dword v133, v192, s[48:49]
	global_store_dword v133, v193, s[48:49] offset:128
	global_store_dword v133, v194, s[48:49] offset:256
	global_store_dword v133, v195, s[48:49] offset:384
	global_store_dword v134, v196, s[48:49]
	global_store_dword v134, v197, s[48:49] offset:128
	global_store_dword v134, v198, s[48:49] offset:256
	global_store_dword v134, v199, s[48:49] offset:384
	global_store_dword v135, v200, s[48:49]
	global_store_dword v135, v201, s[48:49] offset:128
	global_store_dword v135, v202, s[48:49] offset:256
	global_store_dword v135, v203, s[48:49] offset:384
	global_store_dword v136, v224, s[48:49]
	global_store_dword v136, v225, s[48:49] offset:128
	global_store_dword v136, v226, s[48:49] offset:256
	global_store_dword v136, v227, s[48:49] offset:384
	global_store_dword v137, v228, s[48:49]
	global_store_dword v137, v229, s[48:49] offset:128
	global_store_dword v137, v230, s[48:49] offset:256
	global_store_dword v137, v231, s[48:49] offset:384
	v_add_u32_e32 v130, 0x30000, v240
	v_add_u32_e32 v131, 0x31000, v240
	v_add_u32_e32 v132, 0x32000, v240
	v_add_u32_e32 v133, 0x33000, v240
	v_add_u32_e32 v134, 0x38000, v240
	v_add_u32_e32 v135, 0x39000, v240
	v_add_u32_e32 v136, 0x3a000, v240
	v_add_u32_e32 v137, 0x3b000, v240
	global_load_dword v174, v130, s[0:1]
	global_load_dword v175, v130, s[0:1] offset:128
	global_load_dword v176, v130, s[0:1] offset:256
	global_load_dword v177, v130, s[0:1] offset:384
	global_load_dword v184, v131, s[0:1]
	global_load_dword v185, v131, s[0:1] offset:128
	global_load_dword v186, v131, s[0:1] offset:256
	global_load_dword v187, v131, s[0:1] offset:384
	global_load_dword v188, v132, s[0:1]
	global_load_dword v189, v132, s[0:1] offset:128
	global_load_dword v190, v132, s[0:1] offset:256
	global_load_dword v191, v132, s[0:1] offset:384
	global_load_dword v192, v133, s[0:1]
	global_load_dword v193, v133, s[0:1] offset:128
	global_load_dword v194, v133, s[0:1] offset:256
	global_load_dword v195, v133, s[0:1] offset:384
	global_load_dword v196, v134, s[0:1]
	global_load_dword v197, v134, s[0:1] offset:128
	global_load_dword v198, v134, s[0:1] offset:256
	global_load_dword v199, v134, s[0:1] offset:384
	global_load_dword v200, v135, s[0:1]
	global_load_dword v201, v135, s[0:1] offset:128
	global_load_dword v202, v135, s[0:1] offset:256
	global_load_dword v203, v135, s[0:1] offset:384
	global_load_dword v224, v136, s[0:1]
	global_load_dword v225, v136, s[0:1] offset:128
	global_load_dword v226, v136, s[0:1] offset:256
	global_load_dword v227, v136, s[0:1] offset:384
	global_load_dword v228, v137, s[0:1]
	global_load_dword v229, v137, s[0:1] offset:128
	global_load_dword v230, v137, s[0:1] offset:256
	global_load_dword v231, v137, s[0:1] offset:384
	s_waitcnt vmcnt(63)
	v_mul_f32_e32 v138, 0x3fd744fd, v138
	v_mul_f32_e32 v139, 0x3fd744fd, v139
	v_mul_f32_e32 v140, 0x3fd744fd, v140
	v_mul_f32_e32 v141, 0x3fd744fd, v141
	v_mul_f32_e32 v142, 0x3fd744fd, v142
	v_mul_f32_e32 v143, 0x3fd744fd, v143
	v_mul_f32_e32 v144, 0x3fd744fd, v144
	v_mul_f32_e32 v145, 0x3fd744fd, v145
	v_mul_f32_e32 v146, 0x3fd744fd, v146
	v_mul_f32_e32 v147, 0x3fd744fd, v147
	v_mul_f32_e32 v152, 0x3fd744fd, v152
	v_mul_f32_e32 v153, 0x3fd744fd, v153
	v_mul_f32_e32 v154, 0x3fd744fd, v154
	v_mul_f32_e32 v155, 0x3fd744fd, v155
	v_mul_f32_e32 v156, 0x3fd744fd, v156
	v_mul_f32_e32 v157, 0x3fd744fd, v157
	v_mul_f32_e32 v158, 0x3fd744fd, v158
	v_mul_f32_e32 v159, 0x3fd744fd, v159
	v_mul_f32_e32 v160, 0x3fd744fd, v160
	v_mul_f32_e32 v161, 0x3fd744fd, v161
	v_mul_f32_e32 v162, 0x3fd744fd, v162
	v_mul_f32_e32 v163, 0x3fd744fd, v163
	v_mul_f32_e32 v164, 0x3fd744fd, v164
	v_mul_f32_e32 v165, 0x3fd744fd, v165
	v_mul_f32_e32 v166, 0x3fd744fd, v166
	v_mul_f32_e32 v167, 0x3fd744fd, v167
	v_mul_f32_e32 v168, 0x3fd744fd, v168
	v_mul_f32_e32 v169, 0x3fd744fd, v169
	v_mul_f32_e32 v170, 0x3fd744fd, v170
	v_mul_f32_e32 v171, 0x3fd744fd, v171
	v_mul_f32_e32 v172, 0x3fd744fd, v172
	v_mul_f32_e32 v173, 0x3fd744fd, v173
	v_fmac_f32_e32 v138, v50, v241
	v_fmac_f32_e32 v139, v16, v242
	v_fmac_f32_e32 v140, v34, v243
	v_fmac_f32_e32 v141, v0, v151
	v_fmac_f32_e32 v142, v51, v241
	v_fmac_f32_e32 v143, v17, v242
	v_fmac_f32_e32 v144, v35, v243
	v_fmac_f32_e32 v145, v1, v151
	v_fmac_f32_e32 v146, v52, v241
	v_fmac_f32_e32 v147, v18, v242
	v_fmac_f32_e32 v152, v36, v243
	v_fmac_f32_e32 v153, v2, v151
	v_fmac_f32_e32 v154, v53, v241
	v_fmac_f32_e32 v155, v19, v242
	v_fmac_f32_e32 v156, v37, v243
	v_fmac_f32_e32 v157, v3, v151
	v_fmac_f32_e32 v158, v54, v241
	v_fmac_f32_e32 v159, v20, v242
	v_fmac_f32_e32 v160, v38, v243
	v_fmac_f32_e32 v161, v4, v151
	v_fmac_f32_e32 v162, v55, v241
	v_fmac_f32_e32 v163, v21, v242
	v_fmac_f32_e32 v164, v39, v243
	v_fmac_f32_e32 v165, v5, v151
	v_fmac_f32_e32 v166, v56, v241
	v_fmac_f32_e32 v167, v22, v242
	v_fmac_f32_e32 v168, v40, v243
	v_fmac_f32_e32 v169, v6, v151
	v_fmac_f32_e32 v170, v57, v241
	v_fmac_f32_e32 v171, v23, v242
	v_fmac_f32_e32 v172, v41, v243
	v_fmac_f32_e32 v173, v7, v151
	global_store_dword v232, v138, s[48:49]
	global_store_dword v232, v139, s[48:49] offset:128
	global_store_dword v232, v140, s[48:49] offset:256
	global_store_dword v232, v141, s[48:49] offset:384
	global_store_dword v233, v142, s[48:49]
	global_store_dword v233, v143, s[48:49] offset:128
	global_store_dword v233, v144, s[48:49] offset:256
	global_store_dword v233, v145, s[48:49] offset:384
	global_store_dword v234, v146, s[48:49]
	global_store_dword v234, v147, s[48:49] offset:128
	global_store_dword v234, v152, s[48:49] offset:256
	global_store_dword v234, v153, s[48:49] offset:384
	global_store_dword v235, v154, s[48:49]
	global_store_dword v235, v155, s[48:49] offset:128
	global_store_dword v235, v156, s[48:49] offset:256
	global_store_dword v235, v157, s[48:49] offset:384
	global_store_dword v236, v158, s[48:49]
	global_store_dword v236, v159, s[48:49] offset:128
	global_store_dword v236, v160, s[48:49] offset:256
	global_store_dword v236, v161, s[48:49] offset:384
	global_store_dword v237, v162, s[48:49]
	global_store_dword v237, v163, s[48:49] offset:128
	global_store_dword v237, v164, s[48:49] offset:256
	global_store_dword v237, v165, s[48:49] offset:384
	global_store_dword v238, v166, s[48:49]
	global_store_dword v238, v167, s[48:49] offset:128
	global_store_dword v238, v168, s[48:49] offset:256
	global_store_dword v238, v169, s[48:49] offset:384
	global_store_dword v239, v170, s[48:49]
	global_store_dword v239, v171, s[48:49] offset:128
	global_store_dword v239, v172, s[48:49] offset:256
	global_store_dword v239, v173, s[48:49] offset:384
	s_waitcnt vmcnt(32)
	v_mul_f32_e32 v174, 0x3fd744fd, v174
	v_mul_f32_e32 v175, 0x3fd744fd, v175
	v_mul_f32_e32 v176, 0x3fd744fd, v176
	v_mul_f32_e32 v177, 0x3fd744fd, v177
	v_mul_f32_e32 v184, 0x3fd744fd, v184
	v_mul_f32_e32 v185, 0x3fd744fd, v185
	v_mul_f32_e32 v186, 0x3fd744fd, v186
	v_mul_f32_e32 v187, 0x3fd744fd, v187
	v_mul_f32_e32 v188, 0x3fd744fd, v188
	v_mul_f32_e32 v189, 0x3fd744fd, v189
	v_mul_f32_e32 v190, 0x3fd744fd, v190
	v_mul_f32_e32 v191, 0x3fd744fd, v191
	v_mul_f32_e32 v192, 0x3fd744fd, v192
	v_mul_f32_e32 v193, 0x3fd744fd, v193
	v_mul_f32_e32 v194, 0x3fd744fd, v194
	v_mul_f32_e32 v195, 0x3fd744fd, v195
	v_mul_f32_e32 v196, 0x3fd744fd, v196
	v_mul_f32_e32 v197, 0x3fd744fd, v197
	v_mul_f32_e32 v198, 0x3fd744fd, v198
	v_mul_f32_e32 v199, 0x3fd744fd, v199
	v_mul_f32_e32 v200, 0x3fd744fd, v200
	v_mul_f32_e32 v201, 0x3fd744fd, v201
	v_mul_f32_e32 v202, 0x3fd744fd, v202
	v_mul_f32_e32 v203, 0x3fd744fd, v203
	v_mul_f32_e32 v224, 0x3fd744fd, v224
	v_mul_f32_e32 v225, 0x3fd744fd, v225
	v_mul_f32_e32 v226, 0x3fd744fd, v226
	v_mul_f32_e32 v227, 0x3fd744fd, v227
	v_mul_f32_e32 v228, 0x3fd744fd, v228
	v_mul_f32_e32 v229, 0x3fd744fd, v229
	v_mul_f32_e32 v230, 0x3fd744fd, v230
	v_mul_f32_e32 v231, 0x3fd744fd, v231
	v_fmac_f32_e32 v174, v58, v241
	v_fmac_f32_e32 v175, v24, v242
	v_fmac_f32_e32 v176, v42, v243
	v_fmac_f32_e32 v177, v8, v151
	v_fmac_f32_e32 v184, v59, v241
	v_fmac_f32_e32 v185, v25, v242
	v_fmac_f32_e32 v186, v43, v243
	v_fmac_f32_e32 v187, v9, v151
	v_fmac_f32_e32 v188, v60, v241
	v_fmac_f32_e32 v189, v26, v242
	v_fmac_f32_e32 v190, v44, v243
	v_fmac_f32_e32 v191, v10, v151
	v_fmac_f32_e32 v192, v61, v241
	v_fmac_f32_e32 v193, v27, v242
	v_fmac_f32_e32 v194, v45, v243
	v_fmac_f32_e32 v195, v11, v151
	v_fmac_f32_e32 v196, v62, v241
	v_fmac_f32_e32 v197, v28, v242
	v_fmac_f32_e32 v198, v46, v243
	v_fmac_f32_e32 v199, v12, v151
	v_fmac_f32_e32 v200, v63, v241
	v_fmac_f32_e32 v201, v29, v242
	v_fmac_f32_e32 v202, v47, v243
	v_fmac_f32_e32 v203, v13, v151
	v_fmac_f32_e32 v224, v64, v241
	v_fmac_f32_e32 v225, v30, v242
	v_fmac_f32_e32 v226, v48, v243
	v_fmac_f32_e32 v227, v14, v151
	v_fmac_f32_e32 v228, v65, v241
	v_fmac_f32_e32 v229, v31, v242
	v_fmac_f32_e32 v230, v49, v243
	v_fmac_f32_e32 v231, v15, v151
	global_store_dword v130, v174, s[48:49]
	global_store_dword v130, v175, s[48:49] offset:128
	global_store_dword v130, v176, s[48:49] offset:256
	global_store_dword v130, v177, s[48:49] offset:384
	global_store_dword v131, v184, s[48:49]
	global_store_dword v131, v185, s[48:49] offset:128
	global_store_dword v131, v186, s[48:49] offset:256
	global_store_dword v131, v187, s[48:49] offset:384
	global_store_dword v132, v188, s[48:49]
	global_store_dword v132, v189, s[48:49] offset:128
	global_store_dword v132, v190, s[48:49] offset:256
	global_store_dword v132, v191, s[48:49] offset:384
	global_store_dword v133, v192, s[48:49]
	global_store_dword v133, v193, s[48:49] offset:128
	global_store_dword v133, v194, s[48:49] offset:256
	global_store_dword v133, v195, s[48:49] offset:384
	global_store_dword v134, v196, s[48:49]
	global_store_dword v134, v197, s[48:49] offset:128
	global_store_dword v134, v198, s[48:49] offset:256
	global_store_dword v134, v199, s[48:49] offset:384
	global_store_dword v135, v200, s[48:49]
	global_store_dword v135, v201, s[48:49] offset:128
	global_store_dword v135, v202, s[48:49] offset:256
	global_store_dword v135, v203, s[48:49] offset:384
	global_store_dword v136, v224, s[48:49]
	global_store_dword v136, v225, s[48:49] offset:128
	global_store_dword v136, v226, s[48:49] offset:256
	global_store_dword v136, v227, s[48:49] offset:384
	global_store_dword v137, v228, s[48:49]
	global_store_dword v137, v229, s[48:49] offset:128
	global_store_dword v137, v230, s[48:49] offset:256
	global_store_dword v137, v231, s[48:49] offset:384
	s_cbranch_scc1 .LBB0_1692

.LBB0_1851:
	s_setprio 2
	ds_read_b128 v[190:193], v189
	ds_read_b128 v[194:197], v164 offset:36864
	s_cmp_gt_u32 s3, 12
	s_waitcnt lgkmcnt(0)
	v_mfma_f32_32x32x16_bf16 v[0:15], v[190:193], v[194:197], v[0:15]
	ds_read_b128 v[190:193], v189 offset:4608
	s_waitcnt lgkmcnt(0)
	v_mfma_f32_32x32x16_bf16 v[16:31], v[190:193], v[194:197], v[16:31]
	ds_read_b128 v[190:193], v189 offset:9216
	s_waitcnt lgkmcnt(0)
	v_mfma_f32_32x32x16_bf16 v[34:49], v[190:193], v[194:197], v[34:49]
	ds_read_b128 v[190:193], v189 offset:13824
	s_waitcnt lgkmcnt(0)
	v_mfma_f32_32x32x16_bf16 v[50:65], v[190:193], v[194:197], v[50:65]
	ds_read_b128 v[190:193], v189 offset:32
	ds_read_b128 v[194:197], v164 offset:36896
	s_waitcnt lgkmcnt(0)
	v_mfma_f32_32x32x16_bf16 v[0:15], v[190:193], v[194:197], v[0:15]
	ds_read_b128 v[190:193], v189 offset:4640
	s_waitcnt lgkmcnt(0)
	v_mfma_f32_32x32x16_bf16 v[16:31], v[190:193], v[194:197], v[16:31]
	ds_read_b128 v[190:193], v189 offset:9248
	s_waitcnt lgkmcnt(0)
	v_mfma_f32_32x32x16_bf16 v[34:49], v[190:193], v[194:197], v[34:49]
	ds_read_b128 v[190:193], v189 offset:13856
	s_waitcnt lgkmcnt(0)
	v_mfma_f32_32x32x16_bf16 v[50:65], v[190:193], v[194:197], v[50:65]
	ds_read_b128 v[190:193], v189 offset:64
	ds_read_b128 v[194:197], v164 offset:36928
	s_waitcnt lgkmcnt(0)
	v_mfma_f32_32x32x16_bf16 v[0:15], v[190:193], v[194:197], v[0:15]
	ds_read_b128 v[190:193], v189 offset:4672
	s_waitcnt lgkmcnt(0)
	v_mfma_f32_32x32x16_bf16 v[16:31], v[190:193], v[194:197], v[16:31]
	ds_read_b128 v[190:193], v189 offset:9280
	s_waitcnt lgkmcnt(0)
	v_mfma_f32_32x32x16_bf16 v[34:49], v[190:193], v[194:197], v[34:49]
	ds_read_b128 v[190:193], v189 offset:13888
	s_waitcnt lgkmcnt(0)
	v_mfma_f32_32x32x16_bf16 v[50:65], v[190:193], v[194:197], v[50:65]
	ds_read_b128 v[190:193], v189 offset:96
	ds_read_b128 v[194:197], v164 offset:36960
	s_waitcnt lgkmcnt(0)
	v_mfma_f32_32x32x16_bf16 v[0:15], v[190:193], v[194:197], v[0:15]
	ds_read_b128 v[190:193], v189 offset:4704
	s_waitcnt lgkmcnt(0)
	v_mfma_f32_32x32x16_bf16 v[16:31], v[190:193], v[194:197], v[16:31]
	s_setprio 0
	ds_read_b128 v[190:193], v189 offset:9312
	ds_read_b128 v[198:201], v189 offset:13920
	s_waitcnt vmcnt(7)
	ds_write_b128 v166, v[130:133] offset:18432
	s_waitcnt vmcnt(1)
	ds_write_b128 v166, v[138:141] offset:55296
	s_waitcnt vmcnt(5)
	ds_write_b128 v166, v[134:137] offset:23040
	s_waitcnt vmcnt(4)
	ds_write_b128 v166, v[146:149] offset:59904
	s_waitcnt vmcnt(3)
	ds_write_b128 v166, v[142:145] offset:27648
	s_waitcnt vmcnt(2)
	ds_write_b128 v166, v[150:153] offset:64512
	s_waitcnt vmcnt(1)
	ds_write_b128 v166, v[154:157] offset:32256
	s_waitcnt vmcnt(0)
	ds_write_b128 v165, v[158:161] offset:13824
	s_waitcnt lgkmcnt(0)
	s_barrier
	v_mfma_f32_32x32x16_bf16 v[34:49], v[190:193], v[194:197], v[34:49]
	v_mfma_f32_32x32x16_bf16 v[50:65], v[198:201], v[194:197], v[50:65]
	s_cbranch_scc1 .LBB0_1853
	v_add_co_u32_e32 v138, vcc, 0x10000, v180
	v_lshl_add_u64 v[130:131], v[168:169], 0, v[32:33]
	s_nop 0
	v_addc_co_u32_e32 v139, vcc, 0, v181, vcc
	v_add_co_u32_e32 v140, vcc, 0x20000, v180
	v_lshl_add_u64 v[134:135], v[170:171], 0, v[32:33]
	s_nop 0
	v_addc_co_u32_e32 v141, vcc, 0, v181, vcc
	v_add_co_u32_e32 v158, vcc, 0x30000, v180
	global_load_dwordx4 v[130:133], v[130:131], off
	s_nop 0
	v_addc_co_u32_e32 v159, vcc, 0, v181, vcc
	global_load_dwordx4 v[134:137], v[134:135], off
	s_nop 0
	global_load_dwordx4 v[142:145], v[184:185], off offset:128
	global_load_dwordx4 v[146:149], v[138:139], off offset:384
	global_load_dwordx4 v[150:153], v[140:141], off offset:384
	global_load_dwordx4 v[154:157], v[182:183], off
	s_nop 0
	global_load_dwordx4 v[138:141], v[180:181], off offset:384
	s_nop 0
	global_load_dwordx4 v[158:161], v[158:159], off offset:384
.LBB0_1853:
	s_setprio 2
	ds_read_b128 v[180:183], v189 offset:18432
	ds_read_b128 v[190:193], v164 offset:55296
	s_andn2_b64 vcc, exec, s[8:9]
	s_waitcnt lgkmcnt(0)
	v_mfma_f32_32x32x16_bf16 v[0:15], v[180:183], v[190:193], v[0:15]
	ds_read_b128 v[180:183], v189 offset:23040
	s_waitcnt lgkmcnt(0)
	v_mfma_f32_32x32x16_bf16 v[16:31], v[180:183], v[190:193], v[16:31]
	ds_read_b128 v[180:183], v189 offset:27648
	s_waitcnt lgkmcnt(0)
	v_mfma_f32_32x32x16_bf16 v[34:49], v[180:183], v[190:193], v[34:49]
	ds_read_b128 v[180:183], v189 offset:32256
	s_waitcnt lgkmcnt(0)
	v_mfma_f32_32x32x16_bf16 v[50:65], v[180:183], v[190:193], v[50:65]
	ds_read_b128 v[180:183], v189 offset:18464
	ds_read_b128 v[190:193], v164 offset:55328
	s_waitcnt lgkmcnt(0)
	v_mfma_f32_32x32x16_bf16 v[0:15], v[180:183], v[190:193], v[0:15]
	ds_read_b128 v[180:183], v189 offset:23072
	s_waitcnt lgkmcnt(0)
	v_mfma_f32_32x32x16_bf16 v[16:31], v[180:183], v[190:193], v[16:31]
	ds_read_b128 v[180:183], v189 offset:27680
	s_waitcnt lgkmcnt(0)
	v_mfma_f32_32x32x16_bf16 v[34:49], v[180:183], v[190:193], v[34:49]
	ds_read_b128 v[180:183], v189 offset:32288
	s_waitcnt lgkmcnt(0)
	v_mfma_f32_32x32x16_bf16 v[50:65], v[180:183], v[190:193], v[50:65]
	ds_read_b128 v[180:183], v189 offset:18496
	ds_read_b128 v[190:193], v164 offset:55360
	s_waitcnt lgkmcnt(0)
	v_mfma_f32_32x32x16_bf16 v[0:15], v[180:183], v[190:193], v[0:15]
	ds_read_b128 v[180:183], v189 offset:23104
	s_waitcnt lgkmcnt(0)
	v_mfma_f32_32x32x16_bf16 v[16:31], v[180:183], v[190:193], v[16:31]
	ds_read_b128 v[180:183], v189 offset:27712
	s_waitcnt lgkmcnt(0)
	v_mfma_f32_32x32x16_bf16 v[34:49], v[180:183], v[190:193], v[34:49]
	ds_read_b128 v[180:183], v189 offset:32320
	s_waitcnt lgkmcnt(0)
	v_mfma_f32_32x32x16_bf16 v[50:65], v[180:183], v[190:193], v[50:65]
	ds_read_b128 v[180:183], v189 offset:18528
	ds_read_b128 v[190:193], v164 offset:55392
	s_waitcnt lgkmcnt(0)
	v_mfma_f32_32x32x16_bf16 v[0:15], v[180:183], v[190:193], v[0:15]
	ds_read_b128 v[180:183], v189 offset:23136
	s_waitcnt lgkmcnt(0)
	v_mfma_f32_32x32x16_bf16 v[16:31], v[180:183], v[190:193], v[16:31]
	ds_read_b128 v[180:183], v189 offset:27744
	s_waitcnt lgkmcnt(0)
	v_mfma_f32_32x32x16_bf16 v[34:49], v[180:183], v[190:193], v[34:49]
	ds_read_b128 v[180:183], v189 offset:32352
	s_waitcnt lgkmcnt(0)
	v_mfma_f32_32x32x16_bf16 v[50:65], v[180:183], v[190:193], v[50:65]
	s_setprio 0
	s_cbranch_vccnz .LBB0_1848
	ds_write_b128 v166, v[66:69]
	ds_write_b128 v166, v[78:81] offset:36864
	ds_write_b128 v166, v[70:73] offset:4608
	ds_write_b128 v166, v[74:77] offset:41472
	ds_write_b128 v166, v[86:89] offset:9216
	ds_write_b128 v166, v[82:85] offset:46080
	ds_write_b128 v166, v[94:97] offset:13824
	ds_write_b128 v166, v[90:93] offset:50688
	s_branch .LBB0_1848

.LBB0_2049:
	s_setprio 2
	ds_read_b128 v[142:145], v134
	ds_read_b128 v[146:149], v135 offset:36864
	ds_read_b128 v[150:153], v135 offset:46080
	s_cmp_gt_u32 s1, 12
	s_waitcnt lgkmcnt(1)
	v_mfma_f32_32x32x16_bf16 v[34:49], v[142:145], v[146:149], v[34:49]
	s_waitcnt lgkmcnt(0)
	v_mfma_f32_32x32x16_bf16 v[50:65], v[142:145], v[150:153], v[50:65]
	ds_read_b128 v[142:145], v134 offset:4608
	s_waitcnt lgkmcnt(0)
	v_mfma_f32_32x32x16_bf16 v[16:31], v[142:145], v[146:149], v[16:31]
	v_mfma_f32_32x32x16_bf16 v[0:15], v[142:145], v[150:153], v[0:15]
	ds_read_b128 v[142:145], v134 offset:32
	ds_read_b128 v[146:149], v135 offset:36896
	ds_read_b128 v[150:153], v135 offset:46112
	s_waitcnt lgkmcnt(1)
	v_mfma_f32_32x32x16_bf16 v[34:49], v[142:145], v[146:149], v[34:49]
	s_waitcnt lgkmcnt(0)
	v_mfma_f32_32x32x16_bf16 v[50:65], v[142:145], v[150:153], v[50:65]
	ds_read_b128 v[142:145], v134 offset:4640
	s_waitcnt lgkmcnt(0)
	v_mfma_f32_32x32x16_bf16 v[16:31], v[142:145], v[146:149], v[16:31]
	v_mfma_f32_32x32x16_bf16 v[0:15], v[142:145], v[150:153], v[0:15]
	ds_read_b128 v[142:145], v134 offset:64
	ds_read_b128 v[146:149], v135 offset:36928
	ds_read_b128 v[150:153], v135 offset:46144
	s_waitcnt lgkmcnt(1)
	v_mfma_f32_32x32x16_bf16 v[34:49], v[142:145], v[146:149], v[34:49]
	s_waitcnt lgkmcnt(0)
	v_mfma_f32_32x32x16_bf16 v[50:65], v[142:145], v[150:153], v[50:65]
	ds_read_b128 v[142:145], v134 offset:4672
	s_waitcnt lgkmcnt(0)
	v_mfma_f32_32x32x16_bf16 v[16:31], v[142:145], v[146:149], v[16:31]
	v_mfma_f32_32x32x16_bf16 v[0:15], v[142:145], v[150:153], v[0:15]
	ds_read_b128 v[142:145], v134 offset:96
	ds_read_b128 v[146:149], v135 offset:36960
	ds_read_b128 v[150:153], v135 offset:46176
	s_waitcnt lgkmcnt(1)
	v_mfma_f32_32x32x16_bf16 v[34:49], v[142:145], v[146:149], v[34:49]
	s_waitcnt lgkmcnt(0)
	v_mfma_f32_32x32x16_bf16 v[50:65], v[142:145], v[150:153], v[50:65]
	s_setprio 0
	ds_read_b128 v[142:145], v134 offset:4704
	s_waitcnt vmcnt(7)
	ds_write_b128 v136, v[90:93] offset:18432
	s_waitcnt vmcnt(3)
	ds_write_b128 v136, v[98:101] offset:55296
	ds_write_b128 v136, v[102:105] offset:23040
	s_waitcnt vmcnt(2)
	ds_write_b128 v136, v[110:113] offset:59904
	ds_write_b128 v136, v[114:117] offset:27648
	s_waitcnt vmcnt(1)
	ds_write_b128 v136, v[118:121] offset:64512
	ds_write_b128 v136, v[122:125] offset:32256
	s_waitcnt vmcnt(0)
	ds_write_b128 v137, v[126:129] offset:13824
	s_waitcnt lgkmcnt(0)
	s_barrier
	v_mfma_f32_32x32x16_bf16 v[16:31], v[142:145], v[146:149], v[16:31]
	v_mfma_f32_32x32x16_bf16 v[0:15], v[142:145], v[150:153], v[0:15]
	s_cbranch_scc1 .LBB0_2051
	v_add_co_u32_e32 v102, vcc, 0x10000, v140
	global_load_dwordx4 v[90:93], v[140:141], off offset:384
	global_load_dwordx4 v[98:101], v[138:139], off offset:384
	v_addc_co_u32_e32 v103, vcc, 0, v141, vcc
	v_add_co_u32_e32 v110, vcc, 0x10000, v138
	global_load_dwordx4 v[102:105], v[102:103], off offset:384
	s_nop 0
	v_addc_co_u32_e32 v111, vcc, 0, v139, vcc
	v_add_co_u32_e32 v114, vcc, 0x20000, v140
	global_load_dwordx4 v[110:113], v[110:111], off offset:384
	s_nop 0
	v_addc_co_u32_e32 v115, vcc, 0, v141, vcc
	v_add_co_u32_e32 v118, vcc, 0x20000, v138
	global_load_dwordx4 v[114:117], v[114:115], off offset:384
	s_nop 0
	v_addc_co_u32_e32 v119, vcc, 0, v139, vcc
	v_add_co_u32_e32 v122, vcc, 0x30000, v140
	global_load_dwordx4 v[118:121], v[118:119], off offset:384
	s_nop 0
	v_addc_co_u32_e32 v123, vcc, 0, v141, vcc
	v_add_co_u32_e32 v126, vcc, 0x30000, v138
	global_load_dwordx4 v[122:125], v[122:123], off offset:384
	s_nop 0
	v_addc_co_u32_e32 v127, vcc, 0, v139, vcc
	global_load_dwordx4 v[126:129], v[126:127], off offset:384
.LBB0_2051:
	s_setprio 2
	ds_read_b128 v[138:141], v134 offset:18432
	ds_read_b128 v[142:145], v135 offset:55296
	ds_read_b128 v[146:149], v135 offset:64512
	s_andn2_b64 vcc, exec, s[6:7]
	s_waitcnt lgkmcnt(1)
	v_mfma_f32_32x32x16_bf16 v[34:49], v[138:141], v[142:145], v[34:49]
	s_waitcnt lgkmcnt(0)
	v_mfma_f32_32x32x16_bf16 v[50:65], v[138:141], v[146:149], v[50:65]
	ds_read_b128 v[138:141], v134 offset:23040
	s_waitcnt lgkmcnt(0)
	v_mfma_f32_32x32x16_bf16 v[16:31], v[138:141], v[142:145], v[16:31]
	v_mfma_f32_32x32x16_bf16 v[0:15], v[138:141], v[146:149], v[0:15]
	ds_read_b128 v[138:141], v134 offset:18464
	ds_read_b128 v[142:145], v135 offset:55328
	ds_read_b128 v[146:149], v135 offset:64544
	s_waitcnt lgkmcnt(1)
	v_mfma_f32_32x32x16_bf16 v[34:49], v[138:141], v[142:145], v[34:49]
	s_waitcnt lgkmcnt(0)
	v_mfma_f32_32x32x16_bf16 v[50:65], v[138:141], v[146:149], v[50:65]
	ds_read_b128 v[138:141], v134 offset:23072
	s_waitcnt lgkmcnt(0)
	v_mfma_f32_32x32x16_bf16 v[16:31], v[138:141], v[142:145], v[16:31]
	v_mfma_f32_32x32x16_bf16 v[0:15], v[138:141], v[146:149], v[0:15]
	ds_read_b128 v[138:141], v134 offset:18496
	ds_read_b128 v[142:145], v135 offset:55360
	ds_read_b128 v[146:149], v135 offset:64576
	s_waitcnt lgkmcnt(1)
	v_mfma_f32_32x32x16_bf16 v[34:49], v[138:141], v[142:145], v[34:49]
	s_waitcnt lgkmcnt(0)
	v_mfma_f32_32x32x16_bf16 v[50:65], v[138:141], v[146:149], v[50:65]
	ds_read_b128 v[138:141], v134 offset:23104
	s_waitcnt lgkmcnt(0)
	v_mfma_f32_32x32x16_bf16 v[16:31], v[138:141], v[142:145], v[16:31]
	v_mfma_f32_32x32x16_bf16 v[0:15], v[138:141], v[146:149], v[0:15]
	ds_read_b128 v[138:141], v134 offset:18528
	ds_read_b128 v[142:145], v135 offset:55392
	ds_read_b128 v[146:149], v135 offset:64608
	s_waitcnt lgkmcnt(1)
	v_mfma_f32_32x32x16_bf16 v[34:49], v[138:141], v[142:145], v[34:49]
	s_waitcnt lgkmcnt(0)
	v_mfma_f32_32x32x16_bf16 v[50:65], v[138:141], v[146:149], v[50:65]
	ds_read_b128 v[138:141], v134 offset:23136
	s_waitcnt lgkmcnt(0)
	v_mfma_f32_32x32x16_bf16 v[16:31], v[138:141], v[142:145], v[16:31]
	v_mfma_f32_32x32x16_bf16 v[0:15], v[138:141], v[146:149], v[0:15]
	s_setprio 0
	s_cbranch_vccnz .LBB0_2046
	ds_write_b128 v136, v[66:69]
	ds_write_b128 v136, v[70:73] offset:36864
	ds_write_b128 v136, v[74:77] offset:4608
	ds_write_b128 v136, v[78:81] offset:41472
	ds_write_b128 v136, v[82:85] offset:9216
	ds_write_b128 v136, v[86:89] offset:46080
	ds_write_b128 v136, v[94:97] offset:13824
	ds_write_b128 v136, v[106:109] offset:50688
	s_branch .LBB0_2046

.LBB0_2163:
	s_setprio 2
	ds_read_b128 v[142:145], v130
	ds_read_b128 v[146:149], v131 offset:36864
	ds_read_b128 v[150:153], v131 offset:46080
	s_cmp_gt_u32 s1, 28
	s_waitcnt lgkmcnt(1)
	v_mfma_f32_32x32x16_bf16 v[50:65], v[142:145], v[146:149], v[50:65]
	s_waitcnt lgkmcnt(0)
	v_mfma_f32_32x32x16_bf16 v[34:49], v[142:145], v[150:153], v[34:49]
	ds_read_b128 v[142:145], v130 offset:4608
	s_waitcnt lgkmcnt(0)
	v_mfma_f32_32x32x16_bf16 v[16:31], v[142:145], v[146:149], v[16:31]
	v_mfma_f32_32x32x16_bf16 v[0:15], v[142:145], v[150:153], v[0:15]
	ds_read_b128 v[142:145], v130 offset:32
	ds_read_b128 v[146:149], v131 offset:36896
	ds_read_b128 v[150:153], v131 offset:46112
	s_waitcnt lgkmcnt(1)
	v_mfma_f32_32x32x16_bf16 v[50:65], v[142:145], v[146:149], v[50:65]
	s_waitcnt lgkmcnt(0)
	v_mfma_f32_32x32x16_bf16 v[34:49], v[142:145], v[150:153], v[34:49]
	ds_read_b128 v[142:145], v130 offset:4640
	s_waitcnt lgkmcnt(0)
	v_mfma_f32_32x32x16_bf16 v[16:31], v[142:145], v[146:149], v[16:31]
	v_mfma_f32_32x32x16_bf16 v[0:15], v[142:145], v[150:153], v[0:15]
	ds_read_b128 v[142:145], v130 offset:64
	ds_read_b128 v[146:149], v131 offset:36928
	ds_read_b128 v[150:153], v131 offset:46144
	s_waitcnt lgkmcnt(1)
	v_mfma_f32_32x32x16_bf16 v[50:65], v[142:145], v[146:149], v[50:65]
	s_waitcnt lgkmcnt(0)
	v_mfma_f32_32x32x16_bf16 v[34:49], v[142:145], v[150:153], v[34:49]
	ds_read_b128 v[142:145], v130 offset:4672
	s_waitcnt lgkmcnt(0)
	v_mfma_f32_32x32x16_bf16 v[16:31], v[142:145], v[146:149], v[16:31]
	v_mfma_f32_32x32x16_bf16 v[0:15], v[142:145], v[150:153], v[0:15]
	ds_read_b128 v[142:145], v130 offset:96
	ds_read_b128 v[146:149], v131 offset:36960
	ds_read_b128 v[150:153], v131 offset:46176
	s_waitcnt lgkmcnt(1)
	v_mfma_f32_32x32x16_bf16 v[50:65], v[142:145], v[146:149], v[50:65]
	s_waitcnt lgkmcnt(0)
	v_mfma_f32_32x32x16_bf16 v[34:49], v[142:145], v[150:153], v[34:49]
	s_setprio 0
	ds_read_b128 v[142:145], v130 offset:4704
	s_waitcnt vmcnt(7)
	ds_write_b128 v132, v[86:89] offset:18432
	s_waitcnt vmcnt(3)
	ds_write_b128 v132, v[94:97] offset:55296
	ds_write_b128 v132, v[98:101] offset:23040
	s_waitcnt vmcnt(2)
	ds_write_b128 v132, v[106:109] offset:59904
	ds_write_b128 v132, v[110:113] offset:27648
	s_waitcnt vmcnt(1)
	ds_write_b128 v132, v[118:121] offset:64512
	ds_write_b128 v132, v[122:125] offset:32256
	s_waitcnt vmcnt(0)
	ds_write_b128 v133, v[126:129] offset:13824
	s_waitcnt lgkmcnt(0)
	s_barrier
	v_mfma_f32_32x32x16_bf16 v[16:31], v[142:145], v[146:149], v[16:31]
	v_mfma_f32_32x32x16_bf16 v[0:15], v[142:145], v[150:153], v[0:15]
	s_cbranch_scc1 .LBB0_2165
	v_add_co_u32_e32 v98, vcc, 0x10000, v140
	global_load_dwordx4 v[86:89], v[140:141], off offset:384
	global_load_dwordx4 v[94:97], v[138:139], off offset:384
	v_addc_co_u32_e32 v99, vcc, 0, v141, vcc
	v_add_co_u32_e32 v106, vcc, 0x20000, v138
	global_load_dwordx4 v[98:101], v[98:99], off offset:384
	s_nop 0
	v_addc_co_u32_e32 v107, vcc, 0, v139, vcc
	v_add_co_u32_e32 v110, vcc, 0x20000, v140
	global_load_dwordx4 v[106:109], v[106:107], off offset:384
	s_nop 0
	v_addc_co_u32_e32 v111, vcc, 0, v141, vcc
	v_add_co_u32_e32 v118, vcc, 0x40000, v138
	global_load_dwordx4 v[110:113], v[110:111], off offset:384
	s_nop 0
	v_addc_co_u32_e32 v119, vcc, 0, v139, vcc
	v_add_co_u32_e32 v122, vcc, 0x30000, v140
	global_load_dwordx4 v[118:121], v[118:119], off offset:384
	s_nop 0
	v_addc_co_u32_e32 v123, vcc, 0, v141, vcc
	v_add_co_u32_e32 v126, vcc, 0x60000, v138
	global_load_dwordx4 v[122:125], v[122:123], off offset:384
	s_nop 0
	v_addc_co_u32_e32 v127, vcc, 0, v139, vcc
	global_load_dwordx4 v[126:129], v[126:127], off offset:384
.LBB0_2165:
	s_setprio 2
	ds_read_b128 v[138:141], v130 offset:18432
	ds_read_b128 v[142:145], v131 offset:55296
	ds_read_b128 v[146:149], v131 offset:64512
	s_andn2_b64 vcc, exec, s[4:5]
	s_waitcnt lgkmcnt(1)
	v_mfma_f32_32x32x16_bf16 v[50:65], v[138:141], v[142:145], v[50:65]
	s_waitcnt lgkmcnt(0)
	v_mfma_f32_32x32x16_bf16 v[34:49], v[138:141], v[146:149], v[34:49]
	ds_read_b128 v[138:141], v130 offset:23040
	s_waitcnt lgkmcnt(0)
	v_mfma_f32_32x32x16_bf16 v[16:31], v[138:141], v[142:145], v[16:31]
	v_mfma_f32_32x32x16_bf16 v[0:15], v[138:141], v[146:149], v[0:15]
	ds_read_b128 v[138:141], v130 offset:18464
	ds_read_b128 v[142:145], v131 offset:55328
	ds_read_b128 v[146:149], v131 offset:64544
	s_waitcnt lgkmcnt(1)
	v_mfma_f32_32x32x16_bf16 v[50:65], v[138:141], v[142:145], v[50:65]
	s_waitcnt lgkmcnt(0)
	v_mfma_f32_32x32x16_bf16 v[34:49], v[138:141], v[146:149], v[34:49]
	ds_read_b128 v[138:141], v130 offset:23072
	s_waitcnt lgkmcnt(0)
	v_mfma_f32_32x32x16_bf16 v[16:31], v[138:141], v[142:145], v[16:31]
	v_mfma_f32_32x32x16_bf16 v[0:15], v[138:141], v[146:149], v[0:15]
	ds_read_b128 v[138:141], v130 offset:18496
	ds_read_b128 v[142:145], v131 offset:55360
	ds_read_b128 v[146:149], v131 offset:64576
	s_waitcnt lgkmcnt(1)
	v_mfma_f32_32x32x16_bf16 v[50:65], v[138:141], v[142:145], v[50:65]
	s_waitcnt lgkmcnt(0)
	v_mfma_f32_32x32x16_bf16 v[34:49], v[138:141], v[146:149], v[34:49]
	ds_read_b128 v[138:141], v130 offset:23104
	s_waitcnt lgkmcnt(0)
	v_mfma_f32_32x32x16_bf16 v[16:31], v[138:141], v[142:145], v[16:31]
	v_mfma_f32_32x32x16_bf16 v[0:15], v[138:141], v[146:149], v[0:15]
	ds_read_b128 v[138:141], v130 offset:18528
	ds_read_b128 v[142:145], v131 offset:55392
	ds_read_b128 v[146:149], v131 offset:64608
	s_waitcnt lgkmcnt(1)
	v_mfma_f32_32x32x16_bf16 v[50:65], v[138:141], v[142:145], v[50:65]
	s_waitcnt lgkmcnt(0)
	v_mfma_f32_32x32x16_bf16 v[34:49], v[138:141], v[146:149], v[34:49]
	ds_read_b128 v[138:141], v130 offset:23136
	s_waitcnt lgkmcnt(0)
	v_mfma_f32_32x32x16_bf16 v[16:31], v[138:141], v[142:145], v[16:31]
	v_mfma_f32_32x32x16_bf16 v[0:15], v[138:141], v[146:149], v[0:15]
	s_setprio 0
	s_cbranch_vccnz .LBB0_2160
	ds_write_b128 v132, v[66:69]
	ds_write_b128 v132, v[70:73] offset:36864
	ds_write_b128 v132, v[74:77] offset:4608
	ds_write_b128 v132, v[78:81] offset:41472
	ds_write_b128 v132, v[82:85] offset:9216
	ds_write_b128 v132, v[90:93] offset:46080
	ds_write_b128 v132, v[102:105] offset:13824
	ds_write_b128 v132, v[114:117] offset:50688
	s_branch .LBB0_2160

.LBB0_2175:
	s_setprio 2
	ds_read_b128 v[142:145], v134
	ds_read_b128 v[146:149], v135 offset:36864
	ds_read_b128 v[150:153], v135 offset:46080
	s_cmp_gt_u32 s1, 12
	s_waitcnt lgkmcnt(1)
	v_mfma_f32_32x32x16_bf16 v[50:65], v[142:145], v[146:149], v[50:65]
	s_waitcnt lgkmcnt(0)
	v_mfma_f32_32x32x16_bf16 v[34:49], v[142:145], v[150:153], v[34:49]
	ds_read_b128 v[142:145], v134 offset:4608
	s_waitcnt lgkmcnt(0)
	v_mfma_f32_32x32x16_bf16 v[16:31], v[142:145], v[146:149], v[16:31]
	v_mfma_f32_32x32x16_bf16 v[0:15], v[142:145], v[150:153], v[0:15]
	ds_read_b128 v[142:145], v134 offset:32
	ds_read_b128 v[146:149], v135 offset:36896
	ds_read_b128 v[150:153], v135 offset:46112
	s_waitcnt lgkmcnt(1)
	v_mfma_f32_32x32x16_bf16 v[50:65], v[142:145], v[146:149], v[50:65]
	s_waitcnt lgkmcnt(0)
	v_mfma_f32_32x32x16_bf16 v[34:49], v[142:145], v[150:153], v[34:49]
	ds_read_b128 v[142:145], v134 offset:4640
	s_waitcnt lgkmcnt(0)
	v_mfma_f32_32x32x16_bf16 v[16:31], v[142:145], v[146:149], v[16:31]
	v_mfma_f32_32x32x16_bf16 v[0:15], v[142:145], v[150:153], v[0:15]
	ds_read_b128 v[142:145], v134 offset:64
	ds_read_b128 v[146:149], v135 offset:36928
	ds_read_b128 v[150:153], v135 offset:46144
	s_waitcnt lgkmcnt(1)
	v_mfma_f32_32x32x16_bf16 v[50:65], v[142:145], v[146:149], v[50:65]
	s_waitcnt lgkmcnt(0)
	v_mfma_f32_32x32x16_bf16 v[34:49], v[142:145], v[150:153], v[34:49]
	ds_read_b128 v[142:145], v134 offset:4672
	s_waitcnt lgkmcnt(0)
	v_mfma_f32_32x32x16_bf16 v[16:31], v[142:145], v[146:149], v[16:31]
	v_mfma_f32_32x32x16_bf16 v[0:15], v[142:145], v[150:153], v[0:15]
	ds_read_b128 v[142:145], v134 offset:96
	ds_read_b128 v[146:149], v135 offset:36960
	ds_read_b128 v[150:153], v135 offset:46176
	s_waitcnt lgkmcnt(1)
	v_mfma_f32_32x32x16_bf16 v[50:65], v[142:145], v[146:149], v[50:65]
	s_waitcnt lgkmcnt(0)
	v_mfma_f32_32x32x16_bf16 v[34:49], v[142:145], v[150:153], v[34:49]
	s_setprio 0
	ds_read_b128 v[142:145], v134 offset:4704
	s_waitcnt vmcnt(7)
	ds_write_b128 v136, v[90:93] offset:18432
	s_waitcnt vmcnt(3)
	ds_write_b128 v136, v[98:101] offset:55296
	ds_write_b128 v136, v[102:105] offset:23040
	s_waitcnt vmcnt(2)
	ds_write_b128 v136, v[110:113] offset:59904
	ds_write_b128 v136, v[114:117] offset:27648
	s_waitcnt vmcnt(1)
	ds_write_b128 v136, v[118:121] offset:64512
	ds_write_b128 v136, v[122:125] offset:32256
	s_waitcnt vmcnt(0)
	ds_write_b128 v137, v[126:129] offset:13824
	s_waitcnt lgkmcnt(0)
	s_barrier
	v_mfma_f32_32x32x16_bf16 v[16:31], v[142:145], v[146:149], v[16:31]
	v_mfma_f32_32x32x16_bf16 v[0:15], v[142:145], v[150:153], v[0:15]
	s_cbranch_scc1 .LBB0_2177
	v_add_co_u32_e32 v102, vcc, 0x10000, v140
	global_load_dwordx4 v[90:93], v[140:141], off offset:384
	global_load_dwordx4 v[98:101], v[138:139], off offset:384
	v_addc_co_u32_e32 v103, vcc, 0, v141, vcc
	v_add_co_u32_e32 v110, vcc, 0x10000, v138
	global_load_dwordx4 v[102:105], v[102:103], off offset:384
	s_nop 0
	v_addc_co_u32_e32 v111, vcc, 0, v139, vcc
	v_add_co_u32_e32 v114, vcc, 0x20000, v140
	global_load_dwordx4 v[110:113], v[110:111], off offset:384
	s_nop 0
	v_addc_co_u32_e32 v115, vcc, 0, v141, vcc
	v_add_co_u32_e32 v118, vcc, 0x20000, v138
	global_load_dwordx4 v[114:117], v[114:115], off offset:384
	s_nop 0
	v_addc_co_u32_e32 v119, vcc, 0, v139, vcc
	v_add_co_u32_e32 v122, vcc, 0x30000, v140
	global_load_dwordx4 v[118:121], v[118:119], off offset:384
	s_nop 0
	v_addc_co_u32_e32 v123, vcc, 0, v141, vcc
	v_add_co_u32_e32 v126, vcc, 0x30000, v138
	global_load_dwordx4 v[122:125], v[122:123], off offset:384
	s_nop 0
	v_addc_co_u32_e32 v127, vcc, 0, v139, vcc
	global_load_dwordx4 v[126:129], v[126:127], off offset:384
.LBB0_2177:
	s_setprio 2
	ds_read_b128 v[138:141], v134 offset:18432
	ds_read_b128 v[142:145], v135 offset:55296
	ds_read_b128 v[146:149], v135 offset:64512
	s_andn2_b64 vcc, exec, s[6:7]
	s_waitcnt lgkmcnt(1)
	v_mfma_f32_32x32x16_bf16 v[50:65], v[138:141], v[142:145], v[50:65]
	s_waitcnt lgkmcnt(0)
	v_mfma_f32_32x32x16_bf16 v[34:49], v[138:141], v[146:149], v[34:49]
	ds_read_b128 v[138:141], v134 offset:23040
	s_waitcnt lgkmcnt(0)
	v_mfma_f32_32x32x16_bf16 v[16:31], v[138:141], v[142:145], v[16:31]
	v_mfma_f32_32x32x16_bf16 v[0:15], v[138:141], v[146:149], v[0:15]
	ds_read_b128 v[138:141], v134 offset:18464
	ds_read_b128 v[142:145], v135 offset:55328
	ds_read_b128 v[146:149], v135 offset:64544
	s_waitcnt lgkmcnt(1)
	v_mfma_f32_32x32x16_bf16 v[50:65], v[138:141], v[142:145], v[50:65]
	s_waitcnt lgkmcnt(0)
	v_mfma_f32_32x32x16_bf16 v[34:49], v[138:141], v[146:149], v[34:49]
	ds_read_b128 v[138:141], v134 offset:23072
	s_waitcnt lgkmcnt(0)
	v_mfma_f32_32x32x16_bf16 v[16:31], v[138:141], v[142:145], v[16:31]
	v_mfma_f32_32x32x16_bf16 v[0:15], v[138:141], v[146:149], v[0:15]
	ds_read_b128 v[138:141], v134 offset:18496
	ds_read_b128 v[142:145], v135 offset:55360
	ds_read_b128 v[146:149], v135 offset:64576
	s_waitcnt lgkmcnt(1)
	v_mfma_f32_32x32x16_bf16 v[50:65], v[138:141], v[142:145], v[50:65]
	s_waitcnt lgkmcnt(0)
	v_mfma_f32_32x32x16_bf16 v[34:49], v[138:141], v[146:149], v[34:49]
	ds_read_b128 v[138:141], v134 offset:23104
	s_waitcnt lgkmcnt(0)
	v_mfma_f32_32x32x16_bf16 v[16:31], v[138:141], v[142:145], v[16:31]
	v_mfma_f32_32x32x16_bf16 v[0:15], v[138:141], v[146:149], v[0:15]
	ds_read_b128 v[138:141], v134 offset:18528
	ds_read_b128 v[142:145], v135 offset:55392
	ds_read_b128 v[146:149], v135 offset:64608
	s_waitcnt lgkmcnt(1)
	v_mfma_f32_32x32x16_bf16 v[50:65], v[138:141], v[142:145], v[50:65]
	s_waitcnt lgkmcnt(0)
	v_mfma_f32_32x32x16_bf16 v[34:49], v[138:141], v[146:149], v[34:49]
	ds_read_b128 v[138:141], v134 offset:23136
	s_waitcnt lgkmcnt(0)
	v_mfma_f32_32x32x16_bf16 v[16:31], v[138:141], v[142:145], v[16:31]
	v_mfma_f32_32x32x16_bf16 v[0:15], v[138:141], v[146:149], v[0:15]
	s_setprio 0
	s_cbranch_vccnz .LBB0_2172
	ds_write_b128 v136, v[66:69]
	ds_write_b128 v136, v[70:73] offset:36864
	ds_write_b128 v136, v[74:77] offset:4608
	ds_write_b128 v136, v[78:81] offset:41472
	ds_write_b128 v136, v[82:85] offset:9216
	ds_write_b128 v136, v[86:89] offset:46080
	ds_write_b128 v136, v[94:97] offset:13824
	ds_write_b128 v136, v[106:109] offset:50688
	s_branch .LBB0_2172

.LBB0_2635:
	s_setprio 2
	ds_read_b128 v[130:133], v102
	ds_read_b128 v[134:137], v103 offset:36864
	v_cndmask_b32_e64 v105, 0, 1, s[4:5]
	v_cmp_ne_u32_e64 s[0:1], 1, v105
	s_andn2_b64 vcc, exec, s[4:5]
	s_waitcnt lgkmcnt(0)
	v_mfma_f32_32x32x16_bf16 v[16:31], v[130:133], v[134:137], v[16:31]
	ds_read_b128 v[130:133], v102 offset:4608
	s_waitcnt lgkmcnt(0)
	v_mfma_f32_32x32x16_bf16 v[0:15], v[130:133], v[134:137], v[0:15]
	ds_read_b128 v[130:133], v102 offset:32
	ds_read_b128 v[134:137], v103 offset:36896
	s_waitcnt lgkmcnt(0)
	v_mfma_f32_32x32x16_bf16 v[16:31], v[130:133], v[134:137], v[16:31]
	ds_read_b128 v[130:133], v102 offset:4640
	s_waitcnt lgkmcnt(0)
	v_mfma_f32_32x32x16_bf16 v[0:15], v[130:133], v[134:137], v[0:15]
	ds_read_b128 v[130:133], v102 offset:64
	ds_read_b128 v[134:137], v103 offset:36928
	s_waitcnt lgkmcnt(0)
	v_mfma_f32_32x32x16_bf16 v[16:31], v[130:133], v[134:137], v[16:31]
	ds_read_b128 v[130:133], v102 offset:4672
	ds_read_b128 v[138:141], v102 offset:96
	ds_read_b128 v[142:145], v103 offset:36960
	s_waitcnt lgkmcnt(2)
	v_mfma_f32_32x32x16_bf16 v[0:15], v[130:133], v[134:137], v[0:15]
	s_setprio 0
	ds_read_b128 v[130:133], v102 offset:4704
	s_waitcnt vmcnt(7)
	ds_write_b128 v104, v[62:65] offset:18432
	s_waitcnt vmcnt(6)
	ds_write_b128 v104, v[66:69] offset:55296
	s_waitcnt vmcnt(5)
	ds_write_b128 v104, v[70:73] offset:23040
	s_waitcnt vmcnt(4)
	ds_write_b128 v104, v[78:81] offset:59904
	s_waitcnt vmcnt(3)
	ds_write_b128 v104, v[82:85] offset:27648
	s_waitcnt vmcnt(2)
	ds_write_b128 v104, v[86:89] offset:64512
	s_waitcnt vmcnt(1)
	ds_write_b128 v104, v[90:93] offset:32256
	s_waitcnt vmcnt(0)
	ds_write_b128 v32, v[94:97] offset:13824
	s_waitcnt lgkmcnt(0)
	s_barrier
	v_mfma_f32_32x32x16_bf16 v[16:31], v[138:141], v[142:145], v[16:31]
	v_mfma_f32_32x32x16_bf16 v[0:15], v[130:133], v[142:145], v[0:15]
	s_cbranch_vccnz .LBB0_2637
	global_load_dwordx4 v[62:65], v[98:99], off offset:384
	global_load_dwordx4 v[66:69], v[100:101], off offset:384
	global_load_dwordx4 v[70:73], v[118:119], off
	global_load_dwordx4 v[78:81], v[120:121], off
	global_load_dwordx4 v[82:85], v[122:123], off
	global_load_dwordx4 v[86:89], v[124:125], off
	global_load_dwordx4 v[90:93], v[126:127], off
	global_load_dwordx4 v[94:97], v[128:129], off
.LBB0_2637:
	s_setprio 2
	ds_read_b128 v[130:133], v102 offset:18432
	ds_read_b128 v[134:137], v103 offset:55296
	s_and_b64 vcc, exec, s[0:1]
	s_waitcnt lgkmcnt(0)
	v_mfma_f32_32x32x16_bf16 v[16:31], v[130:133], v[134:137], v[16:31]
	ds_read_b128 v[130:133], v102 offset:23040
	s_waitcnt lgkmcnt(0)
	v_mfma_f32_32x32x16_bf16 v[0:15], v[130:133], v[134:137], v[0:15]
	ds_read_b128 v[130:133], v102 offset:18464
	ds_read_b128 v[134:137], v103 offset:55328
	s_waitcnt lgkmcnt(0)
	v_mfma_f32_32x32x16_bf16 v[16:31], v[130:133], v[134:137], v[16:31]
	ds_read_b128 v[130:133], v102 offset:23072
	s_waitcnt lgkmcnt(0)
	v_mfma_f32_32x32x16_bf16 v[0:15], v[130:133], v[134:137], v[0:15]
	ds_read_b128 v[130:133], v102 offset:18496
	ds_read_b128 v[134:137], v103 offset:55360
	s_waitcnt lgkmcnt(0)
	v_mfma_f32_32x32x16_bf16 v[16:31], v[130:133], v[134:137], v[16:31]
	ds_read_b128 v[130:133], v102 offset:23104
	s_waitcnt lgkmcnt(0)
	v_mfma_f32_32x32x16_bf16 v[0:15], v[130:133], v[134:137], v[0:15]
	ds_read_b128 v[130:133], v102 offset:18528
	ds_read_b128 v[134:137], v103 offset:55392
	s_waitcnt lgkmcnt(0)
	v_mfma_f32_32x32x16_bf16 v[16:31], v[130:133], v[134:137], v[16:31]
	ds_read_b128 v[130:133], v102 offset:23136
	s_waitcnt lgkmcnt(0)
	v_mfma_f32_32x32x16_bf16 v[0:15], v[130:133], v[134:137], v[0:15]
	s_setprio 0
	s_cbranch_vccnz .LBB0_2632
	ds_write_b128 v104, v[34:37]
	ds_write_b128 v104, v[38:41] offset:36864
	ds_write_b128 v104, v[42:45] offset:4608
	ds_write_b128 v104, v[46:49] offset:41472
	ds_write_b128 v104, v[50:53] offset:9216
	ds_write_b128 v104, v[54:57] offset:46080
	ds_write_b128 v104, v[58:61] offset:13824
	ds_write_b128 v104, v[74:77] offset:50688
	s_branch .LBB0_2632
